# GEMM K-loops: per-burst s_setprio 3/0 flips deleted; one static s_setprio 1 for waves 4-7 during each K-loop (reset after)
# speedup vs baseline: 1.0098x; 1.0004x over previous
; #define PG8_STAGEA(bufoff, gbase, voff) do { _Pragma("unroll") for (int _i = 0; _i < 2; ++_i) \
;         __builtin_amdgcn_global_load_lds((const unsigned*)((const char*)(gbase) + (voff)[_i]), (LAS unsigned*)(lds + (bufoff) + ldsw + _i * 8192), 16, 0, 0); } while (0)
; #define PG8_LDA(dst, b, h) do { _Pragma("unroll") for (int m = 0; m < 4; ++m) _Pragma("unroll") for (int k = 0; k < 2; ++k) dst[m][k] = *(const LAS bf16x8*)(lds + PG8_SA(b, h) + aoff + m * 2048 + k * 1024); } while (0)
; #define PG8_LDB(dst, b, h) do { _Pragma("unroll") for (int n = 0; n < 2; ++n) _Pragma("unroll") for (int k = 0; k < 2; ++k) dst[n][k] = *(const LAS bf16x8*)(lds + PG8_SB(b, h) + boff + n * 2048 + k * 1024); } while (0)
; #define PG8_MMA(ai, bj, At, Bt) do { __builtin_amdgcn_s_setprio(3); _Pragma("unroll") for (int m = 0; m < 4; ++m) _Pragma("unroll") for (int n = 0; n < 2; ++n) _Pragma("unroll") for (int k = 0; k < 2; ++k) \
;         acc[ai][bj][m][n] = __builtin_amdgcn_mfma_f32_16x16x32_bf16(Bt[n][k], At[m][k], acc[ai][bj][m][n], 0, 0, 0); __builtin_amdgcn_s_setprio(0); } while (0)
; #define PG8_WAIT_V(n) asm volatile("s_waitcnt vmcnt(" #n ")" ::: "memory")
; #define PG8_BAR __builtin_amdgcn_s_barrier()
; template <class Epi, int PARTS>
; __device__ __forceinline__ void gemm_phase(LAS unsigned char* lds, const Gemm g, const StaticOrder& S, const Epi& E) {
;     ...
;         const bool has_next = S.next(ui + 1, nxt);
;         const char* nA = has_next ? PG8_UA(nxt) : cA; const char* nB = has_next ? PG8_UB(nxt) : cB;
;         for (int t = 0; t < nt; t += 2) {
;             const bool last = (t == nt - 2);
;             const char* a1 = cA + (size_t)(t + 1) * kstep;
;             const char* a2 = last ? nA : cA + (size_t)(t + 2) * kstep; const char* b2 = last ? nB : cB + (size_t)(t + 2) * kstep;
;             const char* a3 = a2 + kstep; const char* b3 = b2 + kstep;
;             PG8_LDB(B0, 0, 0); PG8_LDB(B1, 0, 1); PG8_SCHED; PG8_LDA(At, 0, 0); PG8_STAGEA(PG8_SA(1, 1), a1 + hstepA, voffA);
;             PG8_WAIT_V(8); PG8_WAIT_L(0); PG8_BAR; PG8_MMA(0, 0, At, B0); PG8_MMA(0, 1, At, B1); PG8_BAR; PG8_SCHED;
;     ...
;         for (int a = 0; a < 2; ++a)
; #pragma unroll
;             for (int b = 0; b < 2; ++b)
; #pragma unroll
;                 for (int m = 0; m < 4; ++m)
; #pragma unroll
;                     for (int n = 0; n < 2; ++n) acc[a][b][m][n] = (f32x4){0.f, 0.f, 0.f, 0.f};
.LBB0_116:
	s_ashr_i32 s39, s38, 31
	s_lshl_b64 s[48:49], s[38:39], 19
	v_readlane_b32 s34, v254, 58
	s_add_u32 s74, s34, s48
	v_readlane_b32 s34, v254, 59
	s_addc_u32 s75, s34, s49
	s_and_b64 s[0:1], s[0:1], exec
	s_cselect_b32 s39, s75, s47
	s_cselect_b32 s43, s74, s46
	s_add_u32 s51, s46, 0x100
	v_mov_b32_e32 v42, 0
	s_addc_u32 s52, s47, 0
	s_mov_b32 s53, -2
	v_mov_b32_e32 v43, v42
	v_mov_b32_e32 v44, v42
	v_mov_b32_e32 v45, v42
	v_mov_b32_e32 v138, v42
	v_mov_b32_e32 v139, v42
	v_mov_b32_e32 v140, v42
	v_mov_b32_e32 v141, v42
	v_mov_b32_e32 v2, v42
	v_mov_b32_e32 v3, v42
	v_mov_b32_e32 v4, v42
	v_mov_b32_e32 v5, v42
	s_waitcnt vmcnt(0)
	v_mov_b32_e32 v66, v42
	v_mov_b32_e32 v67, v42
	v_mov_b32_e32 v68, v42
	v_mov_b32_e32 v69, v42
	v_mov_b32_e32 v10, v42
	v_mov_b32_e32 v11, v42
	v_mov_b32_e32 v12, v42
	v_mov_b32_e32 v13, v42
	v_mov_b32_e32 v74, v42
	v_mov_b32_e32 v75, v42
	v_mov_b32_e32 v76, v42
	v_mov_b32_e32 v77, v42
	v_mov_b32_e32 v18, v42
	v_mov_b32_e32 v19, v42
	v_mov_b32_e32 v20, v42
	v_mov_b32_e32 v21, v42
	v_mov_b32_e32 v82, v42
	v_mov_b32_e32 v83, v42
	v_mov_b32_e32 v84, v42
	v_mov_b32_e32 v85, v42
	v_mov_b32_e32 v46, v42
	v_mov_b32_e32 v47, v42
	v_mov_b32_e32 v48, v42
	v_mov_b32_e32 v49, v42
	v_mov_b32_e32 v142, v42
	v_mov_b32_e32 v143, v42
	v_mov_b32_e32 v144, v42
	v_mov_b32_e32 v145, v42
	v_mov_b32_e32 v6, v42
	v_mov_b32_e32 v7, v42
	v_mov_b32_e32 v8, v42
	v_mov_b32_e32 v9, v42
	v_mov_b32_e32 v70, v42
	v_mov_b32_e32 v71, v42
	v_mov_b32_e32 v72, v42
	v_mov_b32_e32 v73, v42
	v_mov_b32_e32 v14, v42
	v_mov_b32_e32 v15, v42
	v_mov_b32_e32 v16, v42
	v_mov_b32_e32 v17, v42
	v_mov_b32_e32 v78, v42
	v_mov_b32_e32 v79, v42
	v_mov_b32_e32 v80, v42
	v_mov_b32_e32 v81, v42
	v_mov_b32_e32 v22, v42
	v_mov_b32_e32 v23, v42
	v_mov_b32_e32 v24, v42
	v_mov_b32_e32 v25, v42
	v_mov_b32_e32 v86, v42
	v_mov_b32_e32 v87, v42
	v_mov_b32_e32 v88, v42
	v_mov_b32_e32 v89, v42
	v_mov_b32_e32 v26, v42
	v_mov_b32_e32 v27, v42
	v_mov_b32_e32 v28, v42
	v_mov_b32_e32 v29, v42
	v_mov_b32_e32 v122, v42
	v_mov_b32_e32 v123, v42
	v_mov_b32_e32 v124, v42
	v_mov_b32_e32 v125, v42
	s_waitcnt vmcnt(0)
	v_mov_b32_e32 v34, v42
	v_mov_b32_e32 v35, v42
	v_mov_b32_e32 v36, v42
	v_mov_b32_e32 v37, v42
	v_mov_b32_e32 v130, v42
	v_mov_b32_e32 v131, v42
	v_mov_b32_e32 v132, v42
	v_mov_b32_e32 v133, v42
	v_mov_b32_e32 v50, v42
	v_mov_b32_e32 v51, v42
	v_mov_b32_e32 v52, v42
	v_mov_b32_e32 v53, v42
	v_mov_b32_e32 v146, v42
	v_mov_b32_e32 v147, v42
	v_mov_b32_e32 v148, v42
	v_mov_b32_e32 v149, v42
	v_mov_b32_e32 v54, v42
	v_mov_b32_e32 v55, v42
	v_mov_b32_e32 v56, v42
	v_mov_b32_e32 v57, v42
	v_mov_b32_e32 v150, v42
	v_mov_b32_e32 v151, v42
	v_mov_b32_e32 v152, v42
	v_mov_b32_e32 v153, v42
	v_mov_b32_e32 v30, v42
	v_mov_b32_e32 v31, v42
	v_mov_b32_e32 v32, v42
	v_mov_b32_e32 v33, v42
	v_mov_b32_e32 v126, v42
	v_mov_b32_e32 v127, v42
	v_mov_b32_e32 v128, v42
	v_mov_b32_e32 v129, v42
	v_mov_b32_e32 v38, v42
	v_mov_b32_e32 v39, v42
	v_mov_b32_e32 v40, v42
	v_mov_b32_e32 v41, v42
	v_mov_b32_e32 v134, v42
	v_mov_b32_e32 v135, v42
	v_mov_b32_e32 v136, v42
	v_mov_b32_e32 v137, v42
	v_mov_b32_e32 v58, v42
	v_mov_b32_e32 v59, v42
	v_mov_b32_e32 v60, v42
	v_mov_b32_e32 v61, v42
	v_mov_b32_e32 v154, v42
	v_mov_b32_e32 v155, v42
	v_mov_b32_e32 v156, v42
	v_mov_b32_e32 v157, v42
	v_mov_b32_e32 v62, v42
	v_mov_b32_e32 v63, v42
	v_mov_b32_e32 v64, v42
	v_mov_b32_e32 v65, v42
	v_mov_b32_e32 v158, v42
	v_mov_b32_e32 v159, v42
	v_mov_b32_e32 v160, v42
	v_mov_b32_e32 v161, v42
	v_readfirstlane_b32 s99, v216
	s_cmp_lt_u32 s99, 0x100
	s_cbranch_scc1 .Lgprio0
	s_setprio 1
.Lgprio0:
.LBB0_117:
	s_add_u32 s0, s44, 0x100
	s_addc_u32 s1, s45, 0
	s_add_i32 s34, 0, 0x10000
	s_cmp_eq_u32 s53, 12
	s_cselect_b32 s49, s81, s1
	s_cselect_b32 s48, s80, s0
	v_add_u32_e32 v0, s34, v235
	s_cselect_b32 s47, s39, s52
	s_cselect_b32 s46, s43, s51
	s_add_i32 s35, 0, 0x14000
	ds_read_b128 v[90:93], v0
	ds_read_b128 v[94:97], v0 offset:1024
	ds_read_b128 v[98:101], v0 offset:2048
	ds_read_b128 v[102:105], v0 offset:3072
	v_add_u32_e32 v0, s35, v235
	ds_read_b128 v[106:109], v0
	ds_read_b128 v[110:113], v0 offset:1024
	ds_read_b128 v[114:117], v0 offset:2048
	ds_read_b128 v[118:121], v0 offset:3072
	v_lshl_add_u64 v[188:189], s[44:45], 0, v[176:177]
	s_add_i32 m0, s40, 0xc000
	ds_read_b128 v[162:165], v238
	ds_read_b128 v[180:183], v238 offset:1024
	ds_read_b128 v[184:187], v238 offset:2048
	ds_read_b128 v[196:199], v238 offset:3072
	ds_read_b128 v[200:203], v238 offset:4096
	ds_read_b128 v[204:207], v238 offset:5120
	ds_read_b128 v[208:211], v238 offset:6144
	ds_read_b128 v[212:215], v238 offset:7168
	global_load_lds_dwordx4 v[188:189], off
	v_lshl_add_u64 v[188:189], s[44:45], 0, v[178:179]
	s_add_i32 m0, s40, 0xe000
	s_nop 0
	global_load_lds_dwordx4 v[188:189], off
	s_waitcnt vmcnt(8)
	s_waitcnt lgkmcnt(0)
	s_barrier
; #define PG8_STAGE(bufoff, gbase, voff) do { _Pragma("unroll") for (int _i = 0; _i < 2; ++_i) \
;         __builtin_amdgcn_global_load_lds((const unsigned*)((const char*)(gbase) + (voff)[_i]), (LAS unsigned*)(lds + (bufoff) + ldsw + _i * 8192), 16, 0, 0); } while (0)
; #define PG8_STAGEA(bufoff, gbase, voff) do { _Pragma("unroll") for (int _i = 0; _i < 2; ++_i) \
;         __builtin_amdgcn_global_load_lds((const unsigned*)((const char*)(gbase) + (voff)[_i]), (LAS unsigned*)(lds + (bufoff) + ldsw + _i * 8192), 16, 0, 0); } while (0)
; #define PG8_LDA(dst, b, h) do { _Pragma("unroll") for (int m = 0; m < 4; ++m) _Pragma("unroll") for (int k = 0; k < 2; ++k) dst[m][k] = *(const LAS bf16x8*)(lds + PG8_SA(b, h) + aoff + m * 2048 + k * 1024); } while (0)
; #define PG8_LDB(dst, b, h) do { _Pragma("unroll") for (int n = 0; n < 2; ++n) _Pragma("unroll") for (int k = 0; k < 2; ++k) dst[n][k] = *(const LAS bf16x8*)(lds + PG8_SB(b, h) + boff + n * 2048 + k * 1024); } while (0)
; #define PG8_MMA(ai, bj, At, Bt) do { __builtin_amdgcn_s_setprio(3); _Pragma("unroll") for (int m = 0; m < 4; ++m) _Pragma("unroll") for (int n = 0; n < 2; ++n) _Pragma("unroll") for (int k = 0; k < 2; ++k) \
;         acc[ai][bj][m][n] = __builtin_amdgcn_mfma_f32_16x16x32_bf16(Bt[n][k], At[m][k], acc[ai][bj][m][n], 0, 0, 0); __builtin_amdgcn_s_setprio(0); } while (0)
; #define PG8_WAIT_V(n) asm volatile("s_waitcnt vmcnt(" #n ")" ::: "memory")
; #define PG8_WAIT_L(n) asm volatile("s_waitcnt lgkmcnt(" #n ")" ::: "memory")
; #define PG8_BAR __builtin_amdgcn_s_barrier()
; #define PG8_SCHED __builtin_amdgcn_sched_barrier(0)
; template <class Epi, int PARTS>
; __device__ __forceinline__ void gemm_phase(LAS unsigned char* lds, const Gemm g, const StaticOrder& S, const Epi& E) {
;     ...
;             PG8_LDB(B0, 0, 0); PG8_LDB(B1, 0, 1); PG8_SCHED; PG8_LDA(At, 0, 0); PG8_STAGEA(PG8_SA(1, 1), a1 + hstepA, voffA);
;             PG8_WAIT_V(8); PG8_WAIT_L(0); PG8_BAR; PG8_MMA(0, 0, At, B0); PG8_MMA(0, 1, At, B1); PG8_BAR; PG8_SCHED;
;             PG8_LDA(At, 0, 1); PG8_STAGE(PG8_SB(0, 0), b2, voffB); PG8_STAGE(PG8_SB(0, 1), b2 + hstepB, voffB); PG8_STAGEA(PG8_SA(0, 0), a2, voffA);
;             PG8_WAIT_V(8); PG8_WAIT_L(0); PG8_BAR; PG8_MMA(1, 0, At, B0); PG8_MMA(1, 1, At, B1); PG8_BAR; PG8_SCHED;
	s_waitcnt lgkmcnt(0)
	v_mfma_f32_16x16x32_bf16 v[158:161], v[90:93], v[162:165], v[158:161]
	v_mfma_f32_16x16x32_bf16 v[62:65], v[98:101], v[162:165], v[62:65]
	v_mfma_f32_16x16x32_bf16 v[154:157], v[90:93], v[184:187], v[154:157]
	v_mfma_f32_16x16x32_bf16 v[58:61], v[98:101], v[184:187], v[58:61]
	v_mfma_f32_16x16x32_bf16 v[134:137], v[90:93], v[200:203], v[134:137]
	v_mfma_f32_16x16x32_bf16 v[38:41], v[98:101], v[200:203], v[38:41]
	v_mfma_f32_16x16x32_bf16 v[126:129], v[90:93], v[208:211], v[126:129]
	v_mfma_f32_16x16x32_bf16 v[30:33], v[98:101], v[208:211], v[30:33]
	v_mfma_f32_16x16x32_bf16 v[158:161], v[94:97], v[180:183], v[158:161]
	v_mfma_f32_16x16x32_bf16 v[62:65], v[102:105], v[180:183], v[62:65]
	v_mfma_f32_16x16x32_bf16 v[154:157], v[94:97], v[196:199], v[154:157]
	v_mfma_f32_16x16x32_bf16 v[58:61], v[102:105], v[196:199], v[58:61]
	v_mfma_f32_16x16x32_bf16 v[134:137], v[94:97], v[204:207], v[134:137]
	v_mfma_f32_16x16x32_bf16 v[38:41], v[102:105], v[204:207], v[38:41]
	v_mfma_f32_16x16x32_bf16 v[126:129], v[94:97], v[212:215], v[126:129]
	v_mfma_f32_16x16x32_bf16 v[30:33], v[102:105], v[212:215], v[30:33]
	v_mfma_f32_16x16x32_bf16 v[150:153], v[106:109], v[162:165], v[150:153]
	v_mfma_f32_16x16x32_bf16 v[54:57], v[114:117], v[162:165], v[54:57]
	v_mfma_f32_16x16x32_bf16 v[146:149], v[106:109], v[184:187], v[146:149]
	v_mfma_f32_16x16x32_bf16 v[50:53], v[114:117], v[184:187], v[50:53]
	v_mfma_f32_16x16x32_bf16 v[130:133], v[106:109], v[200:203], v[130:133]
	v_mfma_f32_16x16x32_bf16 v[34:37], v[114:117], v[200:203], v[34:37]
	v_mfma_f32_16x16x32_bf16 v[122:125], v[106:109], v[208:211], v[122:125]
	v_mfma_f32_16x16x32_bf16 v[26:29], v[114:117], v[208:211], v[26:29]
	v_mfma_f32_16x16x32_bf16 v[150:153], v[110:113], v[180:183], v[150:153]
	v_mfma_f32_16x16x32_bf16 v[54:57], v[118:121], v[180:183], v[54:57]
	v_mfma_f32_16x16x32_bf16 v[146:149], v[110:113], v[196:199], v[146:149]
	v_mfma_f32_16x16x32_bf16 v[50:53], v[118:121], v[196:199], v[50:53]
	v_mfma_f32_16x16x32_bf16 v[130:133], v[110:113], v[204:207], v[130:133]
	v_mfma_f32_16x16x32_bf16 v[34:37], v[118:121], v[204:207], v[34:37]
	v_mfma_f32_16x16x32_bf16 v[122:125], v[110:113], v[212:215], v[122:125]
	v_mfma_f32_16x16x32_bf16 v[26:29], v[118:121], v[212:215], v[26:29]
	s_barrier
	s_add_i32 s34, s34, s20
	v_lshl_add_u64 v[188:189], s[46:47], 0, v[168:169]
	s_mov_b32 m0, s34
	ds_read_b128 v[162:165], v238 offset:16384
	ds_read_b128 v[180:183], v238 offset:17408
	ds_read_b128 v[184:187], v238 offset:18432
	ds_read_b128 v[196:199], v238 offset:19456
	ds_read_b128 v[200:203], v238 offset:20480
	ds_read_b128 v[204:207], v238 offset:21504
	ds_read_b128 v[208:211], v238 offset:22528
	ds_read_b128 v[212:215], v238 offset:23552
	global_load_lds_dwordx4 v[188:189], off
	s_add_i32 m0, s34, 0x2000
	s_add_u32 s44, s46, 0x40000
	v_lshl_add_u64 v[224:225], s[46:47], 0, v[172:173]
	s_addc_u32 s45, s47, 0
	s_add_i32 s34, s35, s20
	global_load_lds_dwordx4 v[224:225], off
	v_lshl_add_u64 v[228:229], s[44:45], 0, v[168:169]
	s_mov_b32 m0, s34
	v_lshl_add_u64 v[230:231], s[48:49], 0, v[170:171]
	global_load_lds_dwordx4 v[228:229], off
	v_lshl_add_u64 v[228:229], s[44:45], 0, v[172:173]
	s_add_i32 m0, s34, 0x2000
	s_nop 0
	global_load_lds_dwordx4 v[228:229], off
	v_lshl_add_u64 v[228:229], s[48:49], 0, v[166:167]
	s_mov_b32 m0, s40
	s_nop 0
	global_load_lds_dwordx4 v[228:229], off
	s_mov_b32 m0, s41
	s_nop 0
	global_load_lds_dwordx4 v[230:231], off
	s_waitcnt vmcnt(8)
	s_waitcnt lgkmcnt(0)
	s_barrier
	s_waitcnt lgkmcnt(0)
	v_mfma_f32_16x16x32_bf16 v[86:89], v[90:93], v[162:165], v[86:89]
	v_mfma_f32_16x16x32_bf16 v[22:25], v[98:101], v[162:165], v[22:25]
	v_mfma_f32_16x16x32_bf16 v[78:81], v[90:93], v[184:187], v[78:81]
	v_mfma_f32_16x16x32_bf16 v[14:17], v[98:101], v[184:187], v[14:17]
	v_mfma_f32_16x16x32_bf16 v[70:73], v[90:93], v[200:203], v[70:73]
	v_mfma_f32_16x16x32_bf16 v[6:9], v[98:101], v[200:203], v[6:9]
	v_mfma_f32_16x16x32_bf16 v[46:49], v[98:101], v[208:211], v[46:49]
	v_mfma_f32_16x16x32_bf16 v[86:89], v[94:97], v[180:183], v[86:89]
	v_mfma_f32_16x16x32_bf16 v[22:25], v[102:105], v[180:183], v[22:25]
	v_mfma_f32_16x16x32_bf16 v[78:81], v[94:97], v[196:199], v[78:81]
	v_mfma_f32_16x16x32_bf16 v[14:17], v[102:105], v[196:199], v[14:17]
	v_mfma_f32_16x16x32_bf16 v[70:73], v[94:97], v[204:207], v[70:73]
	v_mfma_f32_16x16x32_bf16 v[6:9], v[102:105], v[204:207], v[6:9]
	v_mfma_f32_16x16x32_bf16 v[90:93], v[90:93], v[208:211], v[142:145]
	v_mfma_f32_16x16x32_bf16 v[46:49], v[102:105], v[212:215], v[46:49]
	v_mfma_f32_16x16x32_bf16 v[90:93], v[94:97], v[212:215], v[90:93]
	v_mfma_f32_16x16x32_bf16 v[82:85], v[106:109], v[162:165], v[82:85]
	v_mfma_f32_16x16x32_bf16 v[18:21], v[114:117], v[162:165], v[18:21]
	v_mfma_f32_16x16x32_bf16 v[74:77], v[106:109], v[184:187], v[74:77]
	v_mfma_f32_16x16x32_bf16 v[10:13], v[114:117], v[184:187], v[10:13]
	v_mfma_f32_16x16x32_bf16 v[66:69], v[106:109], v[200:203], v[66:69]
	v_mfma_f32_16x16x32_bf16 v[2:5], v[114:117], v[200:203], v[2:5]
	v_mfma_f32_16x16x32_bf16 v[42:45], v[114:117], v[208:211], v[42:45]
	v_mfma_f32_16x16x32_bf16 v[82:85], v[110:113], v[180:183], v[82:85]
	v_mfma_f32_16x16x32_bf16 v[18:21], v[118:121], v[180:183], v[18:21]
	v_mfma_f32_16x16x32_bf16 v[74:77], v[110:113], v[196:199], v[74:77]
	v_mfma_f32_16x16x32_bf16 v[10:13], v[118:121], v[196:199], v[10:13]
	v_mfma_f32_16x16x32_bf16 v[66:69], v[110:113], v[204:207], v[66:69]
	v_mfma_f32_16x16x32_bf16 v[2:5], v[118:121], v[204:207], v[2:5]
	v_mfma_f32_16x16x32_bf16 v[94:97], v[106:109], v[208:211], v[138:141]
	v_mfma_f32_16x16x32_bf16 v[42:45], v[118:121], v[212:215], v[42:45]
	v_mfma_f32_16x16x32_bf16 v[94:97], v[110:113], v[212:215], v[94:97]
	s_barrier
; #define PG8_STAGEA(bufoff, gbase, voff) do { _Pragma("unroll") for (int _i = 0; _i < 2; ++_i) \
;         __builtin_amdgcn_global_load_lds((const unsigned*)((const char*)(gbase) + (voff)[_i]), (LAS unsigned*)(lds + (bufoff) + ldsw + _i * 8192), 16, 0, 0); } while (0)
; #define PG8_LDA(dst, b, h) do { _Pragma("unroll") for (int m = 0; m < 4; ++m) _Pragma("unroll") for (int k = 0; k < 2; ++k) dst[m][k] = *(const LAS bf16x8*)(lds + PG8_SA(b, h) + aoff + m * 2048 + k * 1024); } while (0)
; #define PG8_LDB(dst, b, h) do { _Pragma("unroll") for (int n = 0; n < 2; ++n) _Pragma("unroll") for (int k = 0; k < 2; ++k) dst[n][k] = *(const LAS bf16x8*)(lds + PG8_SB(b, h) + boff + n * 2048 + k * 1024); } while (0)
; #define PG8_MMA(ai, bj, At, Bt) do { __builtin_amdgcn_s_setprio(3); _Pragma("unroll") for (int m = 0; m < 4; ++m) _Pragma("unroll") for (int n = 0; n < 2; ++n) _Pragma("unroll") for (int k = 0; k < 2; ++k) \
;         acc[ai][bj][m][n] = __builtin_amdgcn_mfma_f32_16x16x32_bf16(Bt[n][k], At[m][k], acc[ai][bj][m][n], 0, 0, 0); __builtin_amdgcn_s_setprio(0); } while (0)
; #define PG8_WAIT_V(n) asm volatile("s_waitcnt vmcnt(" #n ")" ::: "memory")
; #define PG8_WAIT_L(n) asm volatile("s_waitcnt lgkmcnt(" #n ")" ::: "memory")
; #define PG8_BAR __builtin_amdgcn_s_barrier()
; #define PG8_SCHED __builtin_amdgcn_sched_barrier(0)
; template <class Epi, int PARTS>
; __device__ __forceinline__ void gemm_phase(LAS unsigned char* lds, const Gemm g, const StaticOrder& S, const Epi& E) {
;     ...
;             PG8_LDB(B0, 1, 0); PG8_LDB(B1, 1, 1); PG8_SCHED; PG8_LDA(At, 1, 0); PG8_STAGEA(PG8_SA(0, 1), a2 + hstepA, voffA);
;             PG8_WAIT_V(8); PG8_WAIT_L(0); PG8_BAR; PG8_MMA(0, 0, At, B0); PG8_MMA(0, 1, At, B1); PG8_BAR; PG8_SCHED;
	s_add_i32 s34, 0, 0x18000
	v_add_u32_e32 v0, s34, v235
	s_add_i32 s35, 0, 0x1c000
	ds_read_b128 v[98:101], v0
	ds_read_b128 v[102:105], v0 offset:1024
	ds_read_b128 v[106:109], v0 offset:2048
	ds_read_b128 v[110:113], v0 offset:3072
	v_add_u32_e32 v0, s35, v235
	ds_read_b128 v[114:117], v0
	ds_read_b128 v[118:121], v0 offset:1024
	ds_read_b128 v[162:165], v0 offset:2048
	ds_read_b128 v[180:183], v0 offset:3072
	s_add_u32 s44, s48, 0x2000
	s_addc_u32 s45, s49, 0
	s_mov_b32 m0, s87
	v_lshl_add_u64 v[240:241], s[44:45], 0, v[166:167]
	ds_read_b128 v[138:141], v238 offset:32768
	ds_read_b128 v[142:145], v238 offset:33792
	ds_read_b128 v[184:187], v238 offset:34816
	ds_read_b128 v[196:199], v238 offset:35840
	ds_read_b128 v[200:203], v238 offset:36864
	ds_read_b128 v[204:207], v238 offset:37888
	ds_read_b128 v[208:211], v238 offset:38912
	ds_read_b128 v[212:215], v238 offset:39936
	global_load_lds_dwordx4 v[240:241], off
	v_lshl_add_u64 v[240:241], s[44:45], 0, v[170:171]
	s_mov_b32 m0, s69
	s_nop 0
	global_load_lds_dwordx4 v[240:241], off
	s_waitcnt vmcnt(8)
	s_waitcnt lgkmcnt(0)
	s_barrier
	s_waitcnt lgkmcnt(0)
	v_mfma_f32_16x16x32_bf16 v[158:161], v[98:101], v[138:141], v[158:161]
	v_mfma_f32_16x16x32_bf16 v[62:65], v[106:109], v[138:141], v[62:65]
	v_mfma_f32_16x16x32_bf16 v[154:157], v[98:101], v[184:187], v[154:157]
	v_mfma_f32_16x16x32_bf16 v[58:61], v[106:109], v[184:187], v[58:61]
	v_mfma_f32_16x16x32_bf16 v[134:137], v[98:101], v[200:203], v[134:137]
	v_mfma_f32_16x16x32_bf16 v[38:41], v[106:109], v[200:203], v[38:41]
	v_mfma_f32_16x16x32_bf16 v[126:129], v[98:101], v[208:211], v[126:129]
	v_mfma_f32_16x16x32_bf16 v[30:33], v[106:109], v[208:211], v[30:33]
	v_mfma_f32_16x16x32_bf16 v[158:161], v[102:105], v[142:145], v[158:161]
	v_mfma_f32_16x16x32_bf16 v[62:65], v[110:113], v[142:145], v[62:65]
	v_mfma_f32_16x16x32_bf16 v[154:157], v[102:105], v[196:199], v[154:157]
	v_mfma_f32_16x16x32_bf16 v[58:61], v[110:113], v[196:199], v[58:61]
	v_mfma_f32_16x16x32_bf16 v[134:137], v[102:105], v[204:207], v[134:137]
	v_mfma_f32_16x16x32_bf16 v[38:41], v[110:113], v[204:207], v[38:41]
	v_mfma_f32_16x16x32_bf16 v[126:129], v[102:105], v[212:215], v[126:129]
	v_mfma_f32_16x16x32_bf16 v[30:33], v[110:113], v[212:215], v[30:33]
	v_mfma_f32_16x16x32_bf16 v[150:153], v[114:117], v[138:141], v[150:153]
	v_mfma_f32_16x16x32_bf16 v[54:57], v[162:165], v[138:141], v[54:57]
	v_mfma_f32_16x16x32_bf16 v[138:141], v[114:117], v[184:187], v[146:149]
	v_mfma_f32_16x16x32_bf16 v[50:53], v[162:165], v[184:187], v[50:53]
	v_mfma_f32_16x16x32_bf16 v[130:133], v[114:117], v[200:203], v[130:133]
	v_mfma_f32_16x16x32_bf16 v[34:37], v[162:165], v[200:203], v[34:37]
	v_mfma_f32_16x16x32_bf16 v[122:125], v[114:117], v[208:211], v[122:125]
	v_mfma_f32_16x16x32_bf16 v[26:29], v[162:165], v[208:211], v[26:29]
	v_mfma_f32_16x16x32_bf16 v[150:153], v[118:121], v[142:145], v[150:153]
	v_mfma_f32_16x16x32_bf16 v[54:57], v[180:183], v[142:145], v[54:57]
	v_mfma_f32_16x16x32_bf16 v[146:149], v[118:121], v[196:199], v[138:141]
	v_mfma_f32_16x16x32_bf16 v[50:53], v[180:183], v[196:199], v[50:53]
	v_mfma_f32_16x16x32_bf16 v[130:133], v[118:121], v[204:207], v[130:133]
	v_mfma_f32_16x16x32_bf16 v[34:37], v[180:183], v[204:207], v[34:37]
	v_mfma_f32_16x16x32_bf16 v[122:125], v[118:121], v[212:215], v[122:125]
	v_mfma_f32_16x16x32_bf16 v[26:29], v[180:183], v[212:215], v[26:29]
	s_barrier
; #define PG8_STAGE(bufoff, gbase, voff) do { _Pragma("unroll") for (int _i = 0; _i < 2; ++_i) \
;         __builtin_amdgcn_global_load_lds((const unsigned*)((const char*)(gbase) + (voff)[_i]), (LAS unsigned*)(lds + (bufoff) + ldsw + _i * 8192), 16, 0, 0); } while (0)
; #define PG8_STAGEA(bufoff, gbase, voff) do { _Pragma("unroll") for (int _i = 0; _i < 2; ++_i) \
;         __builtin_amdgcn_global_load_lds((const unsigned*)((const char*)(gbase) + (voff)[_i]), (LAS unsigned*)(lds + (bufoff) + ldsw + _i * 8192), 16, 0, 0); } while (0)
; #define PG8_LDA(dst, b, h) do { _Pragma("unroll") for (int m = 0; m < 4; ++m) _Pragma("unroll") for (int k = 0; k < 2; ++k) dst[m][k] = *(const LAS bf16x8*)(lds + PG8_SA(b, h) + aoff + m * 2048 + k * 1024); } while (0)
; #define PG8_MMA(ai, bj, At, Bt) do { __builtin_amdgcn_s_setprio(3); _Pragma("unroll") for (int m = 0; m < 4; ++m) _Pragma("unroll") for (int n = 0; n < 2; ++n) _Pragma("unroll") for (int k = 0; k < 2; ++k) \
;         acc[ai][bj][m][n] = __builtin_amdgcn_mfma_f32_16x16x32_bf16(Bt[n][k], At[m][k], acc[ai][bj][m][n], 0, 0, 0); __builtin_amdgcn_s_setprio(0); } while (0)
; #define PG8_WAIT_V(n) asm volatile("s_waitcnt vmcnt(" #n ")" ::: "memory")
; #define PG8_WAIT_L(n) asm volatile("s_waitcnt lgkmcnt(" #n ")" ::: "memory")
; #define PG8_BAR __builtin_amdgcn_s_barrier()
; #define PG8_SCHED __builtin_amdgcn_sched_barrier(0)
; template <class Epi, int PARTS>
; __device__ __forceinline__ void gemm_phase(LAS unsigned char* lds, const Gemm g, const StaticOrder& S, const Epi& E) {
;     ...
;             PG8_LDA(At, 1, 1); PG8_STAGE(PG8_SB(1, 0), b3, voffB); PG8_STAGE(PG8_SB(1, 1), b3 + hstepB, voffB); PG8_STAGEA(PG8_SA(1, 0), a3, voffA);
;             PG8_WAIT_V(8); PG8_WAIT_L(0); PG8_BAR; PG8_MMA(1, 0, At, B0); PG8_MMA(1, 1, At, B1); PG8_BAR; PG8_SCHED;
;         }
	s_add_i32 s34, s34, s20
	v_lshl_add_u64 v[142:143], v[188:189], 0, s[72:73]
	s_mov_b32 m0, s34
	ds_read_b128 v[138:141], v238 offset:49152
	ds_read_b128 v[184:187], v238 offset:50176
	ds_read_b128 v[196:199], v238 offset:51200
	ds_read_b128 v[200:203], v238 offset:52224
	ds_read_b128 v[204:207], v238 offset:53248
	ds_read_b128 v[208:211], v238 offset:54272
	ds_read_b128 v[212:215], v238 offset:55296
	ds_read_b128 v[240:243], v238 offset:56320
	global_load_lds_dwordx4 v[142:143], off
	s_add_i32 m0, s34, 0x2000
	s_add_u32 s44, s46, 0x40080
	v_lshl_add_u64 v[142:143], v[224:225], 0, s[72:73]
	s_addc_u32 s45, s47, 0
	s_add_i32 s34, s35, s20
	global_load_lds_dwordx4 v[142:143], off
	v_lshl_add_u64 v[142:143], s[44:45], 0, v[168:169]
	s_mov_b32 m0, s34
	s_nop 0
	global_load_lds_dwordx4 v[142:143], off
	v_lshl_add_u64 v[142:143], s[44:45], 0, v[172:173]
	s_add_i32 m0, s34, 0x2000
	s_nop 0
	global_load_lds_dwordx4 v[142:143], off
	v_lshl_add_u64 v[142:143], v[228:229], 0, s[72:73]
	s_mov_b32 m0, s33
	s_nop 0
	global_load_lds_dwordx4 v[142:143], off
	v_lshl_add_u64 v[142:143], v[230:231], 0, s[72:73]
	s_mov_b32 m0, s36
	s_nop 0
	global_load_lds_dwordx4 v[142:143], off
	s_waitcnt vmcnt(8)
	s_waitcnt lgkmcnt(0)
	s_barrier
	s_waitcnt lgkmcnt(0)
	v_mfma_f32_16x16x32_bf16 v[86:89], v[98:101], v[138:141], v[86:89]
	v_mfma_f32_16x16x32_bf16 v[22:25], v[106:109], v[138:141], v[22:25]
	v_mfma_f32_16x16x32_bf16 v[78:81], v[98:101], v[196:199], v[78:81]
	v_mfma_f32_16x16x32_bf16 v[14:17], v[106:109], v[196:199], v[14:17]
	v_mfma_f32_16x16x32_bf16 v[70:73], v[98:101], v[204:207], v[70:73]
	v_mfma_f32_16x16x32_bf16 v[6:9], v[106:109], v[204:207], v[6:9]
	v_mfma_f32_16x16x32_bf16 v[90:93], v[98:101], v[212:215], v[90:93]
	v_mfma_f32_16x16x32_bf16 v[46:49], v[106:109], v[212:215], v[46:49]
	v_mfma_f32_16x16x32_bf16 v[86:89], v[102:105], v[184:187], v[86:89]
	v_mfma_f32_16x16x32_bf16 v[22:25], v[110:113], v[184:187], v[22:25]
	v_mfma_f32_16x16x32_bf16 v[78:81], v[102:105], v[200:203], v[78:81]
	v_mfma_f32_16x16x32_bf16 v[14:17], v[110:113], v[200:203], v[14:17]
	v_mfma_f32_16x16x32_bf16 v[70:73], v[102:105], v[208:211], v[70:73]
	v_mfma_f32_16x16x32_bf16 v[6:9], v[110:113], v[208:211], v[6:9]
	v_mfma_f32_16x16x32_bf16 v[142:145], v[102:105], v[240:243], v[90:93]
	v_mfma_f32_16x16x32_bf16 v[46:49], v[110:113], v[240:243], v[46:49]
	v_mfma_f32_16x16x32_bf16 v[82:85], v[114:117], v[138:141], v[82:85]
	v_mfma_f32_16x16x32_bf16 v[18:21], v[162:165], v[138:141], v[18:21]
	v_mfma_f32_16x16x32_bf16 v[74:77], v[114:117], v[196:199], v[74:77]
	v_mfma_f32_16x16x32_bf16 v[10:13], v[162:165], v[196:199], v[10:13]
	v_mfma_f32_16x16x32_bf16 v[66:69], v[114:117], v[204:207], v[66:69]
	v_mfma_f32_16x16x32_bf16 v[2:5], v[162:165], v[204:207], v[2:5]
	v_mfma_f32_16x16x32_bf16 v[90:93], v[114:117], v[212:215], v[94:97]
	v_mfma_f32_16x16x32_bf16 v[42:45], v[162:165], v[212:215], v[42:45]
	v_mfma_f32_16x16x32_bf16 v[82:85], v[118:121], v[184:187], v[82:85]
	v_mfma_f32_16x16x32_bf16 v[18:21], v[180:183], v[184:187], v[18:21]
	v_mfma_f32_16x16x32_bf16 v[74:77], v[118:121], v[200:203], v[74:77]
	v_mfma_f32_16x16x32_bf16 v[10:13], v[180:183], v[200:203], v[10:13]
	v_mfma_f32_16x16x32_bf16 v[66:69], v[118:121], v[208:211], v[66:69]
	v_mfma_f32_16x16x32_bf16 v[2:5], v[180:183], v[208:211], v[2:5]
	v_mfma_f32_16x16x32_bf16 v[138:141], v[118:121], v[240:243], v[90:93]
	v_mfma_f32_16x16x32_bf16 v[42:45], v[180:183], v[240:243], v[42:45]
	s_barrier
	s_add_i32 s53, s53, 2
	s_add_u32 s51, s51, 0x100
	s_addc_u32 s52, s52, 0
	s_cmp_gt_u32 s53, 13
	s_mov_b64 s[44:45], s[0:1]
	s_cbranch_scc0 .LBB0_117
	s_setprio 0
	v_readlane_b32 s0, v254, 62
	v_readlane_b32 s1, v254, 63
	s_and_b64 vcc, exec, s[0:1]
	s_cbranch_vccz .LBB0_120
	s_barrier

; #define PG8_STAGEA(bufoff, gbase, voff) do { _Pragma("unroll") for (int _i = 0; _i < 2; ++_i) \
;         __builtin_amdgcn_global_load_lds((const unsigned*)((const char*)(gbase) + (voff)[_i]), (LAS unsigned*)(lds + (bufoff) + ldsw + _i * 8192), 16, 0, 0); } while (0)
; #define PG8_LDA(dst, b, h) do { _Pragma("unroll") for (int m = 0; m < 4; ++m) _Pragma("unroll") for (int k = 0; k < 2; ++k) dst[m][k] = *(const LAS bf16x8*)(lds + PG8_SA(b, h) + aoff + m * 2048 + k * 1024); } while (0)
; #define PG8_LDB(dst, b, h) do { _Pragma("unroll") for (int n = 0; n < 2; ++n) _Pragma("unroll") for (int k = 0; k < 2; ++k) dst[n][k] = *(const LAS bf16x8*)(lds + PG8_SB(b, h) + boff + n * 2048 + k * 1024); } while (0)
; #define PG8_MMA(ai, bj, At, Bt) do { __builtin_amdgcn_s_setprio(3); _Pragma("unroll") for (int m = 0; m < 4; ++m) _Pragma("unroll") for (int n = 0; n < 2; ++n) _Pragma("unroll") for (int k = 0; k < 2; ++k) \
;         acc[ai][bj][m][n] = __builtin_amdgcn_mfma_f32_16x16x32_bf16(Bt[n][k], At[m][k], acc[ai][bj][m][n], 0, 0, 0); __builtin_amdgcn_s_setprio(0); } while (0)
; #define PG8_WAIT_V(n) asm volatile("s_waitcnt vmcnt(" #n ")" ::: "memory")
; #define PG8_BAR __builtin_amdgcn_s_barrier()
; template <class Epi, int PARTS>
; __device__ __forceinline__ void gemm_phase(LAS unsigned char* lds, const Gemm g, const StaticOrder& S, const Epi& E) {
;     ...
;         const bool has_next = S.next(ui + 1, nxt);
;         const char* nA = has_next ? PG8_UA(nxt) : cA; const char* nB = has_next ? PG8_UB(nxt) : cB;
;         for (int t = 0; t < nt; t += 2) {
;             const bool last = (t == nt - 2);
;             const char* a1 = cA + (size_t)(t + 1) * kstep;
;             const char* a2 = last ? nA : cA + (size_t)(t + 2) * kstep; const char* b2 = last ? nB : cB + (size_t)(t + 2) * kstep;
;             const char* a3 = a2 + kstep; const char* b3 = b2 + kstep;
;             PG8_LDB(B0, 0, 0); PG8_LDB(B1, 0, 1); PG8_SCHED; PG8_LDA(At, 0, 0); PG8_STAGEA(PG8_SA(1, 1), a1 + hstepA, voffA);
;             PG8_WAIT_V(8); PG8_WAIT_L(0); PG8_BAR; PG8_MMA(0, 0, At, B0); PG8_MMA(0, 1, At, B1); PG8_BAR; PG8_SCHED;
;     ...
;         for (int a = 0; a < 2; ++a)
; #pragma unroll
;             for (int b = 0; b < 2; ++b)
; #pragma unroll
;                 for (int m = 0; m < 4; ++m)
; #pragma unroll
;                     for (int n = 0; n < 2; ++n) acc[a][b][m][n] = (f32x4){0.f, 0.f, 0.f, 0.f};
.LBB0_168:
	s_ashr_i32 s51, s50, 31
	s_lshl_b64 s[52:53], s[50:51], 19
	s_add_u32 s52, s70, s52
	s_addc_u32 s53, s71, s53
	s_and_b64 s[54:55], s[40:41], exec
	s_cselect_b32 s51, s53, s59
	s_cselect_b32 s57, s52, s58
	s_ashr_i32 s49, s48, 31
	s_lshl_b64 s[54:55], s[48:49], 19
	s_add_u32 s54, s64, s54
	s_addc_u32 s55, s65, s55
	s_and_b64 s[62:63], s[40:41], exec
	s_cselect_b32 s49, s55, s61
	s_cselect_b32 s77, s54, s60
	s_add_u32 s58, s58, 0x40080
	s_addc_u32 s59, s59, 0
	s_add_u32 s80, s60, 0x100
	v_mov_b32_e32 v2, 0
	s_addc_u32 s81, s61, 0
	s_mov_b32 s82, -2
	s_waitcnt lgkmcnt(0)
	v_mov_b32_e32 v3, v2
	v_mov_b32_e32 v4, v2
	v_mov_b32_e32 v5, v2
	v_mov_b32_e32 v6, v2
	v_mov_b32_e32 v7, v2
	v_mov_b32_e32 v8, v2
	v_mov_b32_e32 v9, v2
	v_mov_b32_e32 v18, v2
	v_mov_b32_e32 v19, v2
	v_mov_b32_e32 v20, v2
	v_mov_b32_e32 v21, v2
	v_mov_b32_e32 v22, v2
	v_mov_b32_e32 v23, v2
	v_mov_b32_e32 v24, v2
	v_mov_b32_e32 v25, v2
	s_waitcnt vmcnt(0)
	v_mov_b32_e32 v34, v2
	v_mov_b32_e32 v35, v2
	v_mov_b32_e32 v36, v2
	v_mov_b32_e32 v37, v2
	v_mov_b32_e32 v38, v2
	v_mov_b32_e32 v39, v2
	v_mov_b32_e32 v40, v2
	v_mov_b32_e32 v41, v2
	v_mov_b32_e32 v50, v2
	v_mov_b32_e32 v51, v2
	v_mov_b32_e32 v52, v2
	v_mov_b32_e32 v53, v2
	v_mov_b32_e32 v54, v2
	v_mov_b32_e32 v55, v2
	v_mov_b32_e32 v56, v2
	v_mov_b32_e32 v57, v2
	v_mov_b32_e32 v10, v2
	v_mov_b32_e32 v11, v2
	v_mov_b32_e32 v12, v2
	v_mov_b32_e32 v13, v2
	v_mov_b32_e32 v14, v2
	v_mov_b32_e32 v15, v2
	v_mov_b32_e32 v16, v2
	v_mov_b32_e32 v17, v2
	v_mov_b32_e32 v26, v2
	v_mov_b32_e32 v27, v2
	v_mov_b32_e32 v28, v2
	v_mov_b32_e32 v29, v2
	v_mov_b32_e32 v30, v2
	v_mov_b32_e32 v31, v2
	v_mov_b32_e32 v32, v2
	v_mov_b32_e32 v33, v2
	v_mov_b32_e32 v42, v2
	v_mov_b32_e32 v43, v2
	v_mov_b32_e32 v44, v2
	v_mov_b32_e32 v45, v2
	v_mov_b32_e32 v46, v2
	v_mov_b32_e32 v47, v2
	v_mov_b32_e32 v48, v2
	v_mov_b32_e32 v49, v2
	v_mov_b32_e32 v58, v2
	v_mov_b32_e32 v59, v2
	v_mov_b32_e32 v60, v2
	v_mov_b32_e32 v61, v2
	v_mov_b32_e32 v62, v2
	v_mov_b32_e32 v63, v2
	v_mov_b32_e32 v64, v2
	v_mov_b32_e32 v65, v2
	v_mov_b32_e32 v66, v2
	v_mov_b32_e32 v67, v2
	v_mov_b32_e32 v68, v2
	v_mov_b32_e32 v69, v2
	v_mov_b32_e32 v70, v2
	v_mov_b32_e32 v71, v2
	v_mov_b32_e32 v72, v2
	v_mov_b32_e32 v73, v2
	v_mov_b32_e32 v82, v2
	v_mov_b32_e32 v83, v2
	v_mov_b32_e32 v84, v2
	v_mov_b32_e32 v85, v2
	v_mov_b32_e32 v86, v2
	v_mov_b32_e32 v87, v2
	v_mov_b32_e32 v88, v2
	v_mov_b32_e32 v89, v2
	v_mov_b32_e32 v98, v2
	v_mov_b32_e32 v99, v2
	v_mov_b32_e32 v100, v2
	v_mov_b32_e32 v101, v2
	v_mov_b32_e32 v102, v2
	v_mov_b32_e32 v103, v2
	v_mov_b32_e32 v104, v2
	v_mov_b32_e32 v105, v2
	v_mov_b32_e32 v114, v2
	v_mov_b32_e32 v115, v2
	v_mov_b32_e32 v116, v2
	v_mov_b32_e32 v117, v2
	v_mov_b32_e32 v118, v2
	v_mov_b32_e32 v119, v2
	v_mov_b32_e32 v120, v2
	v_mov_b32_e32 v121, v2
	v_mov_b32_e32 v74, v2
	v_mov_b32_e32 v75, v2
	v_mov_b32_e32 v76, v2
	v_mov_b32_e32 v77, v2
	v_mov_b32_e32 v78, v2
	v_mov_b32_e32 v79, v2
	v_mov_b32_e32 v80, v2
	v_mov_b32_e32 v81, v2
	v_mov_b32_e32 v90, v2
	v_mov_b32_e32 v91, v2
	v_mov_b32_e32 v92, v2
	v_mov_b32_e32 v93, v2
	v_mov_b32_e32 v94, v2
	v_mov_b32_e32 v95, v2
	v_mov_b32_e32 v96, v2
	v_mov_b32_e32 v97, v2
	v_mov_b32_e32 v106, v2
	v_mov_b32_e32 v107, v2
	v_mov_b32_e32 v108, v2
	v_mov_b32_e32 v109, v2
	v_mov_b32_e32 v110, v2
	v_mov_b32_e32 v111, v2
	v_mov_b32_e32 v112, v2
	v_mov_b32_e32 v113, v2
	v_mov_b32_e32 v122, v2
	v_mov_b32_e32 v123, v2
	v_mov_b32_e32 v124, v2
	v_mov_b32_e32 v125, v2
	v_mov_b32_e32 v126, v2
	v_mov_b32_e32 v127, v2
	v_mov_b32_e32 v128, v2
	v_mov_b32_e32 v129, v2
	v_readfirstlane_b32 s99, v216
	s_cmp_lt_u32 s99, 0x100
	s_cbranch_scc1 .Lgprio1
	s_setprio 1
.Lgprio1:
.LBB0_169:
	s_add_u32 s34, s58, 0xfffc0080
	s_addc_u32 s35, s59, -1
	s_add_i32 s83, 0, 0x10000
	s_cmp_eq_u32 s82, 12
	s_cselect_b32 s63, s51, s35
	s_cselect_b32 s62, s57, s34
	s_cselect_b32 s61, s49, s81
	s_cselect_b32 s60, s77, s80
	s_add_i32 s34, 0, 0x14000
	v_add_u32_e32 v152, s83, v141
	v_add_u32_e32 v168, s34, v141
	ds_read_b128 v[136:139], v152
	ds_read_b128 v[144:147], v152 offset:1024
	ds_read_b128 v[148:151], v152 offset:2048
	ds_read_b128 v[152:155], v152 offset:3072
	ds_read_b128 v[156:159], v168
	ds_read_b128 v[160:163], v168 offset:1024
	ds_read_b128 v[164:167], v168 offset:2048
	ds_read_b128 v[168:171], v168 offset:3072
	v_lshl_add_u64 v[188:189], s[58:59], 0, v[132:133]
	s_add_i32 m0, s67, 0xc000
	ds_read_b128 v[172:175], v143
	ds_read_b128 v[176:179], v143 offset:1024
	ds_read_b128 v[180:183], v143 offset:2048
	ds_read_b128 v[184:187], v143 offset:3072
	ds_read_b128 v[196:199], v143 offset:4096
	ds_read_b128 v[200:203], v143 offset:5120
	ds_read_b128 v[204:207], v143 offset:6144
	ds_read_b128 v[208:211], v143 offset:7168
	global_load_lds_dwordx4 v[188:189], off
	v_lshl_add_u64 v[188:189], s[58:59], 0, v[134:135]
	s_add_i32 m0, s67, 0xe000
	s_nop 0
	global_load_lds_dwordx4 v[188:189], off
	s_waitcnt vmcnt(8)
	s_waitcnt lgkmcnt(0)
	s_barrier
; #define PG8_STAGE(bufoff, gbase, voff) do { _Pragma("unroll") for (int _i = 0; _i < 2; ++_i) \
;         __builtin_amdgcn_global_load_lds((const unsigned*)((const char*)(gbase) + (voff)[_i]), (LAS unsigned*)(lds + (bufoff) + ldsw + _i * 8192), 16, 0, 0); } while (0)
; #define PG8_STAGEA(bufoff, gbase, voff) do { _Pragma("unroll") for (int _i = 0; _i < 2; ++_i) \
;         __builtin_amdgcn_global_load_lds((const unsigned*)((const char*)(gbase) + (voff)[_i]), (LAS unsigned*)(lds + (bufoff) + ldsw + _i * 8192), 16, 0, 0); } while (0)
; #define PG8_LDA(dst, b, h) do { _Pragma("unroll") for (int m = 0; m < 4; ++m) _Pragma("unroll") for (int k = 0; k < 2; ++k) dst[m][k] = *(const LAS bf16x8*)(lds + PG8_SA(b, h) + aoff + m * 2048 + k * 1024); } while (0)
; #define PG8_LDB(dst, b, h) do { _Pragma("unroll") for (int n = 0; n < 2; ++n) _Pragma("unroll") for (int k = 0; k < 2; ++k) dst[n][k] = *(const LAS bf16x8*)(lds + PG8_SB(b, h) + boff + n * 2048 + k * 1024); } while (0)
; #define PG8_MMA(ai, bj, At, Bt) do { __builtin_amdgcn_s_setprio(3); _Pragma("unroll") for (int m = 0; m < 4; ++m) _Pragma("unroll") for (int n = 0; n < 2; ++n) _Pragma("unroll") for (int k = 0; k < 2; ++k) \
;         acc[ai][bj][m][n] = __builtin_amdgcn_mfma_f32_16x16x32_bf16(Bt[n][k], At[m][k], acc[ai][bj][m][n], 0, 0, 0); __builtin_amdgcn_s_setprio(0); } while (0)
; #define PG8_WAIT_V(n) asm volatile("s_waitcnt vmcnt(" #n ")" ::: "memory")
; #define PG8_WAIT_L(n) asm volatile("s_waitcnt lgkmcnt(" #n ")" ::: "memory")
; #define PG8_BAR __builtin_amdgcn_s_barrier()
; #define PG8_SCHED __builtin_amdgcn_sched_barrier(0)
; template <class Epi, int PARTS>
; __device__ __forceinline__ void gemm_phase(LAS unsigned char* lds, const Gemm g, const StaticOrder& S, const Epi& E) {
;     ...
;             PG8_LDB(B0, 0, 0); PG8_LDB(B1, 0, 1); PG8_SCHED; PG8_LDA(At, 0, 0); PG8_STAGEA(PG8_SA(1, 1), a1 + hstepA, voffA);
;             PG8_WAIT_V(8); PG8_WAIT_L(0); PG8_BAR; PG8_MMA(0, 0, At, B0); PG8_MMA(0, 1, At, B1); PG8_BAR; PG8_SCHED;
;             PG8_LDA(At, 0, 1); PG8_STAGE(PG8_SB(0, 0), b2, voffB); PG8_STAGE(PG8_SB(0, 1), b2 + hstepB, voffB); PG8_STAGEA(PG8_SA(0, 0), a2, voffA);
;             PG8_WAIT_V(8); PG8_WAIT_L(0); PG8_BAR; PG8_MMA(1, 0, At, B0); PG8_MMA(1, 1, At, B1); PG8_BAR; PG8_SCHED;
	s_waitcnt lgkmcnt(0)
	v_mfma_f32_16x16x32_bf16 v[126:129], v[136:139], v[172:175], v[126:129]
	v_mfma_f32_16x16x32_bf16 v[122:125], v[148:151], v[172:175], v[122:125]
	v_mfma_f32_16x16x32_bf16 v[110:113], v[136:139], v[180:183], v[110:113]
	v_mfma_f32_16x16x32_bf16 v[106:109], v[148:151], v[180:183], v[106:109]
	v_mfma_f32_16x16x32_bf16 v[94:97], v[136:139], v[196:199], v[94:97]
	v_mfma_f32_16x16x32_bf16 v[90:93], v[148:151], v[196:199], v[90:93]
	v_mfma_f32_16x16x32_bf16 v[78:81], v[136:139], v[204:207], v[78:81]
	v_mfma_f32_16x16x32_bf16 v[74:77], v[148:151], v[204:207], v[74:77]
	v_mfma_f32_16x16x32_bf16 v[126:129], v[144:147], v[176:179], v[126:129]
	v_mfma_f32_16x16x32_bf16 v[122:125], v[152:155], v[176:179], v[122:125]
	v_mfma_f32_16x16x32_bf16 v[110:113], v[144:147], v[184:187], v[110:113]
	v_mfma_f32_16x16x32_bf16 v[106:109], v[152:155], v[184:187], v[106:109]
	v_mfma_f32_16x16x32_bf16 v[94:97], v[144:147], v[200:203], v[94:97]
	v_mfma_f32_16x16x32_bf16 v[90:93], v[152:155], v[200:203], v[90:93]
	v_mfma_f32_16x16x32_bf16 v[78:81], v[144:147], v[208:211], v[78:81]
	v_mfma_f32_16x16x32_bf16 v[74:77], v[152:155], v[208:211], v[74:77]
	v_mfma_f32_16x16x32_bf16 v[118:121], v[156:159], v[172:175], v[118:121]
	v_mfma_f32_16x16x32_bf16 v[114:117], v[164:167], v[172:175], v[114:117]
	v_mfma_f32_16x16x32_bf16 v[102:105], v[156:159], v[180:183], v[102:105]
	v_mfma_f32_16x16x32_bf16 v[98:101], v[164:167], v[180:183], v[98:101]
	v_mfma_f32_16x16x32_bf16 v[86:89], v[156:159], v[196:199], v[86:89]
	v_mfma_f32_16x16x32_bf16 v[82:85], v[164:167], v[196:199], v[82:85]
	v_mfma_f32_16x16x32_bf16 v[70:73], v[156:159], v[204:207], v[70:73]
	v_mfma_f32_16x16x32_bf16 v[66:69], v[164:167], v[204:207], v[66:69]
	v_mfma_f32_16x16x32_bf16 v[118:121], v[160:163], v[176:179], v[118:121]
	v_mfma_f32_16x16x32_bf16 v[114:117], v[168:171], v[176:179], v[114:117]
	v_mfma_f32_16x16x32_bf16 v[102:105], v[160:163], v[184:187], v[102:105]
	v_mfma_f32_16x16x32_bf16 v[98:101], v[168:171], v[184:187], v[98:101]
	v_mfma_f32_16x16x32_bf16 v[86:89], v[160:163], v[200:203], v[86:89]
	v_mfma_f32_16x16x32_bf16 v[82:85], v[168:171], v[200:203], v[82:85]
	v_mfma_f32_16x16x32_bf16 v[70:73], v[160:163], v[208:211], v[70:73]
	v_mfma_f32_16x16x32_bf16 v[66:69], v[168:171], v[208:211], v[66:69]
	s_barrier
	s_add_i32 s35, s83, s66
	v_lshl_add_u64 v[188:189], s[60:61], 0, v[0:1]
	s_mov_b32 m0, s35
	ds_read_b128 v[172:175], v143 offset:16384
	ds_read_b128 v[176:179], v143 offset:17408
	ds_read_b128 v[180:183], v143 offset:18432
	ds_read_b128 v[184:187], v143 offset:19456
	ds_read_b128 v[196:199], v143 offset:20480
	ds_read_b128 v[200:203], v143 offset:21504
	ds_read_b128 v[204:207], v143 offset:22528
	ds_read_b128 v[208:211], v143 offset:23552
	global_load_lds_dwordx4 v[188:189], off
	s_add_i32 m0, s35, 0x2000
	s_add_u32 vcc_lo, s60, 0x40000
	v_lshl_add_u64 v[212:213], s[60:61], 0, v[130:131]
	s_addc_u32 vcc_hi, s61, 0
	s_add_i32 s34, s34, s66
	global_load_lds_dwordx4 v[212:213], off
	v_lshl_add_u64 v[214:215], vcc, 0, v[0:1]
	s_mov_b32 m0, s34
	v_lshl_add_u64 v[224:225], s[62:63], 0, v[130:131]
	global_load_lds_dwordx4 v[214:215], off
	v_lshl_add_u64 v[214:215], vcc, 0, v[130:131]
	s_add_i32 m0, s34, 0x2000
	s_nop 0
	global_load_lds_dwordx4 v[214:215], off
	v_lshl_add_u64 v[214:215], s[62:63], 0, v[0:1]
	s_mov_b32 m0, s67
	s_nop 0
	global_load_lds_dwordx4 v[214:215], off
	s_mov_b32 m0, s69
	s_nop 0
	global_load_lds_dwordx4 v[224:225], off
	s_waitcnt vmcnt(8)
	s_waitcnt lgkmcnt(0)
	s_barrier
	s_waitcnt lgkmcnt(0)
	v_mfma_f32_16x16x32_bf16 v[62:65], v[136:139], v[172:175], v[62:65]
	v_mfma_f32_16x16x32_bf16 v[58:61], v[148:151], v[172:175], v[58:61]
	v_mfma_f32_16x16x32_bf16 v[46:49], v[136:139], v[180:183], v[46:49]
	v_mfma_f32_16x16x32_bf16 v[42:45], v[148:151], v[180:183], v[42:45]
	v_mfma_f32_16x16x32_bf16 v[30:33], v[136:139], v[196:199], v[30:33]
	v_mfma_f32_16x16x32_bf16 v[26:29], v[148:151], v[196:199], v[26:29]
	v_mfma_f32_16x16x32_bf16 v[14:17], v[136:139], v[204:207], v[14:17]
	v_mfma_f32_16x16x32_bf16 v[10:13], v[148:151], v[204:207], v[10:13]
	v_mfma_f32_16x16x32_bf16 v[62:65], v[144:147], v[176:179], v[62:65]
	v_mfma_f32_16x16x32_bf16 v[58:61], v[152:155], v[176:179], v[58:61]
	v_mfma_f32_16x16x32_bf16 v[46:49], v[144:147], v[184:187], v[46:49]
	v_mfma_f32_16x16x32_bf16 v[42:45], v[152:155], v[184:187], v[42:45]
	v_mfma_f32_16x16x32_bf16 v[30:33], v[144:147], v[200:203], v[30:33]
	v_mfma_f32_16x16x32_bf16 v[26:29], v[152:155], v[200:203], v[26:29]
	v_mfma_f32_16x16x32_bf16 v[14:17], v[144:147], v[208:211], v[14:17]
	v_mfma_f32_16x16x32_bf16 v[10:13], v[152:155], v[208:211], v[10:13]
	v_mfma_f32_16x16x32_bf16 v[54:57], v[156:159], v[172:175], v[54:57]
	v_mfma_f32_16x16x32_bf16 v[50:53], v[164:167], v[172:175], v[50:53]
	v_mfma_f32_16x16x32_bf16 v[38:41], v[156:159], v[180:183], v[38:41]
	v_mfma_f32_16x16x32_bf16 v[34:37], v[164:167], v[180:183], v[34:37]
	v_mfma_f32_16x16x32_bf16 v[22:25], v[156:159], v[196:199], v[22:25]
	v_mfma_f32_16x16x32_bf16 v[18:21], v[164:167], v[196:199], v[18:21]
	v_mfma_f32_16x16x32_bf16 v[6:9], v[156:159], v[204:207], v[6:9]
	v_mfma_f32_16x16x32_bf16 v[2:5], v[164:167], v[204:207], v[2:5]
	v_mfma_f32_16x16x32_bf16 v[54:57], v[160:163], v[176:179], v[54:57]
	v_mfma_f32_16x16x32_bf16 v[50:53], v[168:171], v[176:179], v[50:53]
	v_mfma_f32_16x16x32_bf16 v[38:41], v[160:163], v[184:187], v[38:41]
	v_mfma_f32_16x16x32_bf16 v[34:37], v[168:171], v[184:187], v[34:37]
	v_mfma_f32_16x16x32_bf16 v[22:25], v[160:163], v[200:203], v[22:25]
	v_mfma_f32_16x16x32_bf16 v[18:21], v[168:171], v[200:203], v[18:21]
	v_mfma_f32_16x16x32_bf16 v[6:9], v[160:163], v[208:211], v[6:9]
	v_mfma_f32_16x16x32_bf16 v[2:5], v[168:171], v[208:211], v[2:5]
	s_barrier
; #define PG8_STAGEA(bufoff, gbase, voff) do { _Pragma("unroll") for (int _i = 0; _i < 2; ++_i) \
;         __builtin_amdgcn_global_load_lds((const unsigned*)((const char*)(gbase) + (voff)[_i]), (LAS unsigned*)(lds + (bufoff) + ldsw + _i * 8192), 16, 0, 0); } while (0)
; #define PG8_LDA(dst, b, h) do { _Pragma("unroll") for (int m = 0; m < 4; ++m) _Pragma("unroll") for (int k = 0; k < 2; ++k) dst[m][k] = *(const LAS bf16x8*)(lds + PG8_SA(b, h) + aoff + m * 2048 + k * 1024); } while (0)
; #define PG8_LDB(dst, b, h) do { _Pragma("unroll") for (int n = 0; n < 2; ++n) _Pragma("unroll") for (int k = 0; k < 2; ++k) dst[n][k] = *(const LAS bf16x8*)(lds + PG8_SB(b, h) + boff + n * 2048 + k * 1024); } while (0)
; #define PG8_MMA(ai, bj, At, Bt) do { __builtin_amdgcn_s_setprio(3); _Pragma("unroll") for (int m = 0; m < 4; ++m) _Pragma("unroll") for (int n = 0; n < 2; ++n) _Pragma("unroll") for (int k = 0; k < 2; ++k) \
;         acc[ai][bj][m][n] = __builtin_amdgcn_mfma_f32_16x16x32_bf16(Bt[n][k], At[m][k], acc[ai][bj][m][n], 0, 0, 0); __builtin_amdgcn_s_setprio(0); } while (0)
; #define PG8_WAIT_V(n) asm volatile("s_waitcnt vmcnt(" #n ")" ::: "memory")
; #define PG8_WAIT_L(n) asm volatile("s_waitcnt lgkmcnt(" #n ")" ::: "memory")
; #define PG8_BAR __builtin_amdgcn_s_barrier()
; #define PG8_SCHED __builtin_amdgcn_sched_barrier(0)
; template <class Epi, int PARTS>
; __device__ __forceinline__ void gemm_phase(LAS unsigned char* lds, const Gemm g, const StaticOrder& S, const Epi& E) {
;     ...
;             PG8_LDB(B0, 1, 0); PG8_LDB(B1, 1, 1); PG8_SCHED; PG8_LDA(At, 1, 0); PG8_STAGEA(PG8_SA(0, 1), a2 + hstepA, voffA);
;             PG8_WAIT_V(8); PG8_WAIT_L(0); PG8_BAR; PG8_MMA(0, 0, At, B0); PG8_MMA(0, 1, At, B1); PG8_BAR; PG8_SCHED;
	s_add_i32 s34, 0, 0x18000
	s_add_i32 s35, 0, 0x1c000
	v_add_u32_e32 v152, s34, v141
	v_add_u32_e32 v168, s35, v141
	ds_read_b128 v[136:139], v152
	ds_read_b128 v[144:147], v152 offset:1024
	ds_read_b128 v[148:151], v152 offset:2048
	ds_read_b128 v[152:155], v152 offset:3072
	ds_read_b128 v[156:159], v168
	ds_read_b128 v[160:163], v168 offset:1024
	ds_read_b128 v[164:167], v168 offset:2048
	ds_read_b128 v[168:171], v168 offset:3072
	s_add_u32 s62, s62, 0x40000
	s_addc_u32 s63, s63, 0
	s_mov_b32 m0, s74
	v_lshl_add_u64 v[228:229], s[62:63], 0, v[0:1]
	ds_read_b128 v[172:175], v143 offset:32768
	ds_read_b128 v[176:179], v143 offset:33792
	ds_read_b128 v[180:183], v143 offset:34816
	ds_read_b128 v[184:187], v143 offset:35840
	ds_read_b128 v[196:199], v143 offset:36864
	ds_read_b128 v[200:203], v143 offset:37888
	ds_read_b128 v[204:207], v143 offset:38912
	ds_read_b128 v[208:211], v143 offset:39936
	global_load_lds_dwordx4 v[228:229], off
	v_lshl_add_u64 v[228:229], s[62:63], 0, v[130:131]
	s_mov_b32 m0, s75
	s_nop 0
	global_load_lds_dwordx4 v[228:229], off
	s_waitcnt vmcnt(8)
	s_waitcnt lgkmcnt(0)
	s_barrier
	s_waitcnt lgkmcnt(0)
	v_mfma_f32_16x16x32_bf16 v[126:129], v[136:139], v[172:175], v[126:129]
	v_mfma_f32_16x16x32_bf16 v[122:125], v[148:151], v[172:175], v[122:125]
	v_mfma_f32_16x16x32_bf16 v[110:113], v[136:139], v[180:183], v[110:113]
	v_mfma_f32_16x16x32_bf16 v[106:109], v[148:151], v[180:183], v[106:109]
	v_mfma_f32_16x16x32_bf16 v[94:97], v[136:139], v[196:199], v[94:97]
	v_mfma_f32_16x16x32_bf16 v[90:93], v[148:151], v[196:199], v[90:93]
	v_mfma_f32_16x16x32_bf16 v[78:81], v[136:139], v[204:207], v[78:81]
	v_mfma_f32_16x16x32_bf16 v[74:77], v[148:151], v[204:207], v[74:77]
	v_mfma_f32_16x16x32_bf16 v[126:129], v[144:147], v[176:179], v[126:129]
	v_mfma_f32_16x16x32_bf16 v[122:125], v[152:155], v[176:179], v[122:125]
	v_mfma_f32_16x16x32_bf16 v[110:113], v[144:147], v[184:187], v[110:113]
	v_mfma_f32_16x16x32_bf16 v[106:109], v[152:155], v[184:187], v[106:109]
	v_mfma_f32_16x16x32_bf16 v[94:97], v[144:147], v[200:203], v[94:97]
	v_mfma_f32_16x16x32_bf16 v[90:93], v[152:155], v[200:203], v[90:93]
	v_mfma_f32_16x16x32_bf16 v[78:81], v[144:147], v[208:211], v[78:81]
	v_mfma_f32_16x16x32_bf16 v[74:77], v[152:155], v[208:211], v[74:77]
	v_mfma_f32_16x16x32_bf16 v[118:121], v[156:159], v[172:175], v[118:121]
	v_mfma_f32_16x16x32_bf16 v[114:117], v[164:167], v[172:175], v[114:117]
	v_mfma_f32_16x16x32_bf16 v[102:105], v[156:159], v[180:183], v[102:105]
	v_mfma_f32_16x16x32_bf16 v[98:101], v[164:167], v[180:183], v[98:101]
	v_mfma_f32_16x16x32_bf16 v[86:89], v[156:159], v[196:199], v[86:89]
	v_mfma_f32_16x16x32_bf16 v[82:85], v[164:167], v[196:199], v[82:85]
	v_mfma_f32_16x16x32_bf16 v[70:73], v[156:159], v[204:207], v[70:73]
	v_mfma_f32_16x16x32_bf16 v[66:69], v[164:167], v[204:207], v[66:69]
	v_mfma_f32_16x16x32_bf16 v[118:121], v[160:163], v[176:179], v[118:121]
	v_mfma_f32_16x16x32_bf16 v[114:117], v[168:171], v[176:179], v[114:117]
	v_mfma_f32_16x16x32_bf16 v[102:105], v[160:163], v[184:187], v[102:105]
	v_mfma_f32_16x16x32_bf16 v[98:101], v[168:171], v[184:187], v[98:101]
	v_mfma_f32_16x16x32_bf16 v[86:89], v[160:163], v[200:203], v[86:89]
	v_mfma_f32_16x16x32_bf16 v[82:85], v[168:171], v[200:203], v[82:85]
	v_mfma_f32_16x16x32_bf16 v[70:73], v[160:163], v[208:211], v[70:73]
	v_mfma_f32_16x16x32_bf16 v[66:69], v[168:171], v[208:211], v[66:69]
	s_barrier
; #define PG8_STAGE(bufoff, gbase, voff) do { _Pragma("unroll") for (int _i = 0; _i < 2; ++_i) \
;         __builtin_amdgcn_global_load_lds((const unsigned*)((const char*)(gbase) + (voff)[_i]), (LAS unsigned*)(lds + (bufoff) + ldsw + _i * 8192), 16, 0, 0); } while (0)
; #define PG8_STAGEA(bufoff, gbase, voff) do { _Pragma("unroll") for (int _i = 0; _i < 2; ++_i) \
;         __builtin_amdgcn_global_load_lds((const unsigned*)((const char*)(gbase) + (voff)[_i]), (LAS unsigned*)(lds + (bufoff) + ldsw + _i * 8192), 16, 0, 0); } while (0)
; #define PG8_LDA(dst, b, h) do { _Pragma("unroll") for (int m = 0; m < 4; ++m) _Pragma("unroll") for (int k = 0; k < 2; ++k) dst[m][k] = *(const LAS bf16x8*)(lds + PG8_SA(b, h) + aoff + m * 2048 + k * 1024); } while (0)
; #define PG8_MMA(ai, bj, At, Bt) do { __builtin_amdgcn_s_setprio(3); _Pragma("unroll") for (int m = 0; m < 4; ++m) _Pragma("unroll") for (int n = 0; n < 2; ++n) _Pragma("unroll") for (int k = 0; k < 2; ++k) \
;         acc[ai][bj][m][n] = __builtin_amdgcn_mfma_f32_16x16x32_bf16(Bt[n][k], At[m][k], acc[ai][bj][m][n], 0, 0, 0); __builtin_amdgcn_s_setprio(0); } while (0)
; #define PG8_WAIT_V(n) asm volatile("s_waitcnt vmcnt(" #n ")" ::: "memory")
; #define PG8_WAIT_L(n) asm volatile("s_waitcnt lgkmcnt(" #n ")" ::: "memory")
; #define PG8_BAR __builtin_amdgcn_s_barrier()
; #define PG8_SCHED __builtin_amdgcn_sched_barrier(0)
; template <class Epi, int PARTS>
; __device__ __forceinline__ void gemm_phase(LAS unsigned char* lds, const Gemm g, const StaticOrder& S, const Epi& E) {
;     ...
;             PG8_LDA(At, 1, 1); PG8_STAGE(PG8_SB(1, 0), b3, voffB); PG8_STAGE(PG8_SB(1, 1), b3 + hstepB, voffB); PG8_STAGEA(PG8_SA(1, 0), a3, voffA);
;             PG8_WAIT_V(8); PG8_WAIT_L(0); PG8_BAR; PG8_MMA(1, 0, At, B0); PG8_MMA(1, 1, At, B1); PG8_BAR; PG8_SCHED;
;         }
	s_add_i32 s34, s34, s66
	v_lshl_add_u64 v[188:189], v[188:189], 0, s[72:73]
	s_mov_b32 m0, s34
	ds_read_b128 v[172:175], v143 offset:49152
	ds_read_b128 v[176:179], v143 offset:50176
	ds_read_b128 v[180:183], v143 offset:51200
	ds_read_b128 v[184:187], v143 offset:52224
	ds_read_b128 v[196:199], v143 offset:53248
	ds_read_b128 v[200:203], v143 offset:54272
	ds_read_b128 v[204:207], v143 offset:55296
	ds_read_b128 v[208:211], v143 offset:56320
	global_load_lds_dwordx4 v[188:189], off
	s_add_i32 m0, s34, 0x2000
	s_add_u32 s60, s60, 0x40080
	v_lshl_add_u64 v[188:189], v[212:213], 0, s[72:73]
	s_addc_u32 s61, s61, 0
	s_add_i32 s34, s35, s66
	global_load_lds_dwordx4 v[188:189], off
	v_lshl_add_u64 v[188:189], s[60:61], 0, v[0:1]
	s_mov_b32 m0, s34
	s_nop 0
	global_load_lds_dwordx4 v[188:189], off
	v_lshl_add_u64 v[188:189], s[60:61], 0, v[130:131]
	s_add_i32 m0, s34, 0x2000
	s_nop 0
	global_load_lds_dwordx4 v[188:189], off
	v_lshl_add_u64 v[188:189], v[214:215], 0, s[72:73]
	s_mov_b32 m0, s33
	s_nop 0
	global_load_lds_dwordx4 v[188:189], off
	v_lshl_add_u64 v[188:189], v[224:225], 0, s[72:73]
	s_mov_b32 m0, s36
	s_nop 0
	global_load_lds_dwordx4 v[188:189], off
	s_waitcnt vmcnt(8)
	s_waitcnt lgkmcnt(0)
	s_barrier
	s_waitcnt lgkmcnt(0)
	v_mfma_f32_16x16x32_bf16 v[62:65], v[136:139], v[172:175], v[62:65]
	v_mfma_f32_16x16x32_bf16 v[58:61], v[148:151], v[172:175], v[58:61]
	v_mfma_f32_16x16x32_bf16 v[46:49], v[136:139], v[180:183], v[46:49]
	v_mfma_f32_16x16x32_bf16 v[42:45], v[148:151], v[180:183], v[42:45]
	v_mfma_f32_16x16x32_bf16 v[30:33], v[136:139], v[196:199], v[30:33]
	v_mfma_f32_16x16x32_bf16 v[26:29], v[148:151], v[196:199], v[26:29]
	v_mfma_f32_16x16x32_bf16 v[14:17], v[136:139], v[204:207], v[14:17]
	v_mfma_f32_16x16x32_bf16 v[10:13], v[148:151], v[204:207], v[10:13]
	v_mfma_f32_16x16x32_bf16 v[62:65], v[144:147], v[176:179], v[62:65]
	v_mfma_f32_16x16x32_bf16 v[58:61], v[152:155], v[176:179], v[58:61]
	v_mfma_f32_16x16x32_bf16 v[46:49], v[144:147], v[184:187], v[46:49]
	v_mfma_f32_16x16x32_bf16 v[42:45], v[152:155], v[184:187], v[42:45]
	v_mfma_f32_16x16x32_bf16 v[30:33], v[144:147], v[200:203], v[30:33]
	v_mfma_f32_16x16x32_bf16 v[26:29], v[152:155], v[200:203], v[26:29]
	v_mfma_f32_16x16x32_bf16 v[14:17], v[144:147], v[208:211], v[14:17]
	v_mfma_f32_16x16x32_bf16 v[10:13], v[152:155], v[208:211], v[10:13]
	v_mfma_f32_16x16x32_bf16 v[54:57], v[156:159], v[172:175], v[54:57]
	v_mfma_f32_16x16x32_bf16 v[50:53], v[164:167], v[172:175], v[50:53]
	v_mfma_f32_16x16x32_bf16 v[38:41], v[156:159], v[180:183], v[38:41]
	v_mfma_f32_16x16x32_bf16 v[34:37], v[164:167], v[180:183], v[34:37]
	v_mfma_f32_16x16x32_bf16 v[22:25], v[156:159], v[196:199], v[22:25]
	v_mfma_f32_16x16x32_bf16 v[18:21], v[164:167], v[196:199], v[18:21]
	v_mfma_f32_16x16x32_bf16 v[6:9], v[156:159], v[204:207], v[6:9]
	v_mfma_f32_16x16x32_bf16 v[2:5], v[164:167], v[204:207], v[2:5]
	v_mfma_f32_16x16x32_bf16 v[54:57], v[160:163], v[176:179], v[54:57]
	v_mfma_f32_16x16x32_bf16 v[50:53], v[168:171], v[176:179], v[50:53]
	v_mfma_f32_16x16x32_bf16 v[38:41], v[160:163], v[184:187], v[38:41]
	v_mfma_f32_16x16x32_bf16 v[34:37], v[168:171], v[184:187], v[34:37]
	v_mfma_f32_16x16x32_bf16 v[22:25], v[160:163], v[200:203], v[22:25]
	v_mfma_f32_16x16x32_bf16 v[18:21], v[168:171], v[200:203], v[18:21]
	v_mfma_f32_16x16x32_bf16 v[6:9], v[160:163], v[208:211], v[6:9]
	v_mfma_f32_16x16x32_bf16 v[2:5], v[168:171], v[208:211], v[2:5]
	s_barrier
	s_add_i32 s82, s82, 2
	s_add_u32 s58, s58, 0x100
	s_addc_u32 s59, s59, 0
	s_add_u32 s80, s80, 0x100
	s_addc_u32 s81, s81, 0
	s_cmp_gt_u32 s82, 13
	s_cbranch_scc0 .LBB0_169
	s_setprio 0
	s_and_b64 vcc, exec, s[46:47]
	s_cbranch_vccz .LBB0_172
	s_barrier

; #define PG8_STAGE(bufoff, gbase, voff) do { _Pragma("unroll") for (int _i = 0; _i < 2; ++_i) \
;         __builtin_amdgcn_global_load_lds((const unsigned*)((const char*)(gbase) + (voff)[_i]), (LAS unsigned*)(lds + (bufoff) + ldsw + _i * 8192), 16, 0, 0); } while (0)
; #define PG8_STAGEA(bufoff, gbase, voff) do { _Pragma("unroll") for (int _i = 0; _i < 2; ++_i) \
;         __builtin_amdgcn_global_load_lds((const unsigned*)((const char*)(gbase) + (voff)[_i]), (LAS unsigned*)(lds + (bufoff) + ldsw + _i * 8192), 16, 0, 0); } while (0)
; #define PG8_LDA(dst, b, h) do { _Pragma("unroll") for (int m = 0; m < 4; ++m) _Pragma("unroll") for (int k = 0; k < 2; ++k) dst[m][k] = *(const LAS bf16x8*)(lds + PG8_SA(b, h) + aoff + m * 2048 + k * 1024); } while (0)
; #define PG8_LDB(dst, b, h) do { _Pragma("unroll") for (int n = 0; n < 2; ++n) _Pragma("unroll") for (int k = 0; k < 2; ++k) dst[n][k] = *(const LAS bf16x8*)(lds + PG8_SB(b, h) + boff + n * 2048 + k * 1024); } while (0)
; #define PG8_WAIT_V(n) asm volatile("s_waitcnt vmcnt(" #n ")" ::: "memory")
; #define PG8_WAIT_L(n) asm volatile("s_waitcnt lgkmcnt(" #n ")" ::: "memory")
; #define PG8_BAR __builtin_amdgcn_s_barrier()
; template <class Epi, int PARTS>
; __device__ __forceinline__ void gemm_phase(LAS unsigned char* lds, const Gemm g, const StaticOrder& S, const Epi& E) {
;     ...
;         const bool has_next = S.next(ui + 1, nxt);
;         const char* nA = has_next ? PG8_UA(nxt) : cA; const char* nB = has_next ? PG8_UB(nxt) : cB;
;         for (int t = 0; t < nt; t += 2) {
;             const bool last = (t == nt - 2);
;             const char* a1 = cA + (size_t)(t + 1) * kstep;
;             const char* a2 = last ? nA : cA + (size_t)(t + 2) * kstep; const char* b2 = last ? nB : cB + (size_t)(t + 2) * kstep;
;             const char* a3 = a2 + kstep; const char* b3 = b2 + kstep;
;             PG8_LDB(B0, 0, 0); PG8_LDB(B1, 0, 1); PG8_SCHED; PG8_LDA(At, 0, 0); PG8_STAGEA(PG8_SA(1, 1), a1 + hstepA, voffA);
;             PG8_WAIT_V(8); PG8_WAIT_L(0); PG8_BAR; PG8_MMA(0, 0, At, B0); PG8_MMA(0, 1, At, B1); PG8_BAR; PG8_SCHED;
;             PG8_LDA(At, 0, 1); PG8_STAGE(PG8_SB(0, 0), b2, voffB); PG8_STAGE(PG8_SB(0, 1), b2 + hstepB, voffB); PG8_STAGEA(PG8_SA(0, 0), a2, voffA);
;             PG8_WAIT_V(8); PG8_WAIT_L(0); PG8_BAR; PG8_MMA(1, 0, At, B0); PG8_MMA(1, 1, At, B1); PG8_BAR; PG8_SCHED;
.LBB0_205:
	s_add_u32 s56, s56, 0x40080
	s_addc_u32 s57, s57, 0
	s_add_u32 s51, s58, 0x100
	s_addc_u32 s53, s59, 0
	s_mov_b32 s75, -2
	v_readfirstlane_b32 s99, v216
	s_cmp_lt_u32 s99, 0x100
	s_cbranch_scc1 .Lgprio2
	s_setprio 1
.Lgprio2:
.LBB0_206:
	s_add_u32 s34, s56, 0xfffc0080
	s_addc_u32 s35, s57, -1
	s_add_i32 s76, 0, 0x10000
	s_cmp_eq_u32 s75, 4
	s_cselect_b32 s61, s1, s35
	s_cselect_b32 s60, s0, s34
	v_add_u32_e32 v0, s76, v180
	s_cselect_b32 s59, s55, s53
	s_cselect_b32 s58, s54, s51
	s_add_i32 s34, 0, 0x14000
	ds_read_b128 v[44:47], v0
	ds_read_b128 v[48:51], v0 offset:1024
	ds_read_b128 v[84:87], v0 offset:2048
	ds_read_b128 v[88:91], v0 offset:3072
	v_add_u32_e32 v0, s34, v180
	ds_read_b128 v[116:119], v0
	ds_read_b128 v[120:123], v0 offset:1024
	ds_read_b128 v[140:143], v0 offset:2048
	ds_read_b128 v[144:147], v0 offset:3072
	v_lshl_add_u64 v[2:3], s[56:57], 0, v[174:175]
	s_add_i32 m0, s37, 0xc000
	ds_read_b128 v[182:185], v181
	ds_read_b128 v[186:189], v181 offset:1024
	ds_read_b128 v[196:199], v181 offset:2048
	ds_read_b128 v[200:203], v181 offset:3072
	ds_read_b128 v[204:207], v181 offset:4096
	ds_read_b128 v[208:211], v181 offset:5120
	ds_read_b128 v[212:215], v181 offset:6144
	ds_read_b128 v[236:239], v181 offset:7168
	global_load_lds_dwordx4 v[2:3], off
	v_lshl_add_u64 v[2:3], s[56:57], 0, v[176:177]
	s_add_i32 m0, s37, 0xe000
	s_nop 0
	global_load_lds_dwordx4 v[2:3], off
	s_waitcnt vmcnt(8)
	s_waitcnt lgkmcnt(0)
	s_barrier
	s_waitcnt lgkmcnt(0)
	v_mfma_f32_16x16x32_bf16 v[72:75], v[44:47], v[182:185], v[72:75]
	v_mfma_f32_16x16x32_bf16 v[68:71], v[84:87], v[182:185], v[68:71]
	v_mfma_f32_16x16x32_bf16 v[104:107], v[44:47], v[196:199], v[104:107]
	v_mfma_f32_16x16x32_bf16 v[100:103], v[84:87], v[196:199], v[100:103]
	v_mfma_f32_16x16x32_bf16 v[136:139], v[44:47], v[204:207], v[136:139]
	v_mfma_f32_16x16x32_bf16 v[132:135], v[84:87], v[204:207], v[132:135]
	v_mfma_f32_16x16x32_bf16 v[112:115], v[44:47], v[212:215], v[112:115]
	v_mfma_f32_16x16x32_bf16 v[108:111], v[84:87], v[212:215], v[108:111]
	v_mfma_f32_16x16x32_bf16 v[72:75], v[48:51], v[186:189], v[72:75]
	v_mfma_f32_16x16x32_bf16 v[68:71], v[88:91], v[186:189], v[68:71]
	v_mfma_f32_16x16x32_bf16 v[104:107], v[48:51], v[200:203], v[104:107]
	v_mfma_f32_16x16x32_bf16 v[100:103], v[88:91], v[200:203], v[100:103]
	v_mfma_f32_16x16x32_bf16 v[136:139], v[48:51], v[208:211], v[136:139]
	v_mfma_f32_16x16x32_bf16 v[132:135], v[88:91], v[208:211], v[132:135]
	v_mfma_f32_16x16x32_bf16 v[112:115], v[48:51], v[236:239], v[112:115]
	v_mfma_f32_16x16x32_bf16 v[108:111], v[88:91], v[236:239], v[108:111]
	v_mfma_f32_16x16x32_bf16 v[160:163], v[116:119], v[182:185], v[160:163]
	v_mfma_f32_16x16x32_bf16 v[156:159], v[140:143], v[182:185], v[156:159]
	v_mfma_f32_16x16x32_bf16 v[152:155], v[116:119], v[196:199], v[152:155]
	v_mfma_f32_16x16x32_bf16 v[148:151], v[140:143], v[196:199], v[148:151]
	v_mfma_f32_16x16x32_bf16 v[128:131], v[116:119], v[204:207], v[128:131]
	v_mfma_f32_16x16x32_bf16 v[124:127], v[140:143], v[204:207], v[124:127]
	v_mfma_f32_16x16x32_bf16 v[96:99], v[116:119], v[212:215], v[96:99]
	v_mfma_f32_16x16x32_bf16 v[92:95], v[140:143], v[212:215], v[92:95]
	v_mfma_f32_16x16x32_bf16 v[160:163], v[120:123], v[186:189], v[160:163]
	v_mfma_f32_16x16x32_bf16 v[156:159], v[144:147], v[186:189], v[156:159]
	v_mfma_f32_16x16x32_bf16 v[152:155], v[120:123], v[200:203], v[152:155]
	v_mfma_f32_16x16x32_bf16 v[148:151], v[144:147], v[200:203], v[148:151]
	v_mfma_f32_16x16x32_bf16 v[128:131], v[120:123], v[208:211], v[128:131]
	v_mfma_f32_16x16x32_bf16 v[124:127], v[144:147], v[208:211], v[124:127]
	v_mfma_f32_16x16x32_bf16 v[96:99], v[120:123], v[236:239], v[96:99]
	v_mfma_f32_16x16x32_bf16 v[92:95], v[144:147], v[236:239], v[92:95]
	s_barrier
	s_add_i32 s35, s76, s36
	v_lshl_add_u64 v[178:179], s[58:59], 0, v[168:169]
	s_mov_b32 m0, s35
	ds_read_b128 v[182:185], v181 offset:16384
	ds_read_b128 v[186:189], v181 offset:17408
	ds_read_b128 v[196:199], v181 offset:18432
	ds_read_b128 v[200:203], v181 offset:19456
	ds_read_b128 v[204:207], v181 offset:20480
	ds_read_b128 v[208:211], v181 offset:21504
	ds_read_b128 v[212:215], v181 offset:22528
	ds_read_b128 v[236:239], v181 offset:23552
	global_load_lds_dwordx4 v[178:179], off
	s_add_i32 m0, s35, 0x2000
	s_add_u32 s76, s58, 0x20000
	v_lshl_add_u64 v[224:225], s[58:59], 0, v[164:165]
	s_addc_u32 s77, s59, 0
	s_add_i32 s34, s34, s36
	global_load_lds_dwordx4 v[224:225], off
	v_lshl_add_u64 v[2:3], s[76:77], 0, v[168:169]
	s_mov_b32 m0, s34
	v_lshl_add_u64 v[228:229], s[60:61], 0, v[170:171]
	global_load_lds_dwordx4 v[2:3], off
	v_lshl_add_u64 v[2:3], s[76:77], 0, v[164:165]
	s_add_i32 m0, s34, 0x2000
	v_lshl_add_u64 v[230:231], s[60:61], 0, v[166:167]
	global_load_lds_dwordx4 v[2:3], off
	s_mov_b32 m0, s37
	s_nop 0
	global_load_lds_dwordx4 v[228:229], off
	s_mov_b32 m0, s62
	s_nop 0
	global_load_lds_dwordx4 v[230:231], off
	s_waitcnt vmcnt(8)
	s_waitcnt lgkmcnt(0)
	s_barrier
; #define PG8_STAGEA(bufoff, gbase, voff) do { _Pragma("unroll") for (int _i = 0; _i < 2; ++_i) \
;         __builtin_amdgcn_global_load_lds((const unsigned*)((const char*)(gbase) + (voff)[_i]), (LAS unsigned*)(lds + (bufoff) + ldsw + _i * 8192), 16, 0, 0); } while (0)
; #define PG8_LDA(dst, b, h) do { _Pragma("unroll") for (int m = 0; m < 4; ++m) _Pragma("unroll") for (int k = 0; k < 2; ++k) dst[m][k] = *(const LAS bf16x8*)(lds + PG8_SA(b, h) + aoff + m * 2048 + k * 1024); } while (0)
; #define PG8_LDB(dst, b, h) do { _Pragma("unroll") for (int n = 0; n < 2; ++n) _Pragma("unroll") for (int k = 0; k < 2; ++k) dst[n][k] = *(const LAS bf16x8*)(lds + PG8_SB(b, h) + boff + n * 2048 + k * 1024); } while (0)
; #define PG8_MMA(ai, bj, At, Bt) do { __builtin_amdgcn_s_setprio(3); _Pragma("unroll") for (int m = 0; m < 4; ++m) _Pragma("unroll") for (int n = 0; n < 2; ++n) _Pragma("unroll") for (int k = 0; k < 2; ++k) \
;         acc[ai][bj][m][n] = __builtin_amdgcn_mfma_f32_16x16x32_bf16(Bt[n][k], At[m][k], acc[ai][bj][m][n], 0, 0, 0); __builtin_amdgcn_s_setprio(0); } while (0)
; #define PG8_WAIT_V(n) asm volatile("s_waitcnt vmcnt(" #n ")" ::: "memory")
; #define PG8_WAIT_L(n) asm volatile("s_waitcnt lgkmcnt(" #n ")" ::: "memory")
; #define PG8_BAR __builtin_amdgcn_s_barrier()
; #define PG8_SCHED __builtin_amdgcn_sched_barrier(0)
; template <class Epi, int PARTS>
; __device__ __forceinline__ void gemm_phase(LAS unsigned char* lds, const Gemm g, const StaticOrder& S, const Epi& E) {
;     ...
;             PG8_WAIT_V(8); PG8_WAIT_L(0); PG8_BAR; PG8_MMA(1, 0, At, B0); PG8_MMA(1, 1, At, B1); PG8_BAR; PG8_SCHED;
;             PG8_LDB(B0, 1, 0); PG8_LDB(B1, 1, 1); PG8_SCHED; PG8_LDA(At, 1, 0); PG8_STAGEA(PG8_SA(0, 1), a2 + hstepA, voffA);
;             PG8_WAIT_V(8); PG8_WAIT_L(0); PG8_BAR; PG8_MMA(0, 0, At, B0); PG8_MMA(0, 1, At, B1); PG8_BAR; PG8_SCHED;
	s_waitcnt lgkmcnt(0)
	v_mfma_f32_16x16x32_bf16 v[80:83], v[44:47], v[182:185], v[80:83]
	v_mfma_f32_16x16x32_bf16 v[76:79], v[84:87], v[182:185], v[76:79]
	v_mfma_f32_16x16x32_bf16 v[56:59], v[44:47], v[196:199], v[56:59]
	v_mfma_f32_16x16x32_bf16 v[52:55], v[84:87], v[196:199], v[52:55]
	v_mfma_f32_16x16x32_bf16 v[32:35], v[44:47], v[204:207], v[32:35]
	v_mfma_f32_16x16x32_bf16 v[28:31], v[84:87], v[204:207], v[28:31]
	v_mfma_f32_16x16x32_bf16 v[16:19], v[44:47], v[212:215], v[16:19]
	v_mfma_f32_16x16x32_bf16 v[12:15], v[84:87], v[212:215], v[12:15]
	v_mfma_f32_16x16x32_bf16 v[80:83], v[48:51], v[186:189], v[80:83]
	v_mfma_f32_16x16x32_bf16 v[76:79], v[88:91], v[186:189], v[76:79]
	v_mfma_f32_16x16x32_bf16 v[56:59], v[48:51], v[200:203], v[56:59]
	v_mfma_f32_16x16x32_bf16 v[52:55], v[88:91], v[200:203], v[52:55]
	v_mfma_f32_16x16x32_bf16 v[32:35], v[48:51], v[208:211], v[32:35]
	v_mfma_f32_16x16x32_bf16 v[28:31], v[88:91], v[208:211], v[28:31]
	v_mfma_f32_16x16x32_bf16 v[16:19], v[48:51], v[236:239], v[16:19]
	v_mfma_f32_16x16x32_bf16 v[12:15], v[88:91], v[236:239], v[12:15]
	v_mfma_f32_16x16x32_bf16 v[40:43], v[116:119], v[196:199], v[40:43]
	v_mfma_f32_16x16x32_bf16 v[36:39], v[140:143], v[196:199], v[36:39]
	v_mfma_f32_16x16x32_bf16 v[24:27], v[116:119], v[204:207], v[24:27]
	v_mfma_f32_16x16x32_bf16 v[20:23], v[140:143], v[204:207], v[20:23]
	v_mfma_f32_16x16x32_bf16 v[8:11], v[116:119], v[212:215], v[8:11]
	v_mfma_f32_16x16x32_bf16 v[2:5], v[140:143], v[212:215], v[4:7]
	v_mfma_f32_16x16x32_bf16 v[44:47], v[116:119], v[182:185], v[64:67]
	v_mfma_f32_16x16x32_bf16 v[48:51], v[140:143], v[182:185], v[60:63]
	v_mfma_f32_16x16x32_bf16 v[40:43], v[120:123], v[200:203], v[40:43]
	v_mfma_f32_16x16x32_bf16 v[36:39], v[144:147], v[200:203], v[36:39]
	v_mfma_f32_16x16x32_bf16 v[24:27], v[120:123], v[208:211], v[24:27]
	v_mfma_f32_16x16x32_bf16 v[20:23], v[144:147], v[208:211], v[20:23]
	v_mfma_f32_16x16x32_bf16 v[8:11], v[120:123], v[236:239], v[8:11]
	v_mfma_f32_16x16x32_bf16 v[2:5], v[144:147], v[236:239], v[2:5]
	v_mfma_f32_16x16x32_bf16 v[44:47], v[120:123], v[186:189], v[44:47]
	v_mfma_f32_16x16x32_bf16 v[48:51], v[144:147], v[186:189], v[48:51]
	s_barrier
	s_add_i32 s34, 0, 0x18000
	v_add_u32_e32 v0, s34, v180
	s_add_i32 s35, 0, 0x1c000
	ds_read_b128 v[60:63], v0
	ds_read_b128 v[64:67], v0 offset:1024
	ds_read_b128 v[84:87], v0 offset:2048
	ds_read_b128 v[88:91], v0 offset:3072
	v_add_u32_e32 v0, s35, v180
	ds_read_b128 v[116:119], v0
	ds_read_b128 v[120:123], v0 offset:1024
	ds_read_b128 v[140:143], v0 offset:2048
	ds_read_b128 v[144:147], v0 offset:3072
	s_add_u32 s60, s60, 0x40000
	s_addc_u32 s61, s61, 0
	s_mov_b32 m0, s63
	v_lshl_add_u64 v[6:7], s[60:61], 0, v[170:171]
	ds_read_b128 v[182:185], v181 offset:32768
	ds_read_b128 v[186:189], v181 offset:33792
	ds_read_b128 v[196:199], v181 offset:34816
	ds_read_b128 v[200:203], v181 offset:35840
	ds_read_b128 v[204:207], v181 offset:36864
	ds_read_b128 v[208:211], v181 offset:37888
	ds_read_b128 v[212:215], v181 offset:38912
	ds_read_b128 v[236:239], v181 offset:39936
	global_load_lds_dwordx4 v[6:7], off
	v_lshl_add_u64 v[6:7], s[60:61], 0, v[166:167]
	s_mov_b32 m0, s64
	s_nop 0
	global_load_lds_dwordx4 v[6:7], off
	s_waitcnt vmcnt(8)
	s_waitcnt lgkmcnt(0)
	s_barrier
	s_waitcnt lgkmcnt(0)
	v_mfma_f32_16x16x32_bf16 v[72:75], v[60:63], v[182:185], v[72:75]
	v_mfma_f32_16x16x32_bf16 v[68:71], v[84:87], v[182:185], v[68:71]
	v_mfma_f32_16x16x32_bf16 v[104:107], v[60:63], v[196:199], v[104:107]
	v_mfma_f32_16x16x32_bf16 v[100:103], v[84:87], v[196:199], v[100:103]
	v_mfma_f32_16x16x32_bf16 v[136:139], v[60:63], v[204:207], v[136:139]
	v_mfma_f32_16x16x32_bf16 v[132:135], v[84:87], v[204:207], v[132:135]
	v_mfma_f32_16x16x32_bf16 v[112:115], v[60:63], v[212:215], v[112:115]
	v_mfma_f32_16x16x32_bf16 v[108:111], v[84:87], v[212:215], v[108:111]
	v_mfma_f32_16x16x32_bf16 v[72:75], v[64:67], v[186:189], v[72:75]
	v_mfma_f32_16x16x32_bf16 v[68:71], v[88:91], v[186:189], v[68:71]
	v_mfma_f32_16x16x32_bf16 v[104:107], v[64:67], v[200:203], v[104:107]
	v_mfma_f32_16x16x32_bf16 v[100:103], v[88:91], v[200:203], v[100:103]
	v_mfma_f32_16x16x32_bf16 v[136:139], v[64:67], v[208:211], v[136:139]
	v_mfma_f32_16x16x32_bf16 v[132:135], v[88:91], v[208:211], v[132:135]
	v_mfma_f32_16x16x32_bf16 v[112:115], v[64:67], v[236:239], v[112:115]
	v_mfma_f32_16x16x32_bf16 v[108:111], v[88:91], v[236:239], v[108:111]
	v_mfma_f32_16x16x32_bf16 v[160:163], v[116:119], v[182:185], v[160:163]
	v_mfma_f32_16x16x32_bf16 v[156:159], v[140:143], v[182:185], v[156:159]
	v_mfma_f32_16x16x32_bf16 v[152:155], v[116:119], v[196:199], v[152:155]
	v_mfma_f32_16x16x32_bf16 v[148:151], v[140:143], v[196:199], v[148:151]
	v_mfma_f32_16x16x32_bf16 v[128:131], v[116:119], v[204:207], v[128:131]
	v_mfma_f32_16x16x32_bf16 v[124:127], v[140:143], v[204:207], v[124:127]
	v_mfma_f32_16x16x32_bf16 v[96:99], v[116:119], v[212:215], v[96:99]
	v_mfma_f32_16x16x32_bf16 v[92:95], v[140:143], v[212:215], v[92:95]
	v_mfma_f32_16x16x32_bf16 v[160:163], v[120:123], v[186:189], v[160:163]
	v_mfma_f32_16x16x32_bf16 v[156:159], v[144:147], v[186:189], v[156:159]
	v_mfma_f32_16x16x32_bf16 v[152:155], v[120:123], v[200:203], v[152:155]
	v_mfma_f32_16x16x32_bf16 v[148:151], v[144:147], v[200:203], v[148:151]
	v_mfma_f32_16x16x32_bf16 v[128:131], v[120:123], v[208:211], v[128:131]
	v_mfma_f32_16x16x32_bf16 v[124:127], v[144:147], v[208:211], v[124:127]
	v_mfma_f32_16x16x32_bf16 v[96:99], v[120:123], v[236:239], v[96:99]
	v_mfma_f32_16x16x32_bf16 v[92:95], v[144:147], v[236:239], v[92:95]
	s_barrier
; #define PG8_STAGE(bufoff, gbase, voff) do { _Pragma("unroll") for (int _i = 0; _i < 2; ++_i) \
;         __builtin_amdgcn_global_load_lds((const unsigned*)((const char*)(gbase) + (voff)[_i]), (LAS unsigned*)(lds + (bufoff) + ldsw + _i * 8192), 16, 0, 0); } while (0)
; #define PG8_STAGEA(bufoff, gbase, voff) do { _Pragma("unroll") for (int _i = 0; _i < 2; ++_i) \
;         __builtin_amdgcn_global_load_lds((const unsigned*)((const char*)(gbase) + (voff)[_i]), (LAS unsigned*)(lds + (bufoff) + ldsw + _i * 8192), 16, 0, 0); } while (0)
; #define PG8_LDA(dst, b, h) do { _Pragma("unroll") for (int m = 0; m < 4; ++m) _Pragma("unroll") for (int k = 0; k < 2; ++k) dst[m][k] = *(const LAS bf16x8*)(lds + PG8_SA(b, h) + aoff + m * 2048 + k * 1024); } while (0)
; #define PG8_MMA(ai, bj, At, Bt) do { __builtin_amdgcn_s_setprio(3); _Pragma("unroll") for (int m = 0; m < 4; ++m) _Pragma("unroll") for (int n = 0; n < 2; ++n) _Pragma("unroll") for (int k = 0; k < 2; ++k) \
;         acc[ai][bj][m][n] = __builtin_amdgcn_mfma_f32_16x16x32_bf16(Bt[n][k], At[m][k], acc[ai][bj][m][n], 0, 0, 0); __builtin_amdgcn_s_setprio(0); } while (0)
; #define PG8_WAIT_V(n) asm volatile("s_waitcnt vmcnt(" #n ")" ::: "memory")
; #define PG8_WAIT_L(n) asm volatile("s_waitcnt lgkmcnt(" #n ")" ::: "memory")
; #define PG8_BAR __builtin_amdgcn_s_barrier()
; #define PG8_SCHED __builtin_amdgcn_sched_barrier(0)
; template <class Epi, int PARTS>
; __device__ __forceinline__ void gemm_phase(LAS unsigned char* lds, const Gemm g, const StaticOrder& S, const Epi& E) {
;     ...
;             PG8_LDA(At, 1, 1); PG8_STAGE(PG8_SB(1, 0), b3, voffB); PG8_STAGE(PG8_SB(1, 1), b3 + hstepB, voffB); PG8_STAGEA(PG8_SA(1, 0), a3, voffA);
;             PG8_WAIT_V(8); PG8_WAIT_L(0); PG8_BAR; PG8_MMA(1, 0, At, B0); PG8_MMA(1, 1, At, B1); PG8_BAR; PG8_SCHED;
;         }
;         if (wr == 0) PG8_BAR;
	s_add_i32 s34, s34, s36
	v_lshl_add_u64 v[6:7], v[178:179], 0, s[72:73]
	s_mov_b32 m0, s34
	ds_read_b128 v[182:185], v181 offset:49152
	ds_read_b128 v[186:189], v181 offset:50176
	ds_read_b128 v[196:199], v181 offset:51200
	ds_read_b128 v[200:203], v181 offset:52224
	ds_read_b128 v[204:207], v181 offset:53248
	ds_read_b128 v[208:211], v181 offset:54272
	ds_read_b128 v[212:215], v181 offset:55296
	ds_read_b128 v[236:239], v181 offset:56320
	global_load_lds_dwordx4 v[6:7], off
	s_add_i32 m0, s34, 0x2000
	s_add_u32 s58, s58, 0x20080
	v_lshl_add_u64 v[6:7], v[224:225], 0, s[72:73]
	s_addc_u32 s59, s59, 0
	s_add_i32 s34, s35, s36
	global_load_lds_dwordx4 v[6:7], off
	v_lshl_add_u64 v[6:7], s[58:59], 0, v[168:169]
	s_mov_b32 m0, s34
	s_nop 0
	global_load_lds_dwordx4 v[6:7], off
	v_lshl_add_u64 v[6:7], s[58:59], 0, v[164:165]
	s_add_i32 m0, s34, 0x2000
	s_nop 0
	global_load_lds_dwordx4 v[6:7], off
	v_lshl_add_u64 v[6:7], v[228:229], 0, s[72:73]
	s_mov_b32 m0, s65
	s_nop 0
	global_load_lds_dwordx4 v[6:7], off
	v_lshl_add_u64 v[6:7], v[230:231], 0, s[72:73]
	s_mov_b32 m0, s66
	s_nop 0
	global_load_lds_dwordx4 v[6:7], off
	s_waitcnt vmcnt(8)
	s_waitcnt lgkmcnt(0)
	s_barrier
	s_waitcnt lgkmcnt(0)
	v_mfma_f32_16x16x32_bf16 v[80:83], v[60:63], v[182:185], v[80:83]
	v_mfma_f32_16x16x32_bf16 v[76:79], v[84:87], v[182:185], v[76:79]
	v_mfma_f32_16x16x32_bf16 v[56:59], v[60:63], v[196:199], v[56:59]
	v_mfma_f32_16x16x32_bf16 v[52:55], v[84:87], v[196:199], v[52:55]
	v_mfma_f32_16x16x32_bf16 v[32:35], v[60:63], v[204:207], v[32:35]
	v_mfma_f32_16x16x32_bf16 v[28:31], v[84:87], v[204:207], v[28:31]
	v_mfma_f32_16x16x32_bf16 v[16:19], v[60:63], v[212:215], v[16:19]
	v_mfma_f32_16x16x32_bf16 v[12:15], v[84:87], v[212:215], v[12:15]
	v_mfma_f32_16x16x32_bf16 v[80:83], v[64:67], v[186:189], v[80:83]
	v_mfma_f32_16x16x32_bf16 v[76:79], v[88:91], v[186:189], v[76:79]
	v_mfma_f32_16x16x32_bf16 v[56:59], v[64:67], v[200:203], v[56:59]
	v_mfma_f32_16x16x32_bf16 v[52:55], v[88:91], v[200:203], v[52:55]
	v_mfma_f32_16x16x32_bf16 v[32:35], v[64:67], v[208:211], v[32:35]
	v_mfma_f32_16x16x32_bf16 v[28:31], v[88:91], v[208:211], v[28:31]
	v_mfma_f32_16x16x32_bf16 v[16:19], v[64:67], v[236:239], v[16:19]
	v_mfma_f32_16x16x32_bf16 v[12:15], v[88:91], v[236:239], v[12:15]
	v_mfma_f32_16x16x32_bf16 v[44:47], v[116:119], v[182:185], v[44:47]
	v_mfma_f32_16x16x32_bf16 v[64:67], v[120:123], v[186:189], v[44:47]
	v_mfma_f32_16x16x32_bf16 v[44:47], v[140:143], v[182:185], v[48:51]
	v_mfma_f32_16x16x32_bf16 v[40:43], v[116:119], v[196:199], v[40:43]
	v_mfma_f32_16x16x32_bf16 v[36:39], v[140:143], v[196:199], v[36:39]
	v_mfma_f32_16x16x32_bf16 v[24:27], v[116:119], v[204:207], v[24:27]
	v_mfma_f32_16x16x32_bf16 v[20:23], v[140:143], v[204:207], v[20:23]
	v_mfma_f32_16x16x32_bf16 v[6:9], v[116:119], v[212:215], v[8:11]
	v_mfma_f32_16x16x32_bf16 v[2:5], v[140:143], v[212:215], v[2:5]
	v_mfma_f32_16x16x32_bf16 v[60:63], v[144:147], v[186:189], v[44:47]
	v_mfma_f32_16x16x32_bf16 v[40:43], v[120:123], v[200:203], v[40:43]
	v_mfma_f32_16x16x32_bf16 v[36:39], v[144:147], v[200:203], v[36:39]
	v_mfma_f32_16x16x32_bf16 v[24:27], v[120:123], v[208:211], v[24:27]
	v_mfma_f32_16x16x32_bf16 v[20:23], v[144:147], v[208:211], v[20:23]
	v_mfma_f32_16x16x32_bf16 v[8:11], v[120:123], v[236:239], v[6:9]
	v_mfma_f32_16x16x32_bf16 v[4:7], v[144:147], v[236:239], v[2:5]
	s_barrier
	s_add_i32 s75, s75, 2
	s_add_u32 s56, s56, 0x100
	s_addc_u32 s57, s57, 0
	s_add_u32 s51, s51, 0x100
	s_addc_u32 s53, s53, 0
	s_cmp_gt_u32 s75, 5
	s_cbranch_scc0 .LBB0_206
	s_setprio 0
	s_and_b64 vcc, exec, s[48:49]
	s_cbranch_vccz .LBB0_209
	s_barrier

; #define PG8_STAGEA(bufoff, gbase, voff) do { _Pragma("unroll") for (int _i = 0; _i < 2; ++_i) \
;         __builtin_amdgcn_global_load_lds((const unsigned*)((const char*)(gbase) + (voff)[_i]), (LAS unsigned*)(lds + (bufoff) + ldsw + _i * 8192), 16, 0, 0); } while (0)
; #define PG8_LDA(dst, b, h) do { _Pragma("unroll") for (int m = 0; m < 4; ++m) _Pragma("unroll") for (int k = 0; k < 2; ++k) dst[m][k] = *(const LAS bf16x8*)(lds + PG8_SA(b, h) + aoff + m * 2048 + k * 1024); } while (0)
; #define PG8_LDB(dst, b, h) do { _Pragma("unroll") for (int n = 0; n < 2; ++n) _Pragma("unroll") for (int k = 0; k < 2; ++k) dst[n][k] = *(const LAS bf16x8*)(lds + PG8_SB(b, h) + boff + n * 2048 + k * 1024); } while (0)
; #define PG8_SCHED __builtin_amdgcn_sched_barrier(0)
; template <class Epi, int PARTS>
; __device__ __forceinline__ void gemm_phase(LAS unsigned char* lds, const Gemm g, const StaticOrder& S, const Epi& E) {
;     ...
;         const bool has_next = S.next(ui + 1, nxt);
;         const char* nA = has_next ? PG8_UA(nxt) : cA; const char* nB = has_next ? PG8_UB(nxt) : cB;
;         for (int t = 0; t < nt; t += 2) {
;             const bool last = (t == nt - 2);
;             const char* a1 = cA + (size_t)(t + 1) * kstep;
;             const char* a2 = last ? nA : cA + (size_t)(t + 2) * kstep; const char* b2 = last ? nB : cB + (size_t)(t + 2) * kstep;
;             const char* a3 = a2 + kstep; const char* b3 = b2 + kstep;
;             PG8_LDB(B0, 0, 0); PG8_LDB(B1, 0, 1); PG8_SCHED; PG8_LDA(At, 0, 0); PG8_STAGEA(PG8_SA(1, 1), a1 + hstepA, voffA);
;     ...
; #pragma unroll
;         for (int a = 0; a < 2; ++a)
; #pragma unroll
;             for (int b = 0; b < 2; ++b)
; #pragma unroll
;                 for (int m = 0; m < 4; ++m)
; #pragma unroll
;                     for (int n = 0; n < 2; ++n) acc[a][b][m][n] = (f32x4){0.f, 0.f, 0.f, 0.f};
.LBB0_344:
	s_ashr_i32 s49, s48, 31
	s_lshl_b64 s[34:35], s[48:49], 20
	s_add_u32 s50, s70, s34
	s_addc_u32 s51, s71, s35
	s_and_b64 s[34:35], s[40:41], exec
	s_cselect_b32 s49, s51, s57
	s_cselect_b32 s55, s50, s56
	s_ashr_i32 s47, s46, 31
	s_lshl_b64 s[34:35], s[46:47], 20
	s_add_u32 s52, s62, s34
	s_addc_u32 s53, s63, s35
	s_and_b64 s[34:35], s[40:41], exec
	s_cselect_b32 s47, s53, s59
	s_cselect_b32 s75, s52, s58
	s_add_u32 s56, s56, 0x80080
	s_addc_u32 s57, s57, 0
	s_add_u32 s76, s58, 0x100
	v_mov_b32_e32 v2, 0
	s_addc_u32 s77, s59, 0
	s_mov_b32 s80, -2
	s_waitcnt lgkmcnt(0)
	v_mov_b32_e32 v3, v2
	v_mov_b32_e32 v4, v2
	v_mov_b32_e32 v5, v2
	v_mov_b32_e32 v6, v2
	v_mov_b32_e32 v7, v2
	v_mov_b32_e32 v8, v2
	v_mov_b32_e32 v9, v2
	v_mov_b32_e32 v18, v2
	v_mov_b32_e32 v19, v2
	v_mov_b32_e32 v20, v2
	v_mov_b32_e32 v21, v2
	v_mov_b32_e32 v22, v2
	v_mov_b32_e32 v23, v2
	v_mov_b32_e32 v24, v2
	v_mov_b32_e32 v25, v2
	s_waitcnt vmcnt(0)
	v_mov_b32_e32 v34, v2
	v_mov_b32_e32 v35, v2
	v_mov_b32_e32 v36, v2
	v_mov_b32_e32 v37, v2
	v_mov_b32_e32 v38, v2
	v_mov_b32_e32 v39, v2
	v_mov_b32_e32 v40, v2
	v_mov_b32_e32 v41, v2
	v_mov_b32_e32 v50, v2
	v_mov_b32_e32 v51, v2
	v_mov_b32_e32 v52, v2
	v_mov_b32_e32 v53, v2
	v_mov_b32_e32 v54, v2
	v_mov_b32_e32 v55, v2
	v_mov_b32_e32 v56, v2
	v_mov_b32_e32 v57, v2
	v_mov_b32_e32 v10, v2
	v_mov_b32_e32 v11, v2
	v_mov_b32_e32 v12, v2
	v_mov_b32_e32 v13, v2
	v_mov_b32_e32 v14, v2
	v_mov_b32_e32 v15, v2
	v_mov_b32_e32 v16, v2
	v_mov_b32_e32 v17, v2
	v_mov_b32_e32 v26, v2
	v_mov_b32_e32 v27, v2
	v_mov_b32_e32 v28, v2
	v_mov_b32_e32 v29, v2
	v_mov_b32_e32 v30, v2
	v_mov_b32_e32 v31, v2
	v_mov_b32_e32 v32, v2
	v_mov_b32_e32 v33, v2
	v_mov_b32_e32 v42, v2
	v_mov_b32_e32 v43, v2
	v_mov_b32_e32 v44, v2
	v_mov_b32_e32 v45, v2
	v_mov_b32_e32 v46, v2
	v_mov_b32_e32 v47, v2
	v_mov_b32_e32 v48, v2
	v_mov_b32_e32 v49, v2
	v_mov_b32_e32 v58, v2
	v_mov_b32_e32 v59, v2
	v_mov_b32_e32 v60, v2
	v_mov_b32_e32 v61, v2
	v_mov_b32_e32 v62, v2
	v_mov_b32_e32 v63, v2
	v_mov_b32_e32 v64, v2
	v_mov_b32_e32 v65, v2
	v_mov_b32_e32 v66, v2
	v_mov_b32_e32 v67, v2
	v_mov_b32_e32 v68, v2
	v_mov_b32_e32 v69, v2
	v_mov_b32_e32 v70, v2
	v_mov_b32_e32 v71, v2
	v_mov_b32_e32 v72, v2
	v_mov_b32_e32 v73, v2
	v_mov_b32_e32 v82, v2
	v_mov_b32_e32 v83, v2
	v_mov_b32_e32 v84, v2
	v_mov_b32_e32 v85, v2
	v_mov_b32_e32 v86, v2
	v_mov_b32_e32 v87, v2
	v_mov_b32_e32 v88, v2
	v_mov_b32_e32 v89, v2
	v_mov_b32_e32 v98, v2
	v_mov_b32_e32 v99, v2
	v_mov_b32_e32 v100, v2
	v_mov_b32_e32 v101, v2
	v_mov_b32_e32 v102, v2
	v_mov_b32_e32 v103, v2
	v_mov_b32_e32 v104, v2
	v_mov_b32_e32 v105, v2
	v_mov_b32_e32 v114, v2
	v_mov_b32_e32 v115, v2
	v_mov_b32_e32 v116, v2
	v_mov_b32_e32 v117, v2
	v_mov_b32_e32 v118, v2
	v_mov_b32_e32 v119, v2
	v_mov_b32_e32 v120, v2
	v_mov_b32_e32 v121, v2
	v_mov_b32_e32 v74, v2
	v_mov_b32_e32 v75, v2
	v_mov_b32_e32 v76, v2
	v_mov_b32_e32 v77, v2
	v_mov_b32_e32 v78, v2
	v_mov_b32_e32 v79, v2
	v_mov_b32_e32 v80, v2
	v_mov_b32_e32 v81, v2
	v_mov_b32_e32 v90, v2
	v_mov_b32_e32 v91, v2
	v_mov_b32_e32 v92, v2
	v_mov_b32_e32 v93, v2
	v_mov_b32_e32 v94, v2
	v_mov_b32_e32 v95, v2
	v_mov_b32_e32 v96, v2
	v_mov_b32_e32 v97, v2
	v_mov_b32_e32 v106, v2
	v_mov_b32_e32 v107, v2
	v_mov_b32_e32 v108, v2
	v_mov_b32_e32 v109, v2
	v_mov_b32_e32 v110, v2
	v_mov_b32_e32 v111, v2
	v_mov_b32_e32 v112, v2
	v_mov_b32_e32 v113, v2
	v_mov_b32_e32 v122, v2
	v_mov_b32_e32 v123, v2
	v_mov_b32_e32 v124, v2
	v_mov_b32_e32 v125, v2
	v_mov_b32_e32 v126, v2
	v_mov_b32_e32 v127, v2
	v_mov_b32_e32 v128, v2
	v_mov_b32_e32 v129, v2
	v_readfirstlane_b32 s99, v216
	s_cmp_lt_u32 s99, 0x100
	s_cbranch_scc1 .Lgprio3
	s_setprio 1
.Lgprio3:
.LBB0_345:
	s_add_u32 s34, s56, 0xfff80080
	s_addc_u32 s35, s57, -1
	s_add_i32 s81, 0, 0x10000
	s_cmp_eq_u32 s80, 28
	s_cselect_b32 s61, s49, s35
	s_cselect_b32 s60, s55, s34
	s_cselect_b32 s59, s47, s77
	s_cselect_b32 s58, s75, s76
	s_add_i32 s82, 0, 0x14000
	v_add_u32_e32 v152, s81, v141
	v_add_u32_e32 v168, s82, v141
	ds_read_b128 v[136:139], v152
	ds_read_b128 v[144:147], v152 offset:1024
	ds_read_b128 v[148:151], v152 offset:2048
	ds_read_b128 v[152:155], v152 offset:3072
	ds_read_b128 v[156:159], v168
	ds_read_b128 v[160:163], v168 offset:1024
	ds_read_b128 v[164:167], v168 offset:2048
	ds_read_b128 v[168:171], v168 offset:3072
	v_lshl_add_u64 v[188:189], s[56:57], 0, v[132:133]
	s_add_i32 m0, s65, 0xc000
	ds_read_b128 v[172:175], v143
	ds_read_b128 v[176:179], v143 offset:1024
	ds_read_b128 v[180:183], v143 offset:2048
	ds_read_b128 v[184:187], v143 offset:3072
	ds_read_b128 v[196:199], v143 offset:4096
	ds_read_b128 v[200:203], v143 offset:5120
	ds_read_b128 v[204:207], v143 offset:6144
	ds_read_b128 v[208:211], v143 offset:7168
	global_load_lds_dwordx4 v[188:189], off
	v_lshl_add_u64 v[188:189], s[56:57], 0, v[134:135]
	s_add_i32 m0, s65, 0xe000
	s_nop 0
	global_load_lds_dwordx4 v[188:189], off
	s_waitcnt vmcnt(8)
	s_waitcnt lgkmcnt(0)
	s_barrier
; #define PG8_STAGE(bufoff, gbase, voff) do { _Pragma("unroll") for (int _i = 0; _i < 2; ++_i) \
;         __builtin_amdgcn_global_load_lds((const unsigned*)((const char*)(gbase) + (voff)[_i]), (LAS unsigned*)(lds + (bufoff) + ldsw + _i * 8192), 16, 0, 0); } while (0)
; #define PG8_STAGEA(bufoff, gbase, voff) do { _Pragma("unroll") for (int _i = 0; _i < 2; ++_i) \
;         __builtin_amdgcn_global_load_lds((const unsigned*)((const char*)(gbase) + (voff)[_i]), (LAS unsigned*)(lds + (bufoff) + ldsw + _i * 8192), 16, 0, 0); } while (0)
; #define PG8_LDA(dst, b, h) do { _Pragma("unroll") for (int m = 0; m < 4; ++m) _Pragma("unroll") for (int k = 0; k < 2; ++k) dst[m][k] = *(const LAS bf16x8*)(lds + PG8_SA(b, h) + aoff + m * 2048 + k * 1024); } while (0)
; #define PG8_MMA(ai, bj, At, Bt) do { __builtin_amdgcn_s_setprio(3); _Pragma("unroll") for (int m = 0; m < 4; ++m) _Pragma("unroll") for (int n = 0; n < 2; ++n) _Pragma("unroll") for (int k = 0; k < 2; ++k) \
;         acc[ai][bj][m][n] = __builtin_amdgcn_mfma_f32_16x16x32_bf16(Bt[n][k], At[m][k], acc[ai][bj][m][n], 0, 0, 0); __builtin_amdgcn_s_setprio(0); } while (0)
; #define PG8_WAIT_V(n) asm volatile("s_waitcnt vmcnt(" #n ")" ::: "memory")
; #define PG8_WAIT_L(n) asm volatile("s_waitcnt lgkmcnt(" #n ")" ::: "memory")
; #define PG8_BAR __builtin_amdgcn_s_barrier()
; #define PG8_SCHED __builtin_amdgcn_sched_barrier(0)
; template <class Epi, int PARTS>
; __device__ __forceinline__ void gemm_phase(LAS unsigned char* lds, const Gemm g, const StaticOrder& S, const Epi& E) {
;     ...
;             PG8_WAIT_V(8); PG8_WAIT_L(0); PG8_BAR; PG8_MMA(0, 0, At, B0); PG8_MMA(0, 1, At, B1); PG8_BAR; PG8_SCHED;
;             PG8_LDA(At, 0, 1); PG8_STAGE(PG8_SB(0, 0), b2, voffB); PG8_STAGE(PG8_SB(0, 1), b2 + hstepB, voffB); PG8_STAGEA(PG8_SA(0, 0), a2, voffA);
;             PG8_WAIT_V(8); PG8_WAIT_L(0); PG8_BAR; PG8_MMA(1, 0, At, B0); PG8_MMA(1, 1, At, B1); PG8_BAR; PG8_SCHED;
	s_waitcnt lgkmcnt(0)
	v_mfma_f32_16x16x32_bf16 v[126:129], v[136:139], v[172:175], v[126:129]
	v_mfma_f32_16x16x32_bf16 v[122:125], v[148:151], v[172:175], v[122:125]
	v_mfma_f32_16x16x32_bf16 v[110:113], v[136:139], v[180:183], v[110:113]
	v_mfma_f32_16x16x32_bf16 v[106:109], v[148:151], v[180:183], v[106:109]
	v_mfma_f32_16x16x32_bf16 v[94:97], v[136:139], v[196:199], v[94:97]
	v_mfma_f32_16x16x32_bf16 v[90:93], v[148:151], v[196:199], v[90:93]
	v_mfma_f32_16x16x32_bf16 v[78:81], v[136:139], v[204:207], v[78:81]
	v_mfma_f32_16x16x32_bf16 v[74:77], v[148:151], v[204:207], v[74:77]
	v_mfma_f32_16x16x32_bf16 v[126:129], v[144:147], v[176:179], v[126:129]
	v_mfma_f32_16x16x32_bf16 v[122:125], v[152:155], v[176:179], v[122:125]
	v_mfma_f32_16x16x32_bf16 v[110:113], v[144:147], v[184:187], v[110:113]
	v_mfma_f32_16x16x32_bf16 v[106:109], v[152:155], v[184:187], v[106:109]
	v_mfma_f32_16x16x32_bf16 v[94:97], v[144:147], v[200:203], v[94:97]
	v_mfma_f32_16x16x32_bf16 v[90:93], v[152:155], v[200:203], v[90:93]
	v_mfma_f32_16x16x32_bf16 v[78:81], v[144:147], v[208:211], v[78:81]
	v_mfma_f32_16x16x32_bf16 v[74:77], v[152:155], v[208:211], v[74:77]
	v_mfma_f32_16x16x32_bf16 v[118:121], v[156:159], v[172:175], v[118:121]
	v_mfma_f32_16x16x32_bf16 v[114:117], v[164:167], v[172:175], v[114:117]
	v_mfma_f32_16x16x32_bf16 v[102:105], v[156:159], v[180:183], v[102:105]
	v_mfma_f32_16x16x32_bf16 v[98:101], v[164:167], v[180:183], v[98:101]
	v_mfma_f32_16x16x32_bf16 v[86:89], v[156:159], v[196:199], v[86:89]
	v_mfma_f32_16x16x32_bf16 v[82:85], v[164:167], v[196:199], v[82:85]
	v_mfma_f32_16x16x32_bf16 v[70:73], v[156:159], v[204:207], v[70:73]
	v_mfma_f32_16x16x32_bf16 v[66:69], v[164:167], v[204:207], v[66:69]
	v_mfma_f32_16x16x32_bf16 v[118:121], v[160:163], v[176:179], v[118:121]
	v_mfma_f32_16x16x32_bf16 v[114:117], v[168:171], v[176:179], v[114:117]
	v_mfma_f32_16x16x32_bf16 v[102:105], v[160:163], v[184:187], v[102:105]
	v_mfma_f32_16x16x32_bf16 v[98:101], v[168:171], v[184:187], v[98:101]
	v_mfma_f32_16x16x32_bf16 v[86:89], v[160:163], v[200:203], v[86:89]
	v_mfma_f32_16x16x32_bf16 v[82:85], v[168:171], v[200:203], v[82:85]
	v_mfma_f32_16x16x32_bf16 v[70:73], v[160:163], v[208:211], v[70:73]
	v_mfma_f32_16x16x32_bf16 v[66:69], v[168:171], v[208:211], v[66:69]
	s_barrier
	s_add_i32 s34, s81, s64
	v_lshl_add_u64 v[188:189], s[58:59], 0, v[0:1]
	s_mov_b32 m0, s34
	ds_read_b128 v[172:175], v143 offset:16384
	ds_read_b128 v[176:179], v143 offset:17408
	ds_read_b128 v[180:183], v143 offset:18432
	ds_read_b128 v[184:187], v143 offset:19456
	ds_read_b128 v[196:199], v143 offset:20480
	ds_read_b128 v[200:203], v143 offset:21504
	ds_read_b128 v[204:207], v143 offset:22528
	ds_read_b128 v[208:211], v143 offset:23552
	global_load_lds_dwordx4 v[188:189], off
	s_add_i32 m0, s34, 0x2000
	s_add_u32 s34, s58, 0x80000
	v_lshl_add_u64 v[212:213], s[58:59], 0, v[130:131]
	s_addc_u32 s35, s59, 0
	s_add_i32 s81, s82, s64
	global_load_lds_dwordx4 v[212:213], off
	v_lshl_add_u64 v[214:215], s[34:35], 0, v[0:1]
	s_mov_b32 m0, s81
	v_lshl_add_u64 v[224:225], s[60:61], 0, v[130:131]
	global_load_lds_dwordx4 v[214:215], off
	v_lshl_add_u64 v[214:215], s[34:35], 0, v[130:131]
	s_add_i32 m0, s81, 0x2000
	s_nop 0
	global_load_lds_dwordx4 v[214:215], off
	v_lshl_add_u64 v[214:215], s[60:61], 0, v[0:1]
	s_mov_b32 m0, s65
	s_nop 0
	global_load_lds_dwordx4 v[214:215], off
	s_mov_b32 m0, s66
	s_nop 0
	global_load_lds_dwordx4 v[224:225], off
	s_waitcnt vmcnt(8)
	s_waitcnt lgkmcnt(0)
	s_barrier
	s_waitcnt lgkmcnt(0)
	v_mfma_f32_16x16x32_bf16 v[62:65], v[136:139], v[172:175], v[62:65]
	v_mfma_f32_16x16x32_bf16 v[58:61], v[148:151], v[172:175], v[58:61]
	v_mfma_f32_16x16x32_bf16 v[46:49], v[136:139], v[180:183], v[46:49]
	v_mfma_f32_16x16x32_bf16 v[42:45], v[148:151], v[180:183], v[42:45]
	v_mfma_f32_16x16x32_bf16 v[30:33], v[136:139], v[196:199], v[30:33]
	v_mfma_f32_16x16x32_bf16 v[26:29], v[148:151], v[196:199], v[26:29]
	v_mfma_f32_16x16x32_bf16 v[14:17], v[136:139], v[204:207], v[14:17]
	v_mfma_f32_16x16x32_bf16 v[10:13], v[148:151], v[204:207], v[10:13]
	v_mfma_f32_16x16x32_bf16 v[62:65], v[144:147], v[176:179], v[62:65]
	v_mfma_f32_16x16x32_bf16 v[58:61], v[152:155], v[176:179], v[58:61]
	v_mfma_f32_16x16x32_bf16 v[46:49], v[144:147], v[184:187], v[46:49]
	v_mfma_f32_16x16x32_bf16 v[42:45], v[152:155], v[184:187], v[42:45]
	v_mfma_f32_16x16x32_bf16 v[30:33], v[144:147], v[200:203], v[30:33]
	v_mfma_f32_16x16x32_bf16 v[26:29], v[152:155], v[200:203], v[26:29]
	v_mfma_f32_16x16x32_bf16 v[14:17], v[144:147], v[208:211], v[14:17]
	v_mfma_f32_16x16x32_bf16 v[10:13], v[152:155], v[208:211], v[10:13]
	v_mfma_f32_16x16x32_bf16 v[54:57], v[156:159], v[172:175], v[54:57]
	v_mfma_f32_16x16x32_bf16 v[50:53], v[164:167], v[172:175], v[50:53]
	v_mfma_f32_16x16x32_bf16 v[38:41], v[156:159], v[180:183], v[38:41]
	v_mfma_f32_16x16x32_bf16 v[34:37], v[164:167], v[180:183], v[34:37]
	v_mfma_f32_16x16x32_bf16 v[22:25], v[156:159], v[196:199], v[22:25]
	v_mfma_f32_16x16x32_bf16 v[18:21], v[164:167], v[196:199], v[18:21]
	v_mfma_f32_16x16x32_bf16 v[6:9], v[156:159], v[204:207], v[6:9]
	v_mfma_f32_16x16x32_bf16 v[2:5], v[164:167], v[204:207], v[2:5]
	v_mfma_f32_16x16x32_bf16 v[54:57], v[160:163], v[176:179], v[54:57]
	v_mfma_f32_16x16x32_bf16 v[50:53], v[168:171], v[176:179], v[50:53]
	v_mfma_f32_16x16x32_bf16 v[38:41], v[160:163], v[184:187], v[38:41]
	v_mfma_f32_16x16x32_bf16 v[34:37], v[168:171], v[184:187], v[34:37]
	v_mfma_f32_16x16x32_bf16 v[22:25], v[160:163], v[200:203], v[22:25]
	v_mfma_f32_16x16x32_bf16 v[18:21], v[168:171], v[200:203], v[18:21]
	v_mfma_f32_16x16x32_bf16 v[6:9], v[160:163], v[208:211], v[6:9]
	v_mfma_f32_16x16x32_bf16 v[2:5], v[168:171], v[208:211], v[2:5]
	s_barrier
; #define PG8_STAGEA(bufoff, gbase, voff) do { _Pragma("unroll") for (int _i = 0; _i < 2; ++_i) \
;         __builtin_amdgcn_global_load_lds((const unsigned*)((const char*)(gbase) + (voff)[_i]), (LAS unsigned*)(lds + (bufoff) + ldsw + _i * 8192), 16, 0, 0); } while (0)
; #define PG8_LDA(dst, b, h) do { _Pragma("unroll") for (int m = 0; m < 4; ++m) _Pragma("unroll") for (int k = 0; k < 2; ++k) dst[m][k] = *(const LAS bf16x8*)(lds + PG8_SA(b, h) + aoff + m * 2048 + k * 1024); } while (0)
; #define PG8_LDB(dst, b, h) do { _Pragma("unroll") for (int n = 0; n < 2; ++n) _Pragma("unroll") for (int k = 0; k < 2; ++k) dst[n][k] = *(const LAS bf16x8*)(lds + PG8_SB(b, h) + boff + n * 2048 + k * 1024); } while (0)
; #define PG8_MMA(ai, bj, At, Bt) do { __builtin_amdgcn_s_setprio(3); _Pragma("unroll") for (int m = 0; m < 4; ++m) _Pragma("unroll") for (int n = 0; n < 2; ++n) _Pragma("unroll") for (int k = 0; k < 2; ++k) \
;         acc[ai][bj][m][n] = __builtin_amdgcn_mfma_f32_16x16x32_bf16(Bt[n][k], At[m][k], acc[ai][bj][m][n], 0, 0, 0); __builtin_amdgcn_s_setprio(0); } while (0)
; #define PG8_WAIT_V(n) asm volatile("s_waitcnt vmcnt(" #n ")" ::: "memory")
; #define PG8_WAIT_L(n) asm volatile("s_waitcnt lgkmcnt(" #n ")" ::: "memory")
; #define PG8_BAR __builtin_amdgcn_s_barrier()
; #define PG8_SCHED __builtin_amdgcn_sched_barrier(0)
; template <class Epi, int PARTS>
; __device__ __forceinline__ void gemm_phase(LAS unsigned char* lds, const Gemm g, const StaticOrder& S, const Epi& E) {
;     ...
;             PG8_LDB(B0, 1, 0); PG8_LDB(B1, 1, 1); PG8_SCHED; PG8_LDA(At, 1, 0); PG8_STAGEA(PG8_SA(0, 1), a2 + hstepA, voffA);
;             PG8_WAIT_V(8); PG8_WAIT_L(0); PG8_BAR; PG8_MMA(0, 0, At, B0); PG8_MMA(0, 1, At, B1); PG8_BAR; PG8_SCHED;
	s_add_i32 s81, 0, 0x18000
	s_add_i32 s82, 0, 0x1c000
	v_add_u32_e32 v152, s81, v141
	v_add_u32_e32 v168, s82, v141
	ds_read_b128 v[136:139], v152
	ds_read_b128 v[144:147], v152 offset:1024
	ds_read_b128 v[148:151], v152 offset:2048
	ds_read_b128 v[152:155], v152 offset:3072
	ds_read_b128 v[156:159], v168
	ds_read_b128 v[160:163], v168 offset:1024
	ds_read_b128 v[164:167], v168 offset:2048
	ds_read_b128 v[168:171], v168 offset:3072
	s_add_u32 s34, s60, 0x80000
	s_addc_u32 s35, s61, 0
	s_mov_b32 m0, s67
	v_lshl_add_u64 v[228:229], s[34:35], 0, v[0:1]
	ds_read_b128 v[172:175], v143 offset:32768
	ds_read_b128 v[176:179], v143 offset:33792
	ds_read_b128 v[180:183], v143 offset:34816
	ds_read_b128 v[184:187], v143 offset:35840
	ds_read_b128 v[196:199], v143 offset:36864
	ds_read_b128 v[200:203], v143 offset:37888
	ds_read_b128 v[204:207], v143 offset:38912
	ds_read_b128 v[208:211], v143 offset:39936
	global_load_lds_dwordx4 v[228:229], off
	v_lshl_add_u64 v[228:229], s[34:35], 0, v[130:131]
	s_mov_b32 m0, s69
	s_nop 0
	global_load_lds_dwordx4 v[228:229], off
	s_waitcnt vmcnt(8)
	s_waitcnt lgkmcnt(0)
	s_barrier
	s_waitcnt lgkmcnt(0)
	v_mfma_f32_16x16x32_bf16 v[126:129], v[136:139], v[172:175], v[126:129]
	v_mfma_f32_16x16x32_bf16 v[122:125], v[148:151], v[172:175], v[122:125]
	v_mfma_f32_16x16x32_bf16 v[110:113], v[136:139], v[180:183], v[110:113]
	v_mfma_f32_16x16x32_bf16 v[106:109], v[148:151], v[180:183], v[106:109]
	v_mfma_f32_16x16x32_bf16 v[94:97], v[136:139], v[196:199], v[94:97]
	v_mfma_f32_16x16x32_bf16 v[90:93], v[148:151], v[196:199], v[90:93]
	v_mfma_f32_16x16x32_bf16 v[78:81], v[136:139], v[204:207], v[78:81]
	v_mfma_f32_16x16x32_bf16 v[74:77], v[148:151], v[204:207], v[74:77]
	v_mfma_f32_16x16x32_bf16 v[126:129], v[144:147], v[176:179], v[126:129]
	v_mfma_f32_16x16x32_bf16 v[122:125], v[152:155], v[176:179], v[122:125]
	v_mfma_f32_16x16x32_bf16 v[110:113], v[144:147], v[184:187], v[110:113]
	v_mfma_f32_16x16x32_bf16 v[106:109], v[152:155], v[184:187], v[106:109]
	v_mfma_f32_16x16x32_bf16 v[94:97], v[144:147], v[200:203], v[94:97]
	v_mfma_f32_16x16x32_bf16 v[90:93], v[152:155], v[200:203], v[90:93]
	v_mfma_f32_16x16x32_bf16 v[78:81], v[144:147], v[208:211], v[78:81]
	v_mfma_f32_16x16x32_bf16 v[74:77], v[152:155], v[208:211], v[74:77]
	v_mfma_f32_16x16x32_bf16 v[118:121], v[156:159], v[172:175], v[118:121]
	v_mfma_f32_16x16x32_bf16 v[114:117], v[164:167], v[172:175], v[114:117]
	v_mfma_f32_16x16x32_bf16 v[102:105], v[156:159], v[180:183], v[102:105]
	v_mfma_f32_16x16x32_bf16 v[98:101], v[164:167], v[180:183], v[98:101]
	v_mfma_f32_16x16x32_bf16 v[86:89], v[156:159], v[196:199], v[86:89]
	v_mfma_f32_16x16x32_bf16 v[82:85], v[164:167], v[196:199], v[82:85]
	v_mfma_f32_16x16x32_bf16 v[70:73], v[156:159], v[204:207], v[70:73]
	v_mfma_f32_16x16x32_bf16 v[66:69], v[164:167], v[204:207], v[66:69]
	v_mfma_f32_16x16x32_bf16 v[118:121], v[160:163], v[176:179], v[118:121]
	v_mfma_f32_16x16x32_bf16 v[114:117], v[168:171], v[176:179], v[114:117]
	v_mfma_f32_16x16x32_bf16 v[102:105], v[160:163], v[184:187], v[102:105]
	v_mfma_f32_16x16x32_bf16 v[98:101], v[168:171], v[184:187], v[98:101]
	v_mfma_f32_16x16x32_bf16 v[86:89], v[160:163], v[200:203], v[86:89]
	v_mfma_f32_16x16x32_bf16 v[82:85], v[168:171], v[200:203], v[82:85]
	v_mfma_f32_16x16x32_bf16 v[70:73], v[160:163], v[208:211], v[70:73]
	v_mfma_f32_16x16x32_bf16 v[66:69], v[168:171], v[208:211], v[66:69]
	s_barrier
; #define PG8_STAGE(bufoff, gbase, voff) do { _Pragma("unroll") for (int _i = 0; _i < 2; ++_i) \
;         __builtin_amdgcn_global_load_lds((const unsigned*)((const char*)(gbase) + (voff)[_i]), (LAS unsigned*)(lds + (bufoff) + ldsw + _i * 8192), 16, 0, 0); } while (0)
; #define PG8_STAGEA(bufoff, gbase, voff) do { _Pragma("unroll") for (int _i = 0; _i < 2; ++_i) \
;         __builtin_amdgcn_global_load_lds((const unsigned*)((const char*)(gbase) + (voff)[_i]), (LAS unsigned*)(lds + (bufoff) + ldsw + _i * 8192), 16, 0, 0); } while (0)
; #define PG8_LDA(dst, b, h) do { _Pragma("unroll") for (int m = 0; m < 4; ++m) _Pragma("unroll") for (int k = 0; k < 2; ++k) dst[m][k] = *(const LAS bf16x8*)(lds + PG8_SA(b, h) + aoff + m * 2048 + k * 1024); } while (0)
; #define PG8_MMA(ai, bj, At, Bt) do { __builtin_amdgcn_s_setprio(3); _Pragma("unroll") for (int m = 0; m < 4; ++m) _Pragma("unroll") for (int n = 0; n < 2; ++n) _Pragma("unroll") for (int k = 0; k < 2; ++k) \
;         acc[ai][bj][m][n] = __builtin_amdgcn_mfma_f32_16x16x32_bf16(Bt[n][k], At[m][k], acc[ai][bj][m][n], 0, 0, 0); __builtin_amdgcn_s_setprio(0); } while (0)
; #define PG8_WAIT_V(n) asm volatile("s_waitcnt vmcnt(" #n ")" ::: "memory")
; #define PG8_WAIT_L(n) asm volatile("s_waitcnt lgkmcnt(" #n ")" ::: "memory")
; #define PG8_BAR __builtin_amdgcn_s_barrier()
; #define PG8_SCHED __builtin_amdgcn_sched_barrier(0)
; template <class Epi, int PARTS>
; __device__ __forceinline__ void gemm_phase(LAS unsigned char* lds, const Gemm g, const StaticOrder& S, const Epi& E) {
;     ...
;             PG8_LDA(At, 1, 1); PG8_STAGE(PG8_SB(1, 0), b3, voffB); PG8_STAGE(PG8_SB(1, 1), b3 + hstepB, voffB); PG8_STAGEA(PG8_SA(1, 0), a3, voffA);
;             PG8_WAIT_V(8); PG8_WAIT_L(0); PG8_BAR; PG8_MMA(1, 0, At, B0); PG8_MMA(1, 1, At, B1); PG8_BAR; PG8_SCHED;
;         }
;         if (wr == 0) PG8_BAR;
	s_add_i32 s34, s81, s64
	v_lshl_add_u64 v[188:189], v[188:189], 0, s[72:73]
	s_mov_b32 m0, s34
	ds_read_b128 v[172:175], v143 offset:49152
	ds_read_b128 v[176:179], v143 offset:50176
	ds_read_b128 v[180:183], v143 offset:51200
	ds_read_b128 v[184:187], v143 offset:52224
	ds_read_b128 v[196:199], v143 offset:53248
	ds_read_b128 v[200:203], v143 offset:54272
	ds_read_b128 v[204:207], v143 offset:55296
	ds_read_b128 v[208:211], v143 offset:56320
	global_load_lds_dwordx4 v[188:189], off
	s_add_i32 m0, s34, 0x2000
	s_add_u32 s34, s58, 0x80080
	v_lshl_add_u64 v[188:189], v[212:213], 0, s[72:73]
	s_addc_u32 s35, s59, 0
	s_add_i32 s58, s82, s64
	global_load_lds_dwordx4 v[188:189], off
	v_lshl_add_u64 v[188:189], s[34:35], 0, v[0:1]
	s_mov_b32 m0, s58
	s_nop 0
	global_load_lds_dwordx4 v[188:189], off
	v_lshl_add_u64 v[188:189], s[34:35], 0, v[130:131]
	s_add_i32 m0, s58, 0x2000
	s_nop 0
	global_load_lds_dwordx4 v[188:189], off
	v_lshl_add_u64 v[188:189], v[214:215], 0, s[72:73]
	s_mov_b32 m0, s33
	s_nop 0
	global_load_lds_dwordx4 v[188:189], off
	v_lshl_add_u64 v[188:189], v[224:225], 0, s[72:73]
	s_mov_b32 m0, s36
	s_nop 0
	global_load_lds_dwordx4 v[188:189], off
	s_waitcnt vmcnt(8)
	s_waitcnt lgkmcnt(0)
	s_barrier
	s_waitcnt lgkmcnt(0)
	v_mfma_f32_16x16x32_bf16 v[62:65], v[136:139], v[172:175], v[62:65]
	v_mfma_f32_16x16x32_bf16 v[58:61], v[148:151], v[172:175], v[58:61]
	v_mfma_f32_16x16x32_bf16 v[46:49], v[136:139], v[180:183], v[46:49]
	v_mfma_f32_16x16x32_bf16 v[42:45], v[148:151], v[180:183], v[42:45]
	v_mfma_f32_16x16x32_bf16 v[30:33], v[136:139], v[196:199], v[30:33]
	v_mfma_f32_16x16x32_bf16 v[26:29], v[148:151], v[196:199], v[26:29]
	v_mfma_f32_16x16x32_bf16 v[14:17], v[136:139], v[204:207], v[14:17]
	v_mfma_f32_16x16x32_bf16 v[10:13], v[148:151], v[204:207], v[10:13]
	v_mfma_f32_16x16x32_bf16 v[62:65], v[144:147], v[176:179], v[62:65]
	v_mfma_f32_16x16x32_bf16 v[58:61], v[152:155], v[176:179], v[58:61]
	v_mfma_f32_16x16x32_bf16 v[46:49], v[144:147], v[184:187], v[46:49]
	v_mfma_f32_16x16x32_bf16 v[42:45], v[152:155], v[184:187], v[42:45]
	v_mfma_f32_16x16x32_bf16 v[30:33], v[144:147], v[200:203], v[30:33]
	v_mfma_f32_16x16x32_bf16 v[26:29], v[152:155], v[200:203], v[26:29]
	v_mfma_f32_16x16x32_bf16 v[14:17], v[144:147], v[208:211], v[14:17]
	v_mfma_f32_16x16x32_bf16 v[10:13], v[152:155], v[208:211], v[10:13]
	v_mfma_f32_16x16x32_bf16 v[54:57], v[156:159], v[172:175], v[54:57]
	v_mfma_f32_16x16x32_bf16 v[50:53], v[164:167], v[172:175], v[50:53]
	v_mfma_f32_16x16x32_bf16 v[38:41], v[156:159], v[180:183], v[38:41]
	v_mfma_f32_16x16x32_bf16 v[34:37], v[164:167], v[180:183], v[34:37]
	v_mfma_f32_16x16x32_bf16 v[22:25], v[156:159], v[196:199], v[22:25]
	v_mfma_f32_16x16x32_bf16 v[18:21], v[164:167], v[196:199], v[18:21]
	v_mfma_f32_16x16x32_bf16 v[6:9], v[156:159], v[204:207], v[6:9]
	v_mfma_f32_16x16x32_bf16 v[2:5], v[164:167], v[204:207], v[2:5]
	v_mfma_f32_16x16x32_bf16 v[54:57], v[160:163], v[176:179], v[54:57]
	v_mfma_f32_16x16x32_bf16 v[50:53], v[168:171], v[176:179], v[50:53]
	v_mfma_f32_16x16x32_bf16 v[38:41], v[160:163], v[184:187], v[38:41]
	v_mfma_f32_16x16x32_bf16 v[34:37], v[168:171], v[184:187], v[34:37]
	v_mfma_f32_16x16x32_bf16 v[22:25], v[160:163], v[200:203], v[22:25]
	v_mfma_f32_16x16x32_bf16 v[18:21], v[168:171], v[200:203], v[18:21]
	v_mfma_f32_16x16x32_bf16 v[6:9], v[160:163], v[208:211], v[6:9]
	v_mfma_f32_16x16x32_bf16 v[2:5], v[168:171], v[208:211], v[2:5]
	s_barrier
	s_add_i32 s80, s80, 2
	s_add_u32 s56, s56, 0x100
	s_addc_u32 s57, s57, 0
	s_add_u32 s76, s76, 0x100
	s_addc_u32 s77, s77, 0
	s_cmp_gt_u32 s80, 29
	s_cbranch_scc0 .LBB0_345
	s_setprio 0
	s_and_b64 vcc, exec, s[44:45]
	s_cbranch_vccz .LBB0_348
	s_barrier

; #define PG8_STAGEA(bufoff, gbase, voff) do { _Pragma("unroll") for (int _i = 0; _i < 2; ++_i) \
;         __builtin_amdgcn_global_load_lds((const unsigned*)((const char*)(gbase) + (voff)[_i]), (LAS unsigned*)(lds + (bufoff) + ldsw + _i * 8192), 16, 0, 0); } while (0)
; #define PG8_LDA(dst, b, h) do { _Pragma("unroll") for (int m = 0; m < 4; ++m) _Pragma("unroll") for (int k = 0; k < 2; ++k) dst[m][k] = *(const LAS bf16x8*)(lds + PG8_SA(b, h) + aoff + m * 2048 + k * 1024); } while (0)
; #define PG8_LDB(dst, b, h) do { _Pragma("unroll") for (int n = 0; n < 2; ++n) _Pragma("unroll") for (int k = 0; k < 2; ++k) dst[n][k] = *(const LAS bf16x8*)(lds + PG8_SB(b, h) + boff + n * 2048 + k * 1024); } while (0)
; #define PG8_SCHED __builtin_amdgcn_sched_barrier(0)
; template <class Epi, int PARTS>
; __device__ __forceinline__ void gemm_phase(LAS unsigned char* lds, const Gemm g, const StaticOrder& S, const Epi& E) {
;     ...
;         const bool has_next = S.next(ui + 1, nxt);
;         const char* nA = has_next ? PG8_UA(nxt) : cA; const char* nB = has_next ? PG8_UB(nxt) : cB;
;         for (int t = 0; t < nt; t += 2) {
;             const bool last = (t == nt - 2);
;             const char* a1 = cA + (size_t)(t + 1) * kstep;
;             const char* a2 = last ? nA : cA + (size_t)(t + 2) * kstep; const char* b2 = last ? nB : cB + (size_t)(t + 2) * kstep;
;             const char* a3 = a2 + kstep; const char* b3 = b2 + kstep;
;             PG8_LDB(B0, 0, 0); PG8_LDB(B1, 0, 1); PG8_SCHED; PG8_LDA(At, 0, 0); PG8_STAGEA(PG8_SA(1, 1), a1 + hstepA, voffA);
;     ...
; #pragma unroll
;         for (int a = 0; a < 2; ++a)
; #pragma unroll
;             for (int b = 0; b < 2; ++b)
; #pragma unroll
;                 for (int m = 0; m < 4; ++m)
; #pragma unroll
;                     for (int n = 0; n < 2; ++n) acc[a][b][m][n] = (f32x4){0.f, 0.f, 0.f, 0.f};
.LBB0_378:
	s_ashr_i32 s55, s54, 31
	s_lshl_b64 s[36:37], s[54:55], 19
	s_add_u32 s56, s24, s36
	s_addc_u32 s57, s25, s37
	s_and_b64 s[36:37], s[38:39], exec
	s_cselect_b32 s1, s57, s61
	s_cselect_b32 s33, s56, s60
	s_ashr_i32 s53, s52, 31
	s_lshl_b64 s[36:37], s[52:53], 19
	v_readlane_b32 s34, v254, 50
	s_add_u32 s58, s34, s36
	v_readlane_b32 s34, v254, 52
	s_addc_u32 s59, s34, s37
	s_and_b64 s[36:37], s[38:39], exec
	s_cselect_b32 s36, s59, s63
	s_cselect_b32 s37, s58, s62
	s_add_u32 s49, s62, 0x100
	v_mov_b32_e32 v2, 0
	s_addc_u32 s53, s63, 0
	s_mov_b32 s55, -2
	v_mov_b32_e32 v3, v2
	v_mov_b32_e32 v4, v2
	v_mov_b32_e32 v5, v2
	v_mov_b32_e32 v6, v2
	v_mov_b32_e32 v7, v2
	v_mov_b32_e32 v8, v2
	v_mov_b32_e32 v9, v2
	v_mov_b32_e32 v10, v2
	v_mov_b32_e32 v11, v2
	v_mov_b32_e32 v12, v2
	v_mov_b32_e32 v13, v2
	v_mov_b32_e32 v14, v2
	v_mov_b32_e32 v15, v2
	v_mov_b32_e32 v16, v2
	v_mov_b32_e32 v17, v2
	v_mov_b32_e32 v26, v2
	v_mov_b32_e32 v27, v2
	v_mov_b32_e32 v28, v2
	v_mov_b32_e32 v29, v2
	s_waitcnt vmcnt(0)
	v_mov_b32_e32 v30, v2
	v_mov_b32_e32 v31, v2
	v_mov_b32_e32 v32, v2
	v_mov_b32_e32 v33, v2
	v_mov_b32_e32 v42, v2
	v_mov_b32_e32 v43, v2
	v_mov_b32_e32 v44, v2
	v_mov_b32_e32 v45, v2
	v_mov_b32_e32 v46, v2
	v_mov_b32_e32 v47, v2
	v_mov_b32_e32 v48, v2
	v_mov_b32_e32 v49, v2
	v_mov_b32_e32 v18, v2
	v_mov_b32_e32 v19, v2
	v_mov_b32_e32 v20, v2
	v_mov_b32_e32 v21, v2
	v_mov_b32_e32 v22, v2
	v_mov_b32_e32 v23, v2
	v_mov_b32_e32 v24, v2
	v_mov_b32_e32 v25, v2
	v_mov_b32_e32 v34, v2
	v_mov_b32_e32 v35, v2
	v_mov_b32_e32 v36, v2
	v_mov_b32_e32 v37, v2
	v_mov_b32_e32 v38, v2
	v_mov_b32_e32 v39, v2
	v_mov_b32_e32 v40, v2
	v_mov_b32_e32 v41, v2
	v_mov_b32_e32 v50, v2
	v_mov_b32_e32 v51, v2
	v_mov_b32_e32 v52, v2
	v_mov_b32_e32 v53, v2
	v_mov_b32_e32 v54, v2
	v_mov_b32_e32 v55, v2
	v_mov_b32_e32 v56, v2
	v_mov_b32_e32 v57, v2
	v_mov_b32_e32 v58, v2
	v_mov_b32_e32 v59, v2
	v_mov_b32_e32 v60, v2
	v_mov_b32_e32 v61, v2
	v_mov_b32_e32 v62, v2
	v_mov_b32_e32 v63, v2
	v_mov_b32_e32 v64, v2
	v_mov_b32_e32 v65, v2
	v_mov_b32_e32 v66, v2
	v_mov_b32_e32 v67, v2
	v_mov_b32_e32 v68, v2
	v_mov_b32_e32 v69, v2
	v_mov_b32_e32 v70, v2
	v_mov_b32_e32 v71, v2
	v_mov_b32_e32 v72, v2
	v_mov_b32_e32 v73, v2
	v_mov_b32_e32 v74, v2
	v_mov_b32_e32 v75, v2
	v_mov_b32_e32 v76, v2
	v_mov_b32_e32 v77, v2
	v_mov_b32_e32 v78, v2
	v_mov_b32_e32 v79, v2
	v_mov_b32_e32 v80, v2
	v_mov_b32_e32 v81, v2
	v_mov_b32_e32 v90, v2
	v_mov_b32_e32 v91, v2
	v_mov_b32_e32 v92, v2
	v_mov_b32_e32 v93, v2
	v_mov_b32_e32 v94, v2
	v_mov_b32_e32 v95, v2
	v_mov_b32_e32 v96, v2
	v_mov_b32_e32 v97, v2
	v_mov_b32_e32 v106, v2
	v_mov_b32_e32 v107, v2
	v_mov_b32_e32 v108, v2
	v_mov_b32_e32 v109, v2
	v_mov_b32_e32 v110, v2
	v_mov_b32_e32 v111, v2
	v_mov_b32_e32 v112, v2
	v_mov_b32_e32 v113, v2
	v_mov_b32_e32 v82, v2
	v_mov_b32_e32 v83, v2
	v_mov_b32_e32 v84, v2
	v_mov_b32_e32 v85, v2
	v_mov_b32_e32 v86, v2
	v_mov_b32_e32 v87, v2
	v_mov_b32_e32 v88, v2
	v_mov_b32_e32 v89, v2
	v_mov_b32_e32 v98, v2
	v_mov_b32_e32 v99, v2
	v_mov_b32_e32 v100, v2
	v_mov_b32_e32 v101, v2
	v_mov_b32_e32 v102, v2
	v_mov_b32_e32 v103, v2
	v_mov_b32_e32 v104, v2
	v_mov_b32_e32 v105, v2
	v_mov_b32_e32 v114, v2
	v_mov_b32_e32 v115, v2
	v_mov_b32_e32 v116, v2
	v_mov_b32_e32 v117, v2
	v_mov_b32_e32 v118, v2
	v_mov_b32_e32 v119, v2
	v_mov_b32_e32 v120, v2
	v_mov_b32_e32 v121, v2
	v_mov_b32_e32 v122, v2
	v_mov_b32_e32 v123, v2
	v_mov_b32_e32 v124, v2
	v_mov_b32_e32 v125, v2
	v_mov_b32_e32 v126, v2
	v_mov_b32_e32 v127, v2
	v_mov_b32_e32 v128, v2
	v_mov_b32_e32 v129, v2
	v_readfirstlane_b32 s99, v216
	s_cmp_lt_u32 s99, 0x100
	s_cbranch_scc1 .Lgprio4
	s_setprio 1
.Lgprio4:
.LBB0_379:
	s_add_u32 s62, s60, 0x100
	s_addc_u32 s63, s61, 0
	s_add_i32 s34, 0, 0x10000
	s_cmp_eq_u32 s55, 12
	s_cselect_b32 s67, s1, s63
	s_cselect_b32 s66, s33, s62
	v_add_u32_e32 v0, s34, v143
	s_cselect_b32 s65, s36, s53
	s_cselect_b32 s64, s37, s49
	s_add_i32 s35, 0, 0x14000
	ds_read_b128 v[130:133], v0
	ds_read_b128 v[154:157], v0 offset:1024
	ds_read_b128 v[158:161], v0 offset:2048
	ds_read_b128 v[162:165], v0 offset:3072
	v_add_u32_e32 v0, s35, v143
	ds_read_b128 v[166:169], v0
	ds_read_b128 v[170:173], v0 offset:1024
	ds_read_b128 v[174:177], v0 offset:2048
	ds_read_b128 v[184:187], v0 offset:3072
	v_lshl_add_u64 v[178:179], s[60:61], 0, v[150:151]
	s_add_i32 m0, s76, 0xc000
	ds_read_b128 v[196:199], v183
	ds_read_b128 v[200:203], v183 offset:1024
	ds_read_b128 v[204:207], v183 offset:2048
	ds_read_b128 v[208:211], v183 offset:3072
	ds_read_b128 v[212:215], v183 offset:4096
	ds_read_b128 v[236:239], v183 offset:5120
	ds_read_b128 v[240:243], v183 offset:6144
	ds_read_b128 v[248:251], v183 offset:7168
	global_load_lds_dwordx4 v[178:179], off
	v_lshl_add_u64 v[178:179], s[60:61], 0, v[152:153]
	s_add_i32 m0, s76, 0xe000
	s_nop 0
	global_load_lds_dwordx4 v[178:179], off
	s_waitcnt vmcnt(8)
	s_waitcnt lgkmcnt(0)
	s_barrier
; #define PG8_STAGE(bufoff, gbase, voff) do { _Pragma("unroll") for (int _i = 0; _i < 2; ++_i) \
;         __builtin_amdgcn_global_load_lds((const unsigned*)((const char*)(gbase) + (voff)[_i]), (LAS unsigned*)(lds + (bufoff) + ldsw + _i * 8192), 16, 0, 0); } while (0)
; #define PG8_STAGEA(bufoff, gbase, voff) do { _Pragma("unroll") for (int _i = 0; _i < 2; ++_i) \
;         __builtin_amdgcn_global_load_lds((const unsigned*)((const char*)(gbase) + (voff)[_i]), (LAS unsigned*)(lds + (bufoff) + ldsw + _i * 8192), 16, 0, 0); } while (0)
; #define PG8_LDA(dst, b, h) do { _Pragma("unroll") for (int m = 0; m < 4; ++m) _Pragma("unroll") for (int k = 0; k < 2; ++k) dst[m][k] = *(const LAS bf16x8*)(lds + PG8_SA(b, h) + aoff + m * 2048 + k * 1024); } while (0)
; #define PG8_MMA(ai, bj, At, Bt) do { __builtin_amdgcn_s_setprio(3); _Pragma("unroll") for (int m = 0; m < 4; ++m) _Pragma("unroll") for (int n = 0; n < 2; ++n) _Pragma("unroll") for (int k = 0; k < 2; ++k) \
;         acc[ai][bj][m][n] = __builtin_amdgcn_mfma_f32_16x16x32_bf16(Bt[n][k], At[m][k], acc[ai][bj][m][n], 0, 0, 0); __builtin_amdgcn_s_setprio(0); } while (0)
; #define PG8_WAIT_V(n) asm volatile("s_waitcnt vmcnt(" #n ")" ::: "memory")
; #define PG8_WAIT_L(n) asm volatile("s_waitcnt lgkmcnt(" #n ")" ::: "memory")
; #define PG8_BAR __builtin_amdgcn_s_barrier()
; #define PG8_SCHED __builtin_amdgcn_sched_barrier(0)
; template <class Epi, int PARTS>
; __device__ __forceinline__ void gemm_phase(LAS unsigned char* lds, const Gemm g, const StaticOrder& S, const Epi& E) {
;     ...
;             PG8_WAIT_V(8); PG8_WAIT_L(0); PG8_BAR; PG8_MMA(0, 0, At, B0); PG8_MMA(0, 1, At, B1); PG8_BAR; PG8_SCHED;
;             PG8_LDA(At, 0, 1); PG8_STAGE(PG8_SB(0, 0), b2, voffB); PG8_STAGE(PG8_SB(0, 1), b2 + hstepB, voffB); PG8_STAGEA(PG8_SA(0, 0), a2, voffA);
;             PG8_WAIT_V(8); PG8_WAIT_L(0); PG8_BAR; PG8_MMA(1, 0, At, B0); PG8_MMA(1, 1, At, B1); PG8_BAR; PG8_SCHED;
	s_waitcnt lgkmcnt(0)
	v_mfma_f32_16x16x32_bf16 v[126:129], v[130:133], v[196:199], v[126:129]
	v_mfma_f32_16x16x32_bf16 v[122:125], v[158:161], v[196:199], v[122:125]
	v_mfma_f32_16x16x32_bf16 v[118:121], v[130:133], v[204:207], v[118:121]
	v_mfma_f32_16x16x32_bf16 v[114:117], v[158:161], v[204:207], v[114:117]
	v_mfma_f32_16x16x32_bf16 v[102:105], v[130:133], v[212:215], v[102:105]
	v_mfma_f32_16x16x32_bf16 v[98:101], v[158:161], v[212:215], v[98:101]
	v_mfma_f32_16x16x32_bf16 v[86:89], v[130:133], v[240:243], v[86:89]
	v_mfma_f32_16x16x32_bf16 v[82:85], v[158:161], v[240:243], v[82:85]
	v_mfma_f32_16x16x32_bf16 v[126:129], v[154:157], v[200:203], v[126:129]
	v_mfma_f32_16x16x32_bf16 v[122:125], v[162:165], v[200:203], v[122:125]
	v_mfma_f32_16x16x32_bf16 v[118:121], v[154:157], v[208:211], v[118:121]
	v_mfma_f32_16x16x32_bf16 v[114:117], v[162:165], v[208:211], v[114:117]
	v_mfma_f32_16x16x32_bf16 v[102:105], v[154:157], v[236:239], v[102:105]
	v_mfma_f32_16x16x32_bf16 v[98:101], v[162:165], v[236:239], v[98:101]
	v_mfma_f32_16x16x32_bf16 v[86:89], v[154:157], v[248:251], v[86:89]
	v_mfma_f32_16x16x32_bf16 v[82:85], v[162:165], v[248:251], v[82:85]
	v_mfma_f32_16x16x32_bf16 v[110:113], v[166:169], v[196:199], v[110:113]
	v_mfma_f32_16x16x32_bf16 v[106:109], v[174:177], v[196:199], v[106:109]
	v_mfma_f32_16x16x32_bf16 v[94:97], v[166:169], v[204:207], v[94:97]
	v_mfma_f32_16x16x32_bf16 v[90:93], v[174:177], v[204:207], v[90:93]
	v_mfma_f32_16x16x32_bf16 v[78:81], v[166:169], v[212:215], v[78:81]
	v_mfma_f32_16x16x32_bf16 v[74:77], v[174:177], v[212:215], v[74:77]
	v_mfma_f32_16x16x32_bf16 v[70:73], v[166:169], v[240:243], v[70:73]
	v_mfma_f32_16x16x32_bf16 v[66:69], v[174:177], v[240:243], v[66:69]
	v_mfma_f32_16x16x32_bf16 v[110:113], v[170:173], v[200:203], v[110:113]
	v_mfma_f32_16x16x32_bf16 v[106:109], v[184:187], v[200:203], v[106:109]
	v_mfma_f32_16x16x32_bf16 v[94:97], v[170:173], v[208:211], v[94:97]
	v_mfma_f32_16x16x32_bf16 v[90:93], v[184:187], v[208:211], v[90:93]
	v_mfma_f32_16x16x32_bf16 v[78:81], v[170:173], v[236:239], v[78:81]
	v_mfma_f32_16x16x32_bf16 v[74:77], v[184:187], v[236:239], v[74:77]
	v_mfma_f32_16x16x32_bf16 v[70:73], v[170:173], v[248:251], v[70:73]
	v_mfma_f32_16x16x32_bf16 v[66:69], v[184:187], v[248:251], v[66:69]
	s_barrier
	s_add_i32 s34, s34, s75
	v_lshl_add_u64 v[178:179], s[64:65], 0, v[138:139]
	s_mov_b32 m0, s34
	ds_read_b128 v[196:199], v183 offset:16384
	ds_read_b128 v[200:203], v183 offset:17408
	ds_read_b128 v[204:207], v183 offset:18432
	ds_read_b128 v[208:211], v183 offset:19456
	ds_read_b128 v[212:215], v183 offset:20480
	ds_read_b128 v[236:239], v183 offset:21504
	ds_read_b128 v[240:243], v183 offset:22528
	ds_read_b128 v[248:251], v183 offset:23552
	global_load_lds_dwordx4 v[178:179], off
	s_add_i32 m0, s34, 0x2000
	s_add_u32 s60, s64, 0x40000
	v_lshl_add_u64 v[188:189], s[64:65], 0, v[134:135]
	s_addc_u32 s61, s65, 0
	s_add_i32 s34, s35, s75
	global_load_lds_dwordx4 v[188:189], off
	v_lshl_add_u64 v[228:229], s[60:61], 0, v[138:139]
	s_mov_b32 m0, s34
	v_lshl_add_u64 v[230:231], s[66:67], 0, v[136:137]
	global_load_lds_dwordx4 v[228:229], off
	v_lshl_add_u64 v[228:229], s[60:61], 0, v[134:135]
	s_add_i32 m0, s34, 0x2000
	s_nop 0
	global_load_lds_dwordx4 v[228:229], off
	v_lshl_add_u64 v[228:229], s[66:67], 0, v[140:141]
	s_mov_b32 m0, s76
	s_nop 0
	global_load_lds_dwordx4 v[228:229], off
	s_mov_b32 m0, s77
	s_nop 0
	global_load_lds_dwordx4 v[230:231], off
	s_waitcnt vmcnt(8)
	s_waitcnt lgkmcnt(0)
	s_barrier
	s_waitcnt lgkmcnt(0)
	v_mfma_f32_16x16x32_bf16 v[62:65], v[130:133], v[196:199], v[62:65]
	v_mfma_f32_16x16x32_bf16 v[58:61], v[158:161], v[196:199], v[58:61]
	v_mfma_f32_16x16x32_bf16 v[54:57], v[130:133], v[204:207], v[54:57]
	v_mfma_f32_16x16x32_bf16 v[50:53], v[158:161], v[204:207], v[50:53]
	v_mfma_f32_16x16x32_bf16 v[38:41], v[130:133], v[212:215], v[38:41]
	v_mfma_f32_16x16x32_bf16 v[34:37], v[158:161], v[212:215], v[34:37]
	v_mfma_f32_16x16x32_bf16 v[22:25], v[130:133], v[240:243], v[22:25]
	v_mfma_f32_16x16x32_bf16 v[18:21], v[158:161], v[240:243], v[18:21]
	v_mfma_f32_16x16x32_bf16 v[62:65], v[154:157], v[200:203], v[62:65]
	v_mfma_f32_16x16x32_bf16 v[58:61], v[162:165], v[200:203], v[58:61]
	v_mfma_f32_16x16x32_bf16 v[54:57], v[154:157], v[208:211], v[54:57]
	v_mfma_f32_16x16x32_bf16 v[50:53], v[162:165], v[208:211], v[50:53]
	v_mfma_f32_16x16x32_bf16 v[38:41], v[154:157], v[236:239], v[38:41]
	v_mfma_f32_16x16x32_bf16 v[34:37], v[162:165], v[236:239], v[34:37]
	v_mfma_f32_16x16x32_bf16 v[22:25], v[154:157], v[248:251], v[22:25]
	v_mfma_f32_16x16x32_bf16 v[18:21], v[162:165], v[248:251], v[18:21]
	v_mfma_f32_16x16x32_bf16 v[46:49], v[166:169], v[196:199], v[46:49]
	v_mfma_f32_16x16x32_bf16 v[42:45], v[174:177], v[196:199], v[42:45]
	v_mfma_f32_16x16x32_bf16 v[30:33], v[166:169], v[204:207], v[30:33]
	v_mfma_f32_16x16x32_bf16 v[26:29], v[174:177], v[204:207], v[26:29]
	v_mfma_f32_16x16x32_bf16 v[14:17], v[166:169], v[212:215], v[14:17]
	v_mfma_f32_16x16x32_bf16 v[10:13], v[174:177], v[212:215], v[10:13]
	v_mfma_f32_16x16x32_bf16 v[6:9], v[166:169], v[240:243], v[6:9]
	v_mfma_f32_16x16x32_bf16 v[2:5], v[174:177], v[240:243], v[2:5]
	v_mfma_f32_16x16x32_bf16 v[46:49], v[170:173], v[200:203], v[46:49]
	v_mfma_f32_16x16x32_bf16 v[42:45], v[184:187], v[200:203], v[42:45]
	v_mfma_f32_16x16x32_bf16 v[30:33], v[170:173], v[208:211], v[30:33]
	v_mfma_f32_16x16x32_bf16 v[26:29], v[184:187], v[208:211], v[26:29]
	v_mfma_f32_16x16x32_bf16 v[14:17], v[170:173], v[236:239], v[14:17]
	v_mfma_f32_16x16x32_bf16 v[10:13], v[184:187], v[236:239], v[10:13]
	v_mfma_f32_16x16x32_bf16 v[6:9], v[170:173], v[248:251], v[6:9]
	v_mfma_f32_16x16x32_bf16 v[2:5], v[184:187], v[248:251], v[2:5]
	s_barrier
; #define PG8_STAGEA(bufoff, gbase, voff) do { _Pragma("unroll") for (int _i = 0; _i < 2; ++_i) \
;         __builtin_amdgcn_global_load_lds((const unsigned*)((const char*)(gbase) + (voff)[_i]), (LAS unsigned*)(lds + (bufoff) + ldsw + _i * 8192), 16, 0, 0); } while (0)
; #define PG8_LDA(dst, b, h) do { _Pragma("unroll") for (int m = 0; m < 4; ++m) _Pragma("unroll") for (int k = 0; k < 2; ++k) dst[m][k] = *(const LAS bf16x8*)(lds + PG8_SA(b, h) + aoff + m * 2048 + k * 1024); } while (0)
; #define PG8_LDB(dst, b, h) do { _Pragma("unroll") for (int n = 0; n < 2; ++n) _Pragma("unroll") for (int k = 0; k < 2; ++k) dst[n][k] = *(const LAS bf16x8*)(lds + PG8_SB(b, h) + boff + n * 2048 + k * 1024); } while (0)
; #define PG8_MMA(ai, bj, At, Bt) do { __builtin_amdgcn_s_setprio(3); _Pragma("unroll") for (int m = 0; m < 4; ++m) _Pragma("unroll") for (int n = 0; n < 2; ++n) _Pragma("unroll") for (int k = 0; k < 2; ++k) \
;         acc[ai][bj][m][n] = __builtin_amdgcn_mfma_f32_16x16x32_bf16(Bt[n][k], At[m][k], acc[ai][bj][m][n], 0, 0, 0); __builtin_amdgcn_s_setprio(0); } while (0)
; #define PG8_WAIT_V(n) asm volatile("s_waitcnt vmcnt(" #n ")" ::: "memory")
; #define PG8_WAIT_L(n) asm volatile("s_waitcnt lgkmcnt(" #n ")" ::: "memory")
; #define PG8_BAR __builtin_amdgcn_s_barrier()
; #define PG8_SCHED __builtin_amdgcn_sched_barrier(0)
; template <class Epi, int PARTS>
; __device__ __forceinline__ void gemm_phase(LAS unsigned char* lds, const Gemm g, const StaticOrder& S, const Epi& E) {
;     ...
;             PG8_LDB(B0, 1, 0); PG8_LDB(B1, 1, 1); PG8_SCHED; PG8_LDA(At, 1, 0); PG8_STAGEA(PG8_SA(0, 1), a2 + hstepA, voffA);
;             PG8_WAIT_V(8); PG8_WAIT_L(0); PG8_BAR; PG8_MMA(0, 0, At, B0); PG8_MMA(0, 1, At, B1); PG8_BAR; PG8_SCHED;
	s_add_i32 s34, 0, 0x18000
	v_add_u32_e32 v0, s34, v143
	s_add_i32 s35, 0, 0x1c000
	ds_read_b128 v[130:133], v0
	ds_read_b128 v[154:157], v0 offset:1024
	ds_read_b128 v[158:161], v0 offset:2048
	ds_read_b128 v[162:165], v0 offset:3072
	v_add_u32_e32 v0, s35, v143
	ds_read_b128 v[166:169], v0
	ds_read_b128 v[170:173], v0 offset:1024
	ds_read_b128 v[174:177], v0 offset:2048
	ds_read_b128 v[184:187], v0 offset:3072
	s_add_u32 s60, s66, 0x2000
	s_addc_u32 s61, s67, 0
	s_mov_b32 m0, s80
	v_lshl_add_u64 v[224:225], s[60:61], 0, v[140:141]
	ds_read_b128 v[196:199], v183 offset:32768
	ds_read_b128 v[200:203], v183 offset:33792
	ds_read_b128 v[204:207], v183 offset:34816
	ds_read_b128 v[208:211], v183 offset:35840
	ds_read_b128 v[212:215], v183 offset:36864
	ds_read_b128 v[236:239], v183 offset:37888
	ds_read_b128 v[240:243], v183 offset:38912
	ds_read_b128 v[248:251], v183 offset:39936
	global_load_lds_dwordx4 v[224:225], off
	v_lshl_add_u64 v[224:225], s[60:61], 0, v[136:137]
	s_mov_b32 m0, s81
	s_nop 0
	global_load_lds_dwordx4 v[224:225], off
	s_waitcnt vmcnt(8)
	s_waitcnt lgkmcnt(0)
	s_barrier
	s_waitcnt lgkmcnt(0)
	v_mfma_f32_16x16x32_bf16 v[126:129], v[130:133], v[196:199], v[126:129]
	v_mfma_f32_16x16x32_bf16 v[122:125], v[158:161], v[196:199], v[122:125]
	v_mfma_f32_16x16x32_bf16 v[118:121], v[130:133], v[204:207], v[118:121]
	v_mfma_f32_16x16x32_bf16 v[114:117], v[158:161], v[204:207], v[114:117]
	v_mfma_f32_16x16x32_bf16 v[102:105], v[130:133], v[212:215], v[102:105]
	v_mfma_f32_16x16x32_bf16 v[98:101], v[158:161], v[212:215], v[98:101]
	v_mfma_f32_16x16x32_bf16 v[86:89], v[130:133], v[240:243], v[86:89]
	v_mfma_f32_16x16x32_bf16 v[82:85], v[158:161], v[240:243], v[82:85]
	v_mfma_f32_16x16x32_bf16 v[126:129], v[154:157], v[200:203], v[126:129]
	v_mfma_f32_16x16x32_bf16 v[122:125], v[162:165], v[200:203], v[122:125]
	v_mfma_f32_16x16x32_bf16 v[118:121], v[154:157], v[208:211], v[118:121]
	v_mfma_f32_16x16x32_bf16 v[114:117], v[162:165], v[208:211], v[114:117]
	v_mfma_f32_16x16x32_bf16 v[102:105], v[154:157], v[236:239], v[102:105]
	v_mfma_f32_16x16x32_bf16 v[98:101], v[162:165], v[236:239], v[98:101]
	v_mfma_f32_16x16x32_bf16 v[86:89], v[154:157], v[248:251], v[86:89]
	v_mfma_f32_16x16x32_bf16 v[82:85], v[162:165], v[248:251], v[82:85]
	v_mfma_f32_16x16x32_bf16 v[110:113], v[166:169], v[196:199], v[110:113]
	v_mfma_f32_16x16x32_bf16 v[106:109], v[174:177], v[196:199], v[106:109]
	v_mfma_f32_16x16x32_bf16 v[94:97], v[166:169], v[204:207], v[94:97]
	v_mfma_f32_16x16x32_bf16 v[90:93], v[174:177], v[204:207], v[90:93]
	v_mfma_f32_16x16x32_bf16 v[78:81], v[166:169], v[212:215], v[78:81]
	v_mfma_f32_16x16x32_bf16 v[74:77], v[174:177], v[212:215], v[74:77]
	v_mfma_f32_16x16x32_bf16 v[70:73], v[166:169], v[240:243], v[70:73]
	v_mfma_f32_16x16x32_bf16 v[66:69], v[174:177], v[240:243], v[66:69]
	v_mfma_f32_16x16x32_bf16 v[110:113], v[170:173], v[200:203], v[110:113]
	v_mfma_f32_16x16x32_bf16 v[106:109], v[184:187], v[200:203], v[106:109]
	v_mfma_f32_16x16x32_bf16 v[94:97], v[170:173], v[208:211], v[94:97]
	v_mfma_f32_16x16x32_bf16 v[90:93], v[184:187], v[208:211], v[90:93]
	v_mfma_f32_16x16x32_bf16 v[78:81], v[170:173], v[236:239], v[78:81]
	v_mfma_f32_16x16x32_bf16 v[74:77], v[184:187], v[236:239], v[74:77]
	v_mfma_f32_16x16x32_bf16 v[70:73], v[170:173], v[248:251], v[70:73]
	v_mfma_f32_16x16x32_bf16 v[66:69], v[184:187], v[248:251], v[66:69]
	s_barrier
; #define PG8_STAGE(bufoff, gbase, voff) do { _Pragma("unroll") for (int _i = 0; _i < 2; ++_i) \
;         __builtin_amdgcn_global_load_lds((const unsigned*)((const char*)(gbase) + (voff)[_i]), (LAS unsigned*)(lds + (bufoff) + ldsw + _i * 8192), 16, 0, 0); } while (0)
; #define PG8_STAGEA(bufoff, gbase, voff) do { _Pragma("unroll") for (int _i = 0; _i < 2; ++_i) \
;         __builtin_amdgcn_global_load_lds((const unsigned*)((const char*)(gbase) + (voff)[_i]), (LAS unsigned*)(lds + (bufoff) + ldsw + _i * 8192), 16, 0, 0); } while (0)
; #define PG8_LDA(dst, b, h) do { _Pragma("unroll") for (int m = 0; m < 4; ++m) _Pragma("unroll") for (int k = 0; k < 2; ++k) dst[m][k] = *(const LAS bf16x8*)(lds + PG8_SA(b, h) + aoff + m * 2048 + k * 1024); } while (0)
; #define PG8_MMA(ai, bj, At, Bt) do { __builtin_amdgcn_s_setprio(3); _Pragma("unroll") for (int m = 0; m < 4; ++m) _Pragma("unroll") for (int n = 0; n < 2; ++n) _Pragma("unroll") for (int k = 0; k < 2; ++k) \
;         acc[ai][bj][m][n] = __builtin_amdgcn_mfma_f32_16x16x32_bf16(Bt[n][k], At[m][k], acc[ai][bj][m][n], 0, 0, 0); __builtin_amdgcn_s_setprio(0); } while (0)
; #define PG8_WAIT_V(n) asm volatile("s_waitcnt vmcnt(" #n ")" ::: "memory")
; #define PG8_WAIT_L(n) asm volatile("s_waitcnt lgkmcnt(" #n ")" ::: "memory")
; #define PG8_BAR __builtin_amdgcn_s_barrier()
; #define PG8_SCHED __builtin_amdgcn_sched_barrier(0)
; template <class Epi, int PARTS>
; __device__ __forceinline__ void gemm_phase(LAS unsigned char* lds, const Gemm g, const StaticOrder& S, const Epi& E) {
;     ...
;             PG8_LDA(At, 1, 1); PG8_STAGE(PG8_SB(1, 0), b3, voffB); PG8_STAGE(PG8_SB(1, 1), b3 + hstepB, voffB); PG8_STAGEA(PG8_SA(1, 0), a3, voffA);
;             PG8_WAIT_V(8); PG8_WAIT_L(0); PG8_BAR; PG8_MMA(1, 0, At, B0); PG8_MMA(1, 1, At, B1); PG8_BAR; PG8_SCHED;
;         }
;         if (wr == 0) PG8_BAR;
	s_add_i32 s34, s34, s75
	v_lshl_add_u64 v[178:179], v[178:179], 0, s[72:73]
	s_mov_b32 m0, s34
	ds_read_b128 v[196:199], v183 offset:49152
	ds_read_b128 v[200:203], v183 offset:50176
	ds_read_b128 v[204:207], v183 offset:51200
	ds_read_b128 v[208:211], v183 offset:52224
	ds_read_b128 v[212:215], v183 offset:53248
	ds_read_b128 v[236:239], v183 offset:54272
	ds_read_b128 v[240:243], v183 offset:55296
	ds_read_b128 v[248:251], v183 offset:56320
	global_load_lds_dwordx4 v[178:179], off
	s_add_i32 m0, s34, 0x2000
	s_add_u32 s60, s64, 0x40080
	v_lshl_add_u64 v[178:179], v[188:189], 0, s[72:73]
	s_addc_u32 s61, s65, 0
	s_add_i32 s34, s35, s75
	global_load_lds_dwordx4 v[178:179], off
	v_lshl_add_u64 v[178:179], s[60:61], 0, v[138:139]
	s_mov_b32 m0, s34
	s_nop 0
	global_load_lds_dwordx4 v[178:179], off
	v_lshl_add_u64 v[178:179], s[60:61], 0, v[134:135]
	s_add_i32 m0, s34, 0x2000
	s_nop 0
	global_load_lds_dwordx4 v[178:179], off
	v_lshl_add_u64 v[178:179], v[228:229], 0, s[72:73]
	s_mov_b32 m0, s82
	s_nop 0
	global_load_lds_dwordx4 v[178:179], off
	v_lshl_add_u64 v[178:179], v[230:231], 0, s[72:73]
	s_mov_b32 m0, s83
	s_nop 0
	global_load_lds_dwordx4 v[178:179], off
	s_waitcnt vmcnt(8)
	s_waitcnt lgkmcnt(0)
	s_barrier
	s_waitcnt lgkmcnt(0)
	v_mfma_f32_16x16x32_bf16 v[62:65], v[130:133], v[196:199], v[62:65]
	v_mfma_f32_16x16x32_bf16 v[58:61], v[158:161], v[196:199], v[58:61]
	v_mfma_f32_16x16x32_bf16 v[54:57], v[130:133], v[204:207], v[54:57]
	v_mfma_f32_16x16x32_bf16 v[50:53], v[158:161], v[204:207], v[50:53]
	v_mfma_f32_16x16x32_bf16 v[38:41], v[130:133], v[212:215], v[38:41]
	v_mfma_f32_16x16x32_bf16 v[34:37], v[158:161], v[212:215], v[34:37]
	v_mfma_f32_16x16x32_bf16 v[22:25], v[130:133], v[240:243], v[22:25]
	v_mfma_f32_16x16x32_bf16 v[18:21], v[158:161], v[240:243], v[18:21]
	v_mfma_f32_16x16x32_bf16 v[62:65], v[154:157], v[200:203], v[62:65]
	v_mfma_f32_16x16x32_bf16 v[58:61], v[162:165], v[200:203], v[58:61]
	v_mfma_f32_16x16x32_bf16 v[54:57], v[154:157], v[208:211], v[54:57]
	v_mfma_f32_16x16x32_bf16 v[50:53], v[162:165], v[208:211], v[50:53]
	v_mfma_f32_16x16x32_bf16 v[38:41], v[154:157], v[236:239], v[38:41]
	v_mfma_f32_16x16x32_bf16 v[34:37], v[162:165], v[236:239], v[34:37]
	v_mfma_f32_16x16x32_bf16 v[22:25], v[154:157], v[248:251], v[22:25]
	v_mfma_f32_16x16x32_bf16 v[18:21], v[162:165], v[248:251], v[18:21]
	v_mfma_f32_16x16x32_bf16 v[46:49], v[166:169], v[196:199], v[46:49]
	v_mfma_f32_16x16x32_bf16 v[42:45], v[174:177], v[196:199], v[42:45]
	v_mfma_f32_16x16x32_bf16 v[30:33], v[166:169], v[204:207], v[30:33]
	v_mfma_f32_16x16x32_bf16 v[26:29], v[174:177], v[204:207], v[26:29]
	v_mfma_f32_16x16x32_bf16 v[14:17], v[166:169], v[212:215], v[14:17]
	v_mfma_f32_16x16x32_bf16 v[10:13], v[174:177], v[212:215], v[10:13]
	v_mfma_f32_16x16x32_bf16 v[6:9], v[166:169], v[240:243], v[6:9]
	v_mfma_f32_16x16x32_bf16 v[2:5], v[174:177], v[240:243], v[2:5]
	v_mfma_f32_16x16x32_bf16 v[46:49], v[170:173], v[200:203], v[46:49]
	v_mfma_f32_16x16x32_bf16 v[42:45], v[184:187], v[200:203], v[42:45]
	v_mfma_f32_16x16x32_bf16 v[30:33], v[170:173], v[208:211], v[30:33]
	v_mfma_f32_16x16x32_bf16 v[26:29], v[184:187], v[208:211], v[26:29]
	v_mfma_f32_16x16x32_bf16 v[14:17], v[170:173], v[236:239], v[14:17]
	v_mfma_f32_16x16x32_bf16 v[10:13], v[184:187], v[236:239], v[10:13]
	v_mfma_f32_16x16x32_bf16 v[6:9], v[170:173], v[248:251], v[6:9]
	v_mfma_f32_16x16x32_bf16 v[2:5], v[184:187], v[248:251], v[2:5]
	s_barrier
	s_add_i32 s55, s55, 2
	s_add_u32 s49, s49, 0x100
	s_addc_u32 s53, s53, 0
	s_cmp_gt_u32 s55, 13
	s_mov_b64 s[60:61], s[62:63]
	s_cbranch_scc0 .LBB0_379
	s_setprio 0
	s_and_b64 vcc, exec, s[44:45]
	s_cbranch_vccz .LBB0_382
	s_barrier

; #define PG8_STAGEA(bufoff, gbase, voff) do { _Pragma("unroll") for (int _i = 0; _i < 2; ++_i) \
;         __builtin_amdgcn_global_load_lds((const unsigned*)((const char*)(gbase) + (voff)[_i]), (LAS unsigned*)(lds + (bufoff) + ldsw + _i * 8192), 16, 0, 0); } while (0)
; #define PG8_LDA(dst, b, h) do { _Pragma("unroll") for (int m = 0; m < 4; ++m) _Pragma("unroll") for (int k = 0; k < 2; ++k) dst[m][k] = *(const LAS bf16x8*)(lds + PG8_SA(b, h) + aoff + m * 2048 + k * 1024); } while (0)
; #define PG8_LDB(dst, b, h) do { _Pragma("unroll") for (int n = 0; n < 2; ++n) _Pragma("unroll") for (int k = 0; k < 2; ++k) dst[n][k] = *(const LAS bf16x8*)(lds + PG8_SB(b, h) + boff + n * 2048 + k * 1024); } while (0)
; #define PG8_SCHED __builtin_amdgcn_sched_barrier(0)
; template <class Epi, int PARTS>
; __device__ __forceinline__ void gemm_phase(LAS unsigned char* lds, const Gemm g, const StaticOrder& S, const Epi& E) {
;     ...
;         const bool has_next = S.next(ui + 1, nxt);
;         const char* nA = has_next ? PG8_UA(nxt) : cA; const char* nB = has_next ? PG8_UB(nxt) : cB;
;         for (int t = 0; t < nt; t += 2) {
;             const bool last = (t == nt - 2);
;             const char* a1 = cA + (size_t)(t + 1) * kstep;
;             const char* a2 = last ? nA : cA + (size_t)(t + 2) * kstep; const char* b2 = last ? nB : cB + (size_t)(t + 2) * kstep;
;             const char* a3 = a2 + kstep; const char* b3 = b2 + kstep;
;             PG8_LDB(B0, 0, 0); PG8_LDB(B1, 0, 1); PG8_SCHED; PG8_LDA(At, 0, 0); PG8_STAGEA(PG8_SA(1, 1), a1 + hstepA, voffA);
;     ...
; #pragma unroll
;         for (int a = 0; a < 2; ++a)
; #pragma unroll
;             for (int b = 0; b < 2; ++b)
; #pragma unroll
;                 for (int m = 0; m < 4; ++m)
; #pragma unroll
;                     for (int n = 0; n < 2; ++n) acc[a][b][m][n] = (f32x4){0.f, 0.f, 0.f, 0.f};
.LBB0_402:
	s_ashr_i32 s49, s48, 31
	s_lshl_b64 s[36:37], s[48:49], 19
	s_add_u32 s52, s24, s36
	s_addc_u32 s53, s25, s37
	s_and_b64 s[36:37], s[40:41], exec
	s_cselect_b32 s33, s53, s57
	s_cselect_b32 s36, s52, s56
	s_ashr_i32 s51, s50, 31
	s_lshl_b64 s[54:55], s[50:51], 19
	v_readlane_b32 s34, v254, 50
	s_add_u32 s54, s34, s54
	v_readlane_b32 s34, v254, 52
	s_addc_u32 s55, s34, s55
	s_and_b64 s[60:61], s[40:41], exec
	s_cselect_b32 s37, s55, s59
	s_cselect_b32 s49, s54, s58
	s_add_u32 s51, s58, 0x100
	v_mov_b32_e32 v2, 0
	s_addc_u32 s69, s59, 0
	s_mov_b32 s82, -2
	v_mov_b32_e32 v3, v2
	v_mov_b32_e32 v4, v2
	v_mov_b32_e32 v5, v2
	v_mov_b32_e32 v6, v2
	v_mov_b32_e32 v7, v2
	v_mov_b32_e32 v8, v2
	v_mov_b32_e32 v9, v2
	v_mov_b32_e32 v18, v2
	v_mov_b32_e32 v19, v2
	v_mov_b32_e32 v20, v2
	v_mov_b32_e32 v21, v2
	v_mov_b32_e32 v22, v2
	v_mov_b32_e32 v23, v2
	v_mov_b32_e32 v24, v2
	v_mov_b32_e32 v25, v2
	s_waitcnt vmcnt(0)
	v_mov_b32_e32 v34, v2
	v_mov_b32_e32 v35, v2
	v_mov_b32_e32 v36, v2
	v_mov_b32_e32 v37, v2
	v_mov_b32_e32 v38, v2
	v_mov_b32_e32 v39, v2
	v_mov_b32_e32 v40, v2
	v_mov_b32_e32 v41, v2
	v_mov_b32_e32 v66, v2
	v_mov_b32_e32 v67, v2
	v_mov_b32_e32 v68, v2
	v_mov_b32_e32 v69, v2
	v_mov_b32_e32 v70, v2
	v_mov_b32_e32 v71, v2
	v_mov_b32_e32 v72, v2
	v_mov_b32_e32 v73, v2
	v_mov_b32_e32 v10, v2
	v_mov_b32_e32 v11, v2
	v_mov_b32_e32 v12, v2
	v_mov_b32_e32 v13, v2
	v_mov_b32_e32 v14, v2
	v_mov_b32_e32 v15, v2
	v_mov_b32_e32 v16, v2
	v_mov_b32_e32 v17, v2
	v_mov_b32_e32 v26, v2
	v_mov_b32_e32 v27, v2
	v_mov_b32_e32 v28, v2
	v_mov_b32_e32 v29, v2
	v_mov_b32_e32 v30, v2
	v_mov_b32_e32 v31, v2
	v_mov_b32_e32 v32, v2
	v_mov_b32_e32 v33, v2
	v_mov_b32_e32 v42, v2
	v_mov_b32_e32 v43, v2
	v_mov_b32_e32 v44, v2
	v_mov_b32_e32 v45, v2
	v_mov_b32_e32 v46, v2
	v_mov_b32_e32 v47, v2
	v_mov_b32_e32 v48, v2
	v_mov_b32_e32 v49, v2
	v_mov_b32_e32 v74, v2
	v_mov_b32_e32 v75, v2
	v_mov_b32_e32 v76, v2
	v_mov_b32_e32 v77, v2
	v_mov_b32_e32 v78, v2
	v_mov_b32_e32 v79, v2
	v_mov_b32_e32 v80, v2
	v_mov_b32_e32 v81, v2
	v_mov_b32_e32 v98, v2
	v_mov_b32_e32 v99, v2
	v_mov_b32_e32 v100, v2
	v_mov_b32_e32 v101, v2
	v_mov_b32_e32 v102, v2
	v_mov_b32_e32 v103, v2
	v_mov_b32_e32 v104, v2
	v_mov_b32_e32 v105, v2
	v_mov_b32_e32 v106, v2
	v_mov_b32_e32 v107, v2
	v_mov_b32_e32 v108, v2
	v_mov_b32_e32 v109, v2
	v_mov_b32_e32 v118, v2
	v_mov_b32_e32 v119, v2
	v_mov_b32_e32 v120, v2
	v_mov_b32_e32 v121, v2
	v_mov_b32_e32 v82, v2
	v_mov_b32_e32 v83, v2
	v_mov_b32_e32 v84, v2
	v_mov_b32_e32 v85, v2
	v_mov_b32_e32 v86, v2
	v_mov_b32_e32 v87, v2
	v_mov_b32_e32 v88, v2
	v_mov_b32_e32 v89, v2
	v_mov_b32_e32 v50, v2
	v_mov_b32_e32 v51, v2
	v_mov_b32_e32 v52, v2
	v_mov_b32_e32 v53, v2
	v_mov_b32_e32 v54, v2
	v_mov_b32_e32 v55, v2
	v_mov_b32_e32 v56, v2
	v_mov_b32_e32 v57, v2
	v_mov_b32_e32 v110, v2
	v_mov_b32_e32 v111, v2
	v_mov_b32_e32 v112, v2
	v_mov_b32_e32 v113, v2
	v_mov_b32_e32 v114, v2
	v_mov_b32_e32 v115, v2
	v_mov_b32_e32 v116, v2
	v_mov_b32_e32 v117, v2
	v_mov_b32_e32 v122, v2
	v_mov_b32_e32 v123, v2
	v_mov_b32_e32 v124, v2
	v_mov_b32_e32 v125, v2
	v_mov_b32_e32 v126, v2
	v_mov_b32_e32 v127, v2
	v_mov_b32_e32 v128, v2
	v_mov_b32_e32 v129, v2
	v_mov_b32_e32 v90, v2
	v_mov_b32_e32 v91, v2
	v_mov_b32_e32 v92, v2
	v_mov_b32_e32 v93, v2
	v_mov_b32_e32 v94, v2
	v_mov_b32_e32 v95, v2
	v_mov_b32_e32 v96, v2
	v_mov_b32_e32 v97, v2
	v_mov_b32_e32 v58, v2
	v_mov_b32_e32 v59, v2
	v_mov_b32_e32 v60, v2
	v_mov_b32_e32 v61, v2
	v_mov_b32_e32 v62, v2
	v_mov_b32_e32 v63, v2
	v_mov_b32_e32 v64, v2
	v_mov_b32_e32 v65, v2
	v_readfirstlane_b32 s99, v216
	s_cmp_lt_u32 s99, 0x100
	s_cbranch_scc1 .Lgprio5
	s_setprio 1
.Lgprio5:
.LBB0_403:
	s_add_u32 s58, s56, 0x100
	s_addc_u32 s59, s57, 0
	s_add_i32 s34, 0, 0x10000
	s_cmp_eq_u32 s82, 12
	s_cselect_b32 s63, s33, s59
	s_cselect_b32 s62, s36, s58
	v_add_u32_e32 v0, s34, v151
	s_cselect_b32 s61, s37, s69
	s_cselect_b32 s60, s49, s51
	s_add_i32 s35, 0, 0x14000
	ds_read_b128 v[130:133], v0
	ds_read_b128 v[134:137], v0 offset:1024
	ds_read_b128 v[138:141], v0 offset:2048
	ds_read_b128 v[164:167], v0 offset:3072
	v_add_u32_e32 v0, s35, v151
	ds_read_b128 v[168:171], v0
	ds_read_b128 v[172:175], v0 offset:1024
	ds_read_b128 v[176:179], v0 offset:2048
	ds_read_b128 v[180:183], v0 offset:3072
	v_lshl_add_u64 v[160:161], s[56:57], 0, v[156:157]
	s_add_i32 m0, s47, 0xc000
	ds_read_b128 v[184:187], v163
	ds_read_b128 v[196:199], v163 offset:1024
	ds_read_b128 v[200:203], v163 offset:2048
	ds_read_b128 v[204:207], v163 offset:3072
	ds_read_b128 v[208:211], v163 offset:4096
	ds_read_b128 v[212:215], v163 offset:5120
	ds_read_b128 v[236:239], v163 offset:6144
	ds_read_b128 v[240:243], v163 offset:7168
	global_load_lds_dwordx4 v[160:161], off
	v_lshl_add_u64 v[160:161], s[56:57], 0, v[158:159]
	s_add_i32 m0, s47, 0xe000
	s_nop 0
	global_load_lds_dwordx4 v[160:161], off
	s_waitcnt vmcnt(8)
	s_waitcnt lgkmcnt(0)
	s_barrier
; #define PG8_STAGE(bufoff, gbase, voff) do { _Pragma("unroll") for (int _i = 0; _i < 2; ++_i) \
;         __builtin_amdgcn_global_load_lds((const unsigned*)((const char*)(gbase) + (voff)[_i]), (LAS unsigned*)(lds + (bufoff) + ldsw + _i * 8192), 16, 0, 0); } while (0)
; #define PG8_STAGEA(bufoff, gbase, voff) do { _Pragma("unroll") for (int _i = 0; _i < 2; ++_i) \
;         __builtin_amdgcn_global_load_lds((const unsigned*)((const char*)(gbase) + (voff)[_i]), (LAS unsigned*)(lds + (bufoff) + ldsw + _i * 8192), 16, 0, 0); } while (0)
; #define PG8_LDA(dst, b, h) do { _Pragma("unroll") for (int m = 0; m < 4; ++m) _Pragma("unroll") for (int k = 0; k < 2; ++k) dst[m][k] = *(const LAS bf16x8*)(lds + PG8_SA(b, h) + aoff + m * 2048 + k * 1024); } while (0)
; #define PG8_MMA(ai, bj, At, Bt) do { __builtin_amdgcn_s_setprio(3); _Pragma("unroll") for (int m = 0; m < 4; ++m) _Pragma("unroll") for (int n = 0; n < 2; ++n) _Pragma("unroll") for (int k = 0; k < 2; ++k) \
;         acc[ai][bj][m][n] = __builtin_amdgcn_mfma_f32_16x16x32_bf16(Bt[n][k], At[m][k], acc[ai][bj][m][n], 0, 0, 0); __builtin_amdgcn_s_setprio(0); } while (0)
; #define PG8_WAIT_V(n) asm volatile("s_waitcnt vmcnt(" #n ")" ::: "memory")
; #define PG8_WAIT_L(n) asm volatile("s_waitcnt lgkmcnt(" #n ")" ::: "memory")
; #define PG8_BAR __builtin_amdgcn_s_barrier()
; #define PG8_SCHED __builtin_amdgcn_sched_barrier(0)
; template <class Epi, int PARTS>
; __device__ __forceinline__ void gemm_phase(LAS unsigned char* lds, const Gemm g, const StaticOrder& S, const Epi& E) {
;     ...
;             PG8_WAIT_V(8); PG8_WAIT_L(0); PG8_BAR; PG8_MMA(0, 0, At, B0); PG8_MMA(0, 1, At, B1); PG8_BAR; PG8_SCHED;
;             PG8_LDA(At, 0, 1); PG8_STAGE(PG8_SB(0, 0), b2, voffB); PG8_STAGE(PG8_SB(0, 1), b2 + hstepB, voffB); PG8_STAGEA(PG8_SA(0, 0), a2, voffA);
;             PG8_WAIT_V(8); PG8_WAIT_L(0); PG8_BAR; PG8_MMA(1, 0, At, B0); PG8_MMA(1, 1, At, B1); PG8_BAR; PG8_SCHED;
	s_waitcnt lgkmcnt(0)
	v_mfma_f32_16x16x32_bf16 v[62:65], v[130:133], v[184:187], v[62:65]
	v_mfma_f32_16x16x32_bf16 v[58:61], v[138:141], v[184:187], v[58:61]
	v_mfma_f32_16x16x32_bf16 v[94:97], v[130:133], v[200:203], v[94:97]
	v_mfma_f32_16x16x32_bf16 v[90:93], v[138:141], v[200:203], v[90:93]
	v_mfma_f32_16x16x32_bf16 v[126:129], v[130:133], v[208:211], v[126:129]
	v_mfma_f32_16x16x32_bf16 v[122:125], v[138:141], v[208:211], v[122:125]
	v_mfma_f32_16x16x32_bf16 v[114:117], v[130:133], v[236:239], v[114:117]
	v_mfma_f32_16x16x32_bf16 v[110:113], v[138:141], v[236:239], v[110:113]
	v_mfma_f32_16x16x32_bf16 v[62:65], v[134:137], v[196:199], v[62:65]
	v_mfma_f32_16x16x32_bf16 v[58:61], v[164:167], v[196:199], v[58:61]
	v_mfma_f32_16x16x32_bf16 v[94:97], v[134:137], v[204:207], v[94:97]
	v_mfma_f32_16x16x32_bf16 v[90:93], v[164:167], v[204:207], v[90:93]
	v_mfma_f32_16x16x32_bf16 v[126:129], v[134:137], v[212:215], v[126:129]
	v_mfma_f32_16x16x32_bf16 v[122:125], v[164:167], v[212:215], v[122:125]
	v_mfma_f32_16x16x32_bf16 v[114:117], v[134:137], v[240:243], v[114:117]
	v_mfma_f32_16x16x32_bf16 v[110:113], v[164:167], v[240:243], v[110:113]
	v_mfma_f32_16x16x32_bf16 v[54:57], v[168:171], v[184:187], v[54:57]
	v_mfma_f32_16x16x32_bf16 v[50:53], v[176:179], v[184:187], v[50:53]
	v_mfma_f32_16x16x32_bf16 v[86:89], v[168:171], v[200:203], v[86:89]
	v_mfma_f32_16x16x32_bf16 v[82:85], v[176:179], v[200:203], v[82:85]
	v_mfma_f32_16x16x32_bf16 v[118:121], v[168:171], v[208:211], v[118:121]
	v_mfma_f32_16x16x32_bf16 v[106:109], v[176:179], v[208:211], v[106:109]
	v_mfma_f32_16x16x32_bf16 v[102:105], v[168:171], v[236:239], v[102:105]
	v_mfma_f32_16x16x32_bf16 v[98:101], v[176:179], v[236:239], v[98:101]
	v_mfma_f32_16x16x32_bf16 v[54:57], v[172:175], v[196:199], v[54:57]
	v_mfma_f32_16x16x32_bf16 v[50:53], v[180:183], v[196:199], v[50:53]
	v_mfma_f32_16x16x32_bf16 v[86:89], v[172:175], v[204:207], v[86:89]
	v_mfma_f32_16x16x32_bf16 v[82:85], v[180:183], v[204:207], v[82:85]
	v_mfma_f32_16x16x32_bf16 v[118:121], v[172:175], v[212:215], v[118:121]
	v_mfma_f32_16x16x32_bf16 v[106:109], v[180:183], v[212:215], v[106:109]
	v_mfma_f32_16x16x32_bf16 v[102:105], v[172:175], v[240:243], v[102:105]
	v_mfma_f32_16x16x32_bf16 v[98:101], v[180:183], v[240:243], v[98:101]
	s_barrier
	s_add_i32 s34, s34, s65
	v_lshl_add_u64 v[160:161], s[60:61], 0, v[146:147]
	s_mov_b32 m0, s34
	ds_read_b128 v[184:187], v163 offset:16384
	ds_read_b128 v[196:199], v163 offset:17408
	ds_read_b128 v[200:203], v163 offset:18432
	ds_read_b128 v[204:207], v163 offset:19456
	ds_read_b128 v[208:211], v163 offset:20480
	ds_read_b128 v[212:215], v163 offset:21504
	ds_read_b128 v[236:239], v163 offset:22528
	ds_read_b128 v[240:243], v163 offset:23552
	global_load_lds_dwordx4 v[160:161], off
	s_add_i32 m0, s34, 0x2000
	s_add_u32 s56, s60, 0x40000
	v_lshl_add_u64 v[188:189], s[60:61], 0, v[142:143]
	s_addc_u32 s57, s61, 0
	s_add_i32 s34, s35, s65
	global_load_lds_dwordx4 v[188:189], off
	v_lshl_add_u64 v[224:225], s[56:57], 0, v[146:147]
	s_mov_b32 m0, s34
	v_lshl_add_u64 v[228:229], s[62:63], 0, v[144:145]
	global_load_lds_dwordx4 v[224:225], off
	v_lshl_add_u64 v[224:225], s[56:57], 0, v[142:143]
	s_add_i32 m0, s34, 0x2000
	s_nop 0
	global_load_lds_dwordx4 v[224:225], off
	v_lshl_add_u64 v[224:225], s[62:63], 0, v[148:149]
	s_mov_b32 m0, s47
	s_nop 0
	global_load_lds_dwordx4 v[224:225], off
	s_mov_b32 m0, s66
	s_nop 0
	global_load_lds_dwordx4 v[228:229], off
	s_waitcnt vmcnt(8)
	s_waitcnt lgkmcnt(0)
	s_barrier
	s_waitcnt lgkmcnt(0)
	v_mfma_f32_16x16x32_bf16 v[78:81], v[130:133], v[184:187], v[78:81]
	v_mfma_f32_16x16x32_bf16 v[74:77], v[138:141], v[184:187], v[74:77]
	v_mfma_f32_16x16x32_bf16 v[46:49], v[130:133], v[200:203], v[46:49]
	v_mfma_f32_16x16x32_bf16 v[42:45], v[138:141], v[200:203], v[42:45]
	v_mfma_f32_16x16x32_bf16 v[30:33], v[130:133], v[208:211], v[30:33]
	v_mfma_f32_16x16x32_bf16 v[26:29], v[138:141], v[208:211], v[26:29]
	v_mfma_f32_16x16x32_bf16 v[14:17], v[130:133], v[236:239], v[14:17]
	v_mfma_f32_16x16x32_bf16 v[10:13], v[138:141], v[236:239], v[10:13]
	v_mfma_f32_16x16x32_bf16 v[78:81], v[134:137], v[196:199], v[78:81]
	v_mfma_f32_16x16x32_bf16 v[74:77], v[164:167], v[196:199], v[74:77]
	v_mfma_f32_16x16x32_bf16 v[46:49], v[134:137], v[204:207], v[46:49]
	v_mfma_f32_16x16x32_bf16 v[42:45], v[164:167], v[204:207], v[42:45]
	v_mfma_f32_16x16x32_bf16 v[30:33], v[134:137], v[212:215], v[30:33]
	v_mfma_f32_16x16x32_bf16 v[26:29], v[164:167], v[212:215], v[26:29]
	v_mfma_f32_16x16x32_bf16 v[14:17], v[134:137], v[240:243], v[14:17]
	v_mfma_f32_16x16x32_bf16 v[10:13], v[164:167], v[240:243], v[10:13]
	v_mfma_f32_16x16x32_bf16 v[70:73], v[168:171], v[184:187], v[70:73]
	v_mfma_f32_16x16x32_bf16 v[66:69], v[176:179], v[184:187], v[66:69]
	v_mfma_f32_16x16x32_bf16 v[38:41], v[168:171], v[200:203], v[38:41]
	v_mfma_f32_16x16x32_bf16 v[34:37], v[176:179], v[200:203], v[34:37]
	v_mfma_f32_16x16x32_bf16 v[22:25], v[168:171], v[208:211], v[22:25]
	v_mfma_f32_16x16x32_bf16 v[18:21], v[176:179], v[208:211], v[18:21]
	v_mfma_f32_16x16x32_bf16 v[6:9], v[168:171], v[236:239], v[6:9]
	v_mfma_f32_16x16x32_bf16 v[2:5], v[176:179], v[236:239], v[2:5]
	v_mfma_f32_16x16x32_bf16 v[70:73], v[172:175], v[196:199], v[70:73]
	v_mfma_f32_16x16x32_bf16 v[66:69], v[180:183], v[196:199], v[66:69]
	v_mfma_f32_16x16x32_bf16 v[38:41], v[172:175], v[204:207], v[38:41]
	v_mfma_f32_16x16x32_bf16 v[34:37], v[180:183], v[204:207], v[34:37]
	v_mfma_f32_16x16x32_bf16 v[22:25], v[172:175], v[212:215], v[22:25]
	v_mfma_f32_16x16x32_bf16 v[18:21], v[180:183], v[212:215], v[18:21]
	v_mfma_f32_16x16x32_bf16 v[6:9], v[172:175], v[240:243], v[6:9]
	v_mfma_f32_16x16x32_bf16 v[2:5], v[180:183], v[240:243], v[2:5]
	s_barrier
; #define PG8_STAGEA(bufoff, gbase, voff) do { _Pragma("unroll") for (int _i = 0; _i < 2; ++_i) \
;         __builtin_amdgcn_global_load_lds((const unsigned*)((const char*)(gbase) + (voff)[_i]), (LAS unsigned*)(lds + (bufoff) + ldsw + _i * 8192), 16, 0, 0); } while (0)
; #define PG8_LDA(dst, b, h) do { _Pragma("unroll") for (int m = 0; m < 4; ++m) _Pragma("unroll") for (int k = 0; k < 2; ++k) dst[m][k] = *(const LAS bf16x8*)(lds + PG8_SA(b, h) + aoff + m * 2048 + k * 1024); } while (0)
; #define PG8_LDB(dst, b, h) do { _Pragma("unroll") for (int n = 0; n < 2; ++n) _Pragma("unroll") for (int k = 0; k < 2; ++k) dst[n][k] = *(const LAS bf16x8*)(lds + PG8_SB(b, h) + boff + n * 2048 + k * 1024); } while (0)
; #define PG8_MMA(ai, bj, At, Bt) do { __builtin_amdgcn_s_setprio(3); _Pragma("unroll") for (int m = 0; m < 4; ++m) _Pragma("unroll") for (int n = 0; n < 2; ++n) _Pragma("unroll") for (int k = 0; k < 2; ++k) \
;         acc[ai][bj][m][n] = __builtin_amdgcn_mfma_f32_16x16x32_bf16(Bt[n][k], At[m][k], acc[ai][bj][m][n], 0, 0, 0); __builtin_amdgcn_s_setprio(0); } while (0)
; #define PG8_WAIT_V(n) asm volatile("s_waitcnt vmcnt(" #n ")" ::: "memory")
; #define PG8_WAIT_L(n) asm volatile("s_waitcnt lgkmcnt(" #n ")" ::: "memory")
; #define PG8_BAR __builtin_amdgcn_s_barrier()
; #define PG8_SCHED __builtin_amdgcn_sched_barrier(0)
; template <class Epi, int PARTS>
; __device__ __forceinline__ void gemm_phase(LAS unsigned char* lds, const Gemm g, const StaticOrder& S, const Epi& E) {
;     ...
;             PG8_LDB(B0, 1, 0); PG8_LDB(B1, 1, 1); PG8_SCHED; PG8_LDA(At, 1, 0); PG8_STAGEA(PG8_SA(0, 1), a2 + hstepA, voffA);
;             PG8_WAIT_V(8); PG8_WAIT_L(0); PG8_BAR; PG8_MMA(0, 0, At, B0); PG8_MMA(0, 1, At, B1); PG8_BAR; PG8_SCHED;
	s_add_i32 s34, 0, 0x18000
	v_add_u32_e32 v0, s34, v151
	s_add_i32 s35, 0, 0x1c000
	ds_read_b128 v[130:133], v0
	ds_read_b128 v[134:137], v0 offset:1024
	ds_read_b128 v[138:141], v0 offset:2048
	ds_read_b128 v[164:167], v0 offset:3072
	v_add_u32_e32 v0, s35, v151
	ds_read_b128 v[168:171], v0
	ds_read_b128 v[172:175], v0 offset:1024
	ds_read_b128 v[176:179], v0 offset:2048
	ds_read_b128 v[180:183], v0 offset:3072
	s_add_u32 s56, s62, 0x2000
	s_addc_u32 s57, s63, 0
	s_mov_b32 m0, s67
	v_lshl_add_u64 v[230:231], s[56:57], 0, v[148:149]
	ds_read_b128 v[184:187], v163 offset:32768
	ds_read_b128 v[196:199], v163 offset:33792
	ds_read_b128 v[200:203], v163 offset:34816
	ds_read_b128 v[204:207], v163 offset:35840
	ds_read_b128 v[208:211], v163 offset:36864
	ds_read_b128 v[212:215], v163 offset:37888
	ds_read_b128 v[236:239], v163 offset:38912
	ds_read_b128 v[240:243], v163 offset:39936
	global_load_lds_dwordx4 v[230:231], off
	v_lshl_add_u64 v[230:231], s[56:57], 0, v[144:145]
	s_mov_b32 m0, s74
	s_nop 0
	global_load_lds_dwordx4 v[230:231], off
	s_waitcnt vmcnt(8)
	s_waitcnt lgkmcnt(0)
	s_barrier
	s_waitcnt lgkmcnt(0)
	v_mfma_f32_16x16x32_bf16 v[62:65], v[130:133], v[184:187], v[62:65]
	v_mfma_f32_16x16x32_bf16 v[58:61], v[138:141], v[184:187], v[58:61]
	v_mfma_f32_16x16x32_bf16 v[94:97], v[130:133], v[200:203], v[94:97]
	v_mfma_f32_16x16x32_bf16 v[90:93], v[138:141], v[200:203], v[90:93]
	v_mfma_f32_16x16x32_bf16 v[126:129], v[130:133], v[208:211], v[126:129]
	v_mfma_f32_16x16x32_bf16 v[122:125], v[138:141], v[208:211], v[122:125]
	v_mfma_f32_16x16x32_bf16 v[114:117], v[130:133], v[236:239], v[114:117]
	v_mfma_f32_16x16x32_bf16 v[110:113], v[138:141], v[236:239], v[110:113]
	v_mfma_f32_16x16x32_bf16 v[62:65], v[134:137], v[196:199], v[62:65]
	v_mfma_f32_16x16x32_bf16 v[58:61], v[164:167], v[196:199], v[58:61]
	v_mfma_f32_16x16x32_bf16 v[94:97], v[134:137], v[204:207], v[94:97]
	v_mfma_f32_16x16x32_bf16 v[90:93], v[164:167], v[204:207], v[90:93]
	v_mfma_f32_16x16x32_bf16 v[126:129], v[134:137], v[212:215], v[126:129]
	v_mfma_f32_16x16x32_bf16 v[122:125], v[164:167], v[212:215], v[122:125]
	v_mfma_f32_16x16x32_bf16 v[114:117], v[134:137], v[240:243], v[114:117]
	v_mfma_f32_16x16x32_bf16 v[110:113], v[164:167], v[240:243], v[110:113]
	v_mfma_f32_16x16x32_bf16 v[54:57], v[168:171], v[184:187], v[54:57]
	v_mfma_f32_16x16x32_bf16 v[50:53], v[176:179], v[184:187], v[50:53]
	v_mfma_f32_16x16x32_bf16 v[86:89], v[168:171], v[200:203], v[86:89]
	v_mfma_f32_16x16x32_bf16 v[82:85], v[176:179], v[200:203], v[82:85]
	v_mfma_f32_16x16x32_bf16 v[118:121], v[168:171], v[208:211], v[118:121]
	v_mfma_f32_16x16x32_bf16 v[106:109], v[176:179], v[208:211], v[106:109]
	v_mfma_f32_16x16x32_bf16 v[102:105], v[168:171], v[236:239], v[102:105]
	v_mfma_f32_16x16x32_bf16 v[98:101], v[176:179], v[236:239], v[98:101]
	v_mfma_f32_16x16x32_bf16 v[54:57], v[172:175], v[196:199], v[54:57]
	v_mfma_f32_16x16x32_bf16 v[50:53], v[180:183], v[196:199], v[50:53]
	v_mfma_f32_16x16x32_bf16 v[86:89], v[172:175], v[204:207], v[86:89]
	v_mfma_f32_16x16x32_bf16 v[82:85], v[180:183], v[204:207], v[82:85]
	v_mfma_f32_16x16x32_bf16 v[118:121], v[172:175], v[212:215], v[118:121]
	v_mfma_f32_16x16x32_bf16 v[106:109], v[180:183], v[212:215], v[106:109]
	v_mfma_f32_16x16x32_bf16 v[102:105], v[172:175], v[240:243], v[102:105]
	v_mfma_f32_16x16x32_bf16 v[98:101], v[180:183], v[240:243], v[98:101]
	s_barrier
; #define PG8_STAGE(bufoff, gbase, voff) do { _Pragma("unroll") for (int _i = 0; _i < 2; ++_i) \
;         __builtin_amdgcn_global_load_lds((const unsigned*)((const char*)(gbase) + (voff)[_i]), (LAS unsigned*)(lds + (bufoff) + ldsw + _i * 8192), 16, 0, 0); } while (0)
; #define PG8_STAGEA(bufoff, gbase, voff) do { _Pragma("unroll") for (int _i = 0; _i < 2; ++_i) \
;         __builtin_amdgcn_global_load_lds((const unsigned*)((const char*)(gbase) + (voff)[_i]), (LAS unsigned*)(lds + (bufoff) + ldsw + _i * 8192), 16, 0, 0); } while (0)
; #define PG8_LDA(dst, b, h) do { _Pragma("unroll") for (int m = 0; m < 4; ++m) _Pragma("unroll") for (int k = 0; k < 2; ++k) dst[m][k] = *(const LAS bf16x8*)(lds + PG8_SA(b, h) + aoff + m * 2048 + k * 1024); } while (0)
; #define PG8_MMA(ai, bj, At, Bt) do { __builtin_amdgcn_s_setprio(3); _Pragma("unroll") for (int m = 0; m < 4; ++m) _Pragma("unroll") for (int n = 0; n < 2; ++n) _Pragma("unroll") for (int k = 0; k < 2; ++k) \
;         acc[ai][bj][m][n] = __builtin_amdgcn_mfma_f32_16x16x32_bf16(Bt[n][k], At[m][k], acc[ai][bj][m][n], 0, 0, 0); __builtin_amdgcn_s_setprio(0); } while (0)
; #define PG8_WAIT_V(n) asm volatile("s_waitcnt vmcnt(" #n ")" ::: "memory")
; #define PG8_WAIT_L(n) asm volatile("s_waitcnt lgkmcnt(" #n ")" ::: "memory")
; #define PG8_BAR __builtin_amdgcn_s_barrier()
; #define PG8_SCHED __builtin_amdgcn_sched_barrier(0)
; template <class Epi, int PARTS>
; __device__ __forceinline__ void gemm_phase(LAS unsigned char* lds, const Gemm g, const StaticOrder& S, const Epi& E) {
;     ...
;             PG8_LDA(At, 1, 1); PG8_STAGE(PG8_SB(1, 0), b3, voffB); PG8_STAGE(PG8_SB(1, 1), b3 + hstepB, voffB); PG8_STAGEA(PG8_SA(1, 0), a3, voffA);
;             PG8_WAIT_V(8); PG8_WAIT_L(0); PG8_BAR; PG8_MMA(1, 0, At, B0); PG8_MMA(1, 1, At, B1); PG8_BAR; PG8_SCHED;
;         }
;         if (wr == 0) PG8_BAR;
	s_add_i32 s34, s34, s65
	v_lshl_add_u64 v[160:161], v[160:161], 0, s[72:73]
	s_mov_b32 m0, s34
	ds_read_b128 v[184:187], v163 offset:49152
	ds_read_b128 v[196:199], v163 offset:50176
	ds_read_b128 v[200:203], v163 offset:51200
	ds_read_b128 v[204:207], v163 offset:52224
	ds_read_b128 v[208:211], v163 offset:53248
	ds_read_b128 v[212:215], v163 offset:54272
	ds_read_b128 v[236:239], v163 offset:55296
	ds_read_b128 v[240:243], v163 offset:56320
	global_load_lds_dwordx4 v[160:161], off
	s_add_i32 m0, s34, 0x2000
	s_add_u32 s56, s60, 0x40080
	v_lshl_add_u64 v[160:161], v[188:189], 0, s[72:73]
	s_addc_u32 s57, s61, 0
	s_add_i32 s34, s35, s65
	global_load_lds_dwordx4 v[160:161], off
	v_lshl_add_u64 v[160:161], s[56:57], 0, v[146:147]
	s_mov_b32 m0, s34
	s_nop 0
	global_load_lds_dwordx4 v[160:161], off
	v_lshl_add_u64 v[160:161], s[56:57], 0, v[142:143]
	s_add_i32 m0, s34, 0x2000
	s_nop 0
	global_load_lds_dwordx4 v[160:161], off
	v_lshl_add_u64 v[160:161], v[224:225], 0, s[72:73]
	s_mov_b32 m0, s76
	s_nop 0
	global_load_lds_dwordx4 v[160:161], off
	v_lshl_add_u64 v[160:161], v[228:229], 0, s[72:73]
	s_mov_b32 m0, s77
	s_nop 0
	global_load_lds_dwordx4 v[160:161], off
	s_waitcnt vmcnt(8)
	s_waitcnt lgkmcnt(0)
	s_barrier
	s_waitcnt lgkmcnt(0)
	v_mfma_f32_16x16x32_bf16 v[78:81], v[130:133], v[184:187], v[78:81]
	v_mfma_f32_16x16x32_bf16 v[74:77], v[138:141], v[184:187], v[74:77]
	v_mfma_f32_16x16x32_bf16 v[46:49], v[130:133], v[200:203], v[46:49]
	v_mfma_f32_16x16x32_bf16 v[42:45], v[138:141], v[200:203], v[42:45]
	v_mfma_f32_16x16x32_bf16 v[30:33], v[130:133], v[208:211], v[30:33]
	v_mfma_f32_16x16x32_bf16 v[26:29], v[138:141], v[208:211], v[26:29]
	v_mfma_f32_16x16x32_bf16 v[14:17], v[130:133], v[236:239], v[14:17]
	v_mfma_f32_16x16x32_bf16 v[10:13], v[138:141], v[236:239], v[10:13]
	v_mfma_f32_16x16x32_bf16 v[78:81], v[134:137], v[196:199], v[78:81]
	v_mfma_f32_16x16x32_bf16 v[74:77], v[164:167], v[196:199], v[74:77]
	v_mfma_f32_16x16x32_bf16 v[46:49], v[134:137], v[204:207], v[46:49]
	v_mfma_f32_16x16x32_bf16 v[42:45], v[164:167], v[204:207], v[42:45]
	v_mfma_f32_16x16x32_bf16 v[30:33], v[134:137], v[212:215], v[30:33]
	v_mfma_f32_16x16x32_bf16 v[26:29], v[164:167], v[212:215], v[26:29]
	v_mfma_f32_16x16x32_bf16 v[14:17], v[134:137], v[240:243], v[14:17]
	v_mfma_f32_16x16x32_bf16 v[10:13], v[164:167], v[240:243], v[10:13]
	v_mfma_f32_16x16x32_bf16 v[70:73], v[168:171], v[184:187], v[70:73]
	v_mfma_f32_16x16x32_bf16 v[66:69], v[176:179], v[184:187], v[66:69]
	v_mfma_f32_16x16x32_bf16 v[38:41], v[168:171], v[200:203], v[38:41]
	v_mfma_f32_16x16x32_bf16 v[34:37], v[176:179], v[200:203], v[34:37]
	v_mfma_f32_16x16x32_bf16 v[22:25], v[168:171], v[208:211], v[22:25]
	v_mfma_f32_16x16x32_bf16 v[18:21], v[176:179], v[208:211], v[18:21]
	v_mfma_f32_16x16x32_bf16 v[6:9], v[168:171], v[236:239], v[6:9]
	v_mfma_f32_16x16x32_bf16 v[2:5], v[176:179], v[236:239], v[2:5]
	v_mfma_f32_16x16x32_bf16 v[70:73], v[172:175], v[196:199], v[70:73]
	v_mfma_f32_16x16x32_bf16 v[66:69], v[180:183], v[196:199], v[66:69]
	v_mfma_f32_16x16x32_bf16 v[38:41], v[172:175], v[204:207], v[38:41]
	v_mfma_f32_16x16x32_bf16 v[34:37], v[180:183], v[204:207], v[34:37]
	v_mfma_f32_16x16x32_bf16 v[22:25], v[172:175], v[212:215], v[22:25]
	v_mfma_f32_16x16x32_bf16 v[18:21], v[180:183], v[212:215], v[18:21]
	v_mfma_f32_16x16x32_bf16 v[6:9], v[172:175], v[240:243], v[6:9]
	v_mfma_f32_16x16x32_bf16 v[2:5], v[180:183], v[240:243], v[2:5]
	s_barrier
	s_add_i32 s82, s82, 2
	s_add_u32 s51, s51, 0x100
	s_addc_u32 s69, s69, 0
	s_cmp_gt_u32 s82, 13
	s_mov_b64 s[56:57], s[58:59]
	s_cbranch_scc0 .LBB0_403
	s_setprio 0
	s_and_b64 vcc, exec, s[44:45]
	s_cbranch_vccz .LBB0_406
	s_barrier

; #define PG8_STAGEA(bufoff, gbase, voff) do { _Pragma("unroll") for (int _i = 0; _i < 2; ++_i) \
;         __builtin_amdgcn_global_load_lds((const unsigned*)((const char*)(gbase) + (voff)[_i]), (LAS unsigned*)(lds + (bufoff) + ldsw + _i * 8192), 16, 0, 0); } while (0)
; #define PG8_LDA(dst, b, h) do { _Pragma("unroll") for (int m = 0; m < 4; ++m) _Pragma("unroll") for (int k = 0; k < 2; ++k) dst[m][k] = *(const LAS bf16x8*)(lds + PG8_SA(b, h) + aoff + m * 2048 + k * 1024); } while (0)
; #define PG8_LDB(dst, b, h) do { _Pragma("unroll") for (int n = 0; n < 2; ++n) _Pragma("unroll") for (int k = 0; k < 2; ++k) dst[n][k] = *(const LAS bf16x8*)(lds + PG8_SB(b, h) + boff + n * 2048 + k * 1024); } while (0)
; #define PG8_SCHED __builtin_amdgcn_sched_barrier(0)
; template <class Epi, int PARTS>
; __device__ __forceinline__ void gemm_phase(LAS unsigned char* lds, const Gemm g, const StaticOrder& S, const Epi& E) {
;     ...
;         const bool has_next = S.next(ui + 1, nxt);
;         const char* nA = has_next ? PG8_UA(nxt) : cA; const char* nB = has_next ? PG8_UB(nxt) : cB;
;         for (int t = 0; t < nt; t += 2) {
;             const bool last = (t == nt - 2);
;             const char* a1 = cA + (size_t)(t + 1) * kstep;
;             const char* a2 = last ? nA : cA + (size_t)(t + 2) * kstep; const char* b2 = last ? nB : cB + (size_t)(t + 2) * kstep;
;             const char* a3 = a2 + kstep; const char* b3 = b2 + kstep;
;             PG8_LDB(B0, 0, 0); PG8_LDB(B1, 0, 1); PG8_SCHED; PG8_LDA(At, 0, 0); PG8_STAGEA(PG8_SA(1, 1), a1 + hstepA, voffA);
;     ...
; #pragma unroll
;         for (int a = 0; a < 2; ++a)
; #pragma unroll
;             for (int b = 0; b < 2; ++b)
; #pragma unroll
;                 for (int m = 0; m < 4; ++m)
; #pragma unroll
;                     for (int n = 0; n < 2; ++n) acc[a][b][m][n] = (f32x4){0.f, 0.f, 0.f, 0.f};
.LBB0_437:
	s_ashr_i32 s45, s44, 31
	s_lshl_b64 s[36:37], s[44:45], 19
	s_add_u32 s48, s24, s36
	s_addc_u32 s49, s25, s37
	s_and_b64 s[36:37], s[38:39], exec
	s_cselect_b32 s20, s49, s55
	s_cselect_b32 s36, s48, s54
	s_ashr_i32 s47, s46, 31
	s_lshl_b64 s[50:51], s[46:47], 19
	v_readlane_b32 s34, v254, 50
	s_add_u32 s50, s34, s50
	v_readlane_b32 s34, v254, 52
	s_addc_u32 s51, s34, s51
	s_and_b64 s[58:59], s[38:39], exec
	s_cselect_b32 s37, s51, s57
	s_cselect_b32 s45, s50, s56
	s_add_u32 s47, s56, 0x100
	v_mov_b32_e32 v2, 0
	s_addc_u32 s53, s57, 0
	s_mov_b32 s69, -2
	v_mov_b32_e32 v3, v2
	v_mov_b32_e32 v4, v2
	v_mov_b32_e32 v5, v2
	v_mov_b32_e32 v6, v2
	v_mov_b32_e32 v7, v2
	v_mov_b32_e32 v8, v2
	v_mov_b32_e32 v9, v2
	v_mov_b32_e32 v18, v2
	v_mov_b32_e32 v19, v2
	v_mov_b32_e32 v20, v2
	v_mov_b32_e32 v21, v2
	v_mov_b32_e32 v22, v2
	v_mov_b32_e32 v23, v2
	v_mov_b32_e32 v24, v2
	v_mov_b32_e32 v25, v2
	s_waitcnt vmcnt(0)
	v_mov_b32_e32 v34, v2
	v_mov_b32_e32 v35, v2
	v_mov_b32_e32 v36, v2
	v_mov_b32_e32 v37, v2
	v_mov_b32_e32 v38, v2
	v_mov_b32_e32 v39, v2
	v_mov_b32_e32 v40, v2
	v_mov_b32_e32 v41, v2
	v_mov_b32_e32 v50, v2
	v_mov_b32_e32 v51, v2
	v_mov_b32_e32 v52, v2
	v_mov_b32_e32 v53, v2
	v_mov_b32_e32 v54, v2
	v_mov_b32_e32 v55, v2
	v_mov_b32_e32 v56, v2
	v_mov_b32_e32 v57, v2
	v_mov_b32_e32 v10, v2
	v_mov_b32_e32 v11, v2
	v_mov_b32_e32 v12, v2
	v_mov_b32_e32 v13, v2
	v_mov_b32_e32 v14, v2
	v_mov_b32_e32 v15, v2
	v_mov_b32_e32 v16, v2
	v_mov_b32_e32 v17, v2
	v_mov_b32_e32 v26, v2
	v_mov_b32_e32 v27, v2
	v_mov_b32_e32 v28, v2
	v_mov_b32_e32 v29, v2
	v_mov_b32_e32 v30, v2
	v_mov_b32_e32 v31, v2
	v_mov_b32_e32 v32, v2
	v_mov_b32_e32 v33, v2
	v_mov_b32_e32 v42, v2
	v_mov_b32_e32 v43, v2
	v_mov_b32_e32 v44, v2
	v_mov_b32_e32 v45, v2
	v_mov_b32_e32 v46, v2
	v_mov_b32_e32 v47, v2
	v_mov_b32_e32 v48, v2
	v_mov_b32_e32 v49, v2
	v_mov_b32_e32 v58, v2
	v_mov_b32_e32 v59, v2
	v_mov_b32_e32 v60, v2
	v_mov_b32_e32 v61, v2
	v_mov_b32_e32 v62, v2
	v_mov_b32_e32 v63, v2
	v_mov_b32_e32 v64, v2
	v_mov_b32_e32 v65, v2
	v_mov_b32_e32 v66, v2
	v_mov_b32_e32 v67, v2
	v_mov_b32_e32 v68, v2
	v_mov_b32_e32 v69, v2
	v_mov_b32_e32 v70, v2
	v_mov_b32_e32 v71, v2
	v_mov_b32_e32 v72, v2
	v_mov_b32_e32 v73, v2
	v_mov_b32_e32 v82, v2
	v_mov_b32_e32 v83, v2
	v_mov_b32_e32 v84, v2
	v_mov_b32_e32 v85, v2
	v_mov_b32_e32 v86, v2
	v_mov_b32_e32 v87, v2
	v_mov_b32_e32 v88, v2
	v_mov_b32_e32 v89, v2
	v_mov_b32_e32 v98, v2
	v_mov_b32_e32 v99, v2
	v_mov_b32_e32 v100, v2
	v_mov_b32_e32 v101, v2
	v_mov_b32_e32 v102, v2
	v_mov_b32_e32 v103, v2
	v_mov_b32_e32 v104, v2
	v_mov_b32_e32 v105, v2
	v_mov_b32_e32 v114, v2
	v_mov_b32_e32 v115, v2
	v_mov_b32_e32 v116, v2
	v_mov_b32_e32 v117, v2
	v_mov_b32_e32 v118, v2
	v_mov_b32_e32 v119, v2
	v_mov_b32_e32 v120, v2
	v_mov_b32_e32 v121, v2
	v_mov_b32_e32 v74, v2
	v_mov_b32_e32 v75, v2
	v_mov_b32_e32 v76, v2
	v_mov_b32_e32 v77, v2
	v_mov_b32_e32 v78, v2
	v_mov_b32_e32 v79, v2
	v_mov_b32_e32 v80, v2
	v_mov_b32_e32 v81, v2
	v_mov_b32_e32 v90, v2
	v_mov_b32_e32 v91, v2
	v_mov_b32_e32 v92, v2
	v_mov_b32_e32 v93, v2
	v_mov_b32_e32 v94, v2
	v_mov_b32_e32 v95, v2
	v_mov_b32_e32 v96, v2
	v_mov_b32_e32 v97, v2
	v_mov_b32_e32 v106, v2
	v_mov_b32_e32 v107, v2
	v_mov_b32_e32 v108, v2
	v_mov_b32_e32 v109, v2
	v_mov_b32_e32 v110, v2
	v_mov_b32_e32 v111, v2
	v_mov_b32_e32 v112, v2
	v_mov_b32_e32 v113, v2
	v_mov_b32_e32 v122, v2
	v_mov_b32_e32 v123, v2
	v_mov_b32_e32 v124, v2
	v_mov_b32_e32 v125, v2
	v_mov_b32_e32 v126, v2
	v_mov_b32_e32 v127, v2
	v_mov_b32_e32 v128, v2
	v_mov_b32_e32 v129, v2
	v_readfirstlane_b32 s99, v216
	s_cmp_lt_u32 s99, 0x100
	s_cbranch_scc1 .Lgprio6
	s_setprio 1
.Lgprio6:
.LBB0_438:
	s_add_u32 s56, s54, 0x100
	s_addc_u32 s57, s55, 0
	s_add_i32 s34, 0, 0x10000
	s_cmp_eq_u32 s69, 12
	s_cselect_b32 s61, s20, s57
	s_cselect_b32 s60, s36, s56
	v_add_u32_e32 v0, s34, v151
	s_cselect_b32 s59, s37, s53
	s_cselect_b32 s58, s45, s47
	s_add_i32 s35, 0, 0x14000
	ds_read_b128 v[130:133], v0
	ds_read_b128 v[134:137], v0 offset:1024
	ds_read_b128 v[138:141], v0 offset:2048
	ds_read_b128 v[162:165], v0 offset:3072
	v_add_u32_e32 v0, s35, v151
	ds_read_b128 v[166:169], v0
	ds_read_b128 v[170:173], v0 offset:1024
	ds_read_b128 v[174:177], v0 offset:2048
	ds_read_b128 v[178:181], v0 offset:3072
	v_lshl_add_u64 v[224:225], s[54:55], 0, v[154:155]
	s_add_i32 m0, s63, 0xc000
	ds_read_b128 v[182:185], v161
	ds_read_b128 v[186:189], v161 offset:1024
	ds_read_b128 v[196:199], v161 offset:2048
	ds_read_b128 v[200:203], v161 offset:3072
	ds_read_b128 v[204:207], v161 offset:4096
	ds_read_b128 v[208:211], v161 offset:5120
	ds_read_b128 v[212:215], v161 offset:6144
	ds_read_b128 v[236:239], v161 offset:7168
	global_load_lds_dwordx4 v[224:225], off
	v_lshl_add_u64 v[224:225], s[54:55], 0, v[156:157]
	s_add_i32 m0, s63, 0xe000
	s_nop 0
	global_load_lds_dwordx4 v[224:225], off
	s_waitcnt vmcnt(8)
	s_waitcnt lgkmcnt(0)
	s_barrier
; #define PG8_STAGE(bufoff, gbase, voff) do { _Pragma("unroll") for (int _i = 0; _i < 2; ++_i) \
;         __builtin_amdgcn_global_load_lds((const unsigned*)((const char*)(gbase) + (voff)[_i]), (LAS unsigned*)(lds + (bufoff) + ldsw + _i * 8192), 16, 0, 0); } while (0)
; #define PG8_STAGEA(bufoff, gbase, voff) do { _Pragma("unroll") for (int _i = 0; _i < 2; ++_i) \
;         __builtin_amdgcn_global_load_lds((const unsigned*)((const char*)(gbase) + (voff)[_i]), (LAS unsigned*)(lds + (bufoff) + ldsw + _i * 8192), 16, 0, 0); } while (0)
; #define PG8_LDA(dst, b, h) do { _Pragma("unroll") for (int m = 0; m < 4; ++m) _Pragma("unroll") for (int k = 0; k < 2; ++k) dst[m][k] = *(const LAS bf16x8*)(lds + PG8_SA(b, h) + aoff + m * 2048 + k * 1024); } while (0)
; #define PG8_MMA(ai, bj, At, Bt) do { __builtin_amdgcn_s_setprio(3); _Pragma("unroll") for (int m = 0; m < 4; ++m) _Pragma("unroll") for (int n = 0; n < 2; ++n) _Pragma("unroll") for (int k = 0; k < 2; ++k) \
;         acc[ai][bj][m][n] = __builtin_amdgcn_mfma_f32_16x16x32_bf16(Bt[n][k], At[m][k], acc[ai][bj][m][n], 0, 0, 0); __builtin_amdgcn_s_setprio(0); } while (0)
; #define PG8_WAIT_V(n) asm volatile("s_waitcnt vmcnt(" #n ")" ::: "memory")
; #define PG8_WAIT_L(n) asm volatile("s_waitcnt lgkmcnt(" #n ")" ::: "memory")
; #define PG8_BAR __builtin_amdgcn_s_barrier()
; #define PG8_SCHED __builtin_amdgcn_sched_barrier(0)
; template <class Epi, int PARTS>
; __device__ __forceinline__ void gemm_phase(LAS unsigned char* lds, const Gemm g, const StaticOrder& S, const Epi& E) {
;     ...
;             PG8_WAIT_V(8); PG8_WAIT_L(0); PG8_BAR; PG8_MMA(0, 0, At, B0); PG8_MMA(0, 1, At, B1); PG8_BAR; PG8_SCHED;
;             PG8_LDA(At, 0, 1); PG8_STAGE(PG8_SB(0, 0), b2, voffB); PG8_STAGE(PG8_SB(0, 1), b2 + hstepB, voffB); PG8_STAGEA(PG8_SA(0, 0), a2, voffA);
;             PG8_WAIT_V(8); PG8_WAIT_L(0); PG8_BAR; PG8_MMA(1, 0, At, B0); PG8_MMA(1, 1, At, B1); PG8_BAR; PG8_SCHED;
	s_waitcnt lgkmcnt(0)
	v_mfma_f32_16x16x32_bf16 v[126:129], v[130:133], v[182:185], v[126:129]
	v_mfma_f32_16x16x32_bf16 v[122:125], v[138:141], v[182:185], v[122:125]
	v_mfma_f32_16x16x32_bf16 v[110:113], v[130:133], v[196:199], v[110:113]
	v_mfma_f32_16x16x32_bf16 v[106:109], v[138:141], v[196:199], v[106:109]
	v_mfma_f32_16x16x32_bf16 v[94:97], v[130:133], v[204:207], v[94:97]
	v_mfma_f32_16x16x32_bf16 v[90:93], v[138:141], v[204:207], v[90:93]
	v_mfma_f32_16x16x32_bf16 v[78:81], v[130:133], v[212:215], v[78:81]
	v_mfma_f32_16x16x32_bf16 v[74:77], v[138:141], v[212:215], v[74:77]
	v_mfma_f32_16x16x32_bf16 v[126:129], v[134:137], v[186:189], v[126:129]
	v_mfma_f32_16x16x32_bf16 v[122:125], v[162:165], v[186:189], v[122:125]
	v_mfma_f32_16x16x32_bf16 v[110:113], v[134:137], v[200:203], v[110:113]
	v_mfma_f32_16x16x32_bf16 v[106:109], v[162:165], v[200:203], v[106:109]
	v_mfma_f32_16x16x32_bf16 v[94:97], v[134:137], v[208:211], v[94:97]
	v_mfma_f32_16x16x32_bf16 v[90:93], v[162:165], v[208:211], v[90:93]
	v_mfma_f32_16x16x32_bf16 v[78:81], v[134:137], v[236:239], v[78:81]
	v_mfma_f32_16x16x32_bf16 v[74:77], v[162:165], v[236:239], v[74:77]
	v_mfma_f32_16x16x32_bf16 v[118:121], v[166:169], v[182:185], v[118:121]
	v_mfma_f32_16x16x32_bf16 v[114:117], v[174:177], v[182:185], v[114:117]
	v_mfma_f32_16x16x32_bf16 v[102:105], v[166:169], v[196:199], v[102:105]
	v_mfma_f32_16x16x32_bf16 v[98:101], v[174:177], v[196:199], v[98:101]
	v_mfma_f32_16x16x32_bf16 v[86:89], v[166:169], v[204:207], v[86:89]
	v_mfma_f32_16x16x32_bf16 v[82:85], v[174:177], v[204:207], v[82:85]
	v_mfma_f32_16x16x32_bf16 v[70:73], v[166:169], v[212:215], v[70:73]
	v_mfma_f32_16x16x32_bf16 v[66:69], v[174:177], v[212:215], v[66:69]
	v_mfma_f32_16x16x32_bf16 v[118:121], v[170:173], v[186:189], v[118:121]
	v_mfma_f32_16x16x32_bf16 v[114:117], v[178:181], v[186:189], v[114:117]
	v_mfma_f32_16x16x32_bf16 v[102:105], v[170:173], v[200:203], v[102:105]
	v_mfma_f32_16x16x32_bf16 v[98:101], v[178:181], v[200:203], v[98:101]
	v_mfma_f32_16x16x32_bf16 v[86:89], v[170:173], v[208:211], v[86:89]
	v_mfma_f32_16x16x32_bf16 v[82:85], v[178:181], v[208:211], v[82:85]
	v_mfma_f32_16x16x32_bf16 v[70:73], v[170:173], v[236:239], v[70:73]
	v_mfma_f32_16x16x32_bf16 v[66:69], v[178:181], v[236:239], v[66:69]
	s_barrier
	s_add_i32 s34, s34, s62
	v_lshl_add_u64 v[224:225], s[58:59], 0, v[146:147]
	s_mov_b32 m0, s34
	ds_read_b128 v[182:185], v161 offset:16384
	ds_read_b128 v[186:189], v161 offset:17408
	ds_read_b128 v[196:199], v161 offset:18432
	ds_read_b128 v[200:203], v161 offset:19456
	ds_read_b128 v[204:207], v161 offset:20480
	ds_read_b128 v[208:211], v161 offset:21504
	ds_read_b128 v[212:215], v161 offset:22528
	ds_read_b128 v[236:239], v161 offset:23552
	global_load_lds_dwordx4 v[224:225], off
	s_add_i32 m0, s34, 0x2000
	s_add_u32 s54, s58, 0x40000
	v_lshl_add_u64 v[228:229], s[58:59], 0, v[142:143]
	s_addc_u32 s55, s59, 0
	s_add_i32 s34, s35, s62
	global_load_lds_dwordx4 v[228:229], off
	v_lshl_add_u64 v[230:231], s[54:55], 0, v[146:147]
	s_mov_b32 m0, s34
	v_lshl_add_u64 v[240:241], s[60:61], 0, v[144:145]
	global_load_lds_dwordx4 v[230:231], off
	v_lshl_add_u64 v[230:231], s[54:55], 0, v[142:143]
	s_add_i32 m0, s34, 0x2000
	s_nop 0
	global_load_lds_dwordx4 v[230:231], off
	v_lshl_add_u64 v[230:231], s[60:61], 0, v[148:149]
	s_mov_b32 m0, s63
	s_nop 0
	global_load_lds_dwordx4 v[230:231], off
	s_mov_b32 m0, s64
	s_nop 0
	global_load_lds_dwordx4 v[240:241], off
	s_waitcnt vmcnt(8)
	s_waitcnt lgkmcnt(0)
	s_barrier
	s_waitcnt lgkmcnt(0)
	v_mfma_f32_16x16x32_bf16 v[62:65], v[130:133], v[182:185], v[62:65]
	v_mfma_f32_16x16x32_bf16 v[58:61], v[138:141], v[182:185], v[58:61]
	v_mfma_f32_16x16x32_bf16 v[46:49], v[130:133], v[196:199], v[46:49]
	v_mfma_f32_16x16x32_bf16 v[42:45], v[138:141], v[196:199], v[42:45]
	v_mfma_f32_16x16x32_bf16 v[30:33], v[130:133], v[204:207], v[30:33]
	v_mfma_f32_16x16x32_bf16 v[26:29], v[138:141], v[204:207], v[26:29]
	v_mfma_f32_16x16x32_bf16 v[14:17], v[130:133], v[212:215], v[14:17]
	v_mfma_f32_16x16x32_bf16 v[10:13], v[138:141], v[212:215], v[10:13]
	v_mfma_f32_16x16x32_bf16 v[62:65], v[134:137], v[186:189], v[62:65]
	v_mfma_f32_16x16x32_bf16 v[58:61], v[162:165], v[186:189], v[58:61]
	v_mfma_f32_16x16x32_bf16 v[46:49], v[134:137], v[200:203], v[46:49]
	v_mfma_f32_16x16x32_bf16 v[42:45], v[162:165], v[200:203], v[42:45]
	v_mfma_f32_16x16x32_bf16 v[30:33], v[134:137], v[208:211], v[30:33]
	v_mfma_f32_16x16x32_bf16 v[26:29], v[162:165], v[208:211], v[26:29]
	v_mfma_f32_16x16x32_bf16 v[14:17], v[134:137], v[236:239], v[14:17]
	v_mfma_f32_16x16x32_bf16 v[10:13], v[162:165], v[236:239], v[10:13]
	v_mfma_f32_16x16x32_bf16 v[54:57], v[166:169], v[182:185], v[54:57]
	v_mfma_f32_16x16x32_bf16 v[50:53], v[174:177], v[182:185], v[50:53]
	v_mfma_f32_16x16x32_bf16 v[38:41], v[166:169], v[196:199], v[38:41]
	v_mfma_f32_16x16x32_bf16 v[34:37], v[174:177], v[196:199], v[34:37]
	v_mfma_f32_16x16x32_bf16 v[22:25], v[166:169], v[204:207], v[22:25]
	v_mfma_f32_16x16x32_bf16 v[18:21], v[174:177], v[204:207], v[18:21]
	v_mfma_f32_16x16x32_bf16 v[6:9], v[166:169], v[212:215], v[6:9]
	v_mfma_f32_16x16x32_bf16 v[2:5], v[174:177], v[212:215], v[2:5]
	v_mfma_f32_16x16x32_bf16 v[54:57], v[170:173], v[186:189], v[54:57]
	v_mfma_f32_16x16x32_bf16 v[50:53], v[178:181], v[186:189], v[50:53]
	v_mfma_f32_16x16x32_bf16 v[38:41], v[170:173], v[200:203], v[38:41]
	v_mfma_f32_16x16x32_bf16 v[34:37], v[178:181], v[200:203], v[34:37]
	v_mfma_f32_16x16x32_bf16 v[22:25], v[170:173], v[208:211], v[22:25]
	v_mfma_f32_16x16x32_bf16 v[18:21], v[178:181], v[208:211], v[18:21]
	v_mfma_f32_16x16x32_bf16 v[6:9], v[170:173], v[236:239], v[6:9]
	v_mfma_f32_16x16x32_bf16 v[2:5], v[178:181], v[236:239], v[2:5]
	s_barrier
; #define PG8_STAGEA(bufoff, gbase, voff) do { _Pragma("unroll") for (int _i = 0; _i < 2; ++_i) \
;         __builtin_amdgcn_global_load_lds((const unsigned*)((const char*)(gbase) + (voff)[_i]), (LAS unsigned*)(lds + (bufoff) + ldsw + _i * 8192), 16, 0, 0); } while (0)
; #define PG8_LDA(dst, b, h) do { _Pragma("unroll") for (int m = 0; m < 4; ++m) _Pragma("unroll") for (int k = 0; k < 2; ++k) dst[m][k] = *(const LAS bf16x8*)(lds + PG8_SA(b, h) + aoff + m * 2048 + k * 1024); } while (0)
; #define PG8_LDB(dst, b, h) do { _Pragma("unroll") for (int n = 0; n < 2; ++n) _Pragma("unroll") for (int k = 0; k < 2; ++k) dst[n][k] = *(const LAS bf16x8*)(lds + PG8_SB(b, h) + boff + n * 2048 + k * 1024); } while (0)
; #define PG8_MMA(ai, bj, At, Bt) do { __builtin_amdgcn_s_setprio(3); _Pragma("unroll") for (int m = 0; m < 4; ++m) _Pragma("unroll") for (int n = 0; n < 2; ++n) _Pragma("unroll") for (int k = 0; k < 2; ++k) \
;         acc[ai][bj][m][n] = __builtin_amdgcn_mfma_f32_16x16x32_bf16(Bt[n][k], At[m][k], acc[ai][bj][m][n], 0, 0, 0); __builtin_amdgcn_s_setprio(0); } while (0)
; #define PG8_WAIT_V(n) asm volatile("s_waitcnt vmcnt(" #n ")" ::: "memory")
; #define PG8_WAIT_L(n) asm volatile("s_waitcnt lgkmcnt(" #n ")" ::: "memory")
; #define PG8_BAR __builtin_amdgcn_s_barrier()
; #define PG8_SCHED __builtin_amdgcn_sched_barrier(0)
; template <class Epi, int PARTS>
; __device__ __forceinline__ void gemm_phase(LAS unsigned char* lds, const Gemm g, const StaticOrder& S, const Epi& E) {
;     ...
;             PG8_LDB(B0, 1, 0); PG8_LDB(B1, 1, 1); PG8_SCHED; PG8_LDA(At, 1, 0); PG8_STAGEA(PG8_SA(0, 1), a2 + hstepA, voffA);
;             PG8_WAIT_V(8); PG8_WAIT_L(0); PG8_BAR; PG8_MMA(0, 0, At, B0); PG8_MMA(0, 1, At, B1); PG8_BAR; PG8_SCHED;
	s_add_i32 s34, 0, 0x18000
	v_add_u32_e32 v0, s34, v151
	s_add_i32 s35, 0, 0x1c000
	ds_read_b128 v[130:133], v0
	ds_read_b128 v[134:137], v0 offset:1024
	ds_read_b128 v[138:141], v0 offset:2048
	ds_read_b128 v[162:165], v0 offset:3072
	v_add_u32_e32 v0, s35, v151
	ds_read_b128 v[166:169], v0
	ds_read_b128 v[170:173], v0 offset:1024
	ds_read_b128 v[174:177], v0 offset:2048
	ds_read_b128 v[178:181], v0 offset:3072
	s_add_u32 s54, s60, 0x2000
	s_addc_u32 s55, s61, 0
	s_mov_b32 m0, s65
	v_lshl_add_u64 v[242:243], s[54:55], 0, v[148:149]
	ds_read_b128 v[182:185], v161 offset:32768
	ds_read_b128 v[186:189], v161 offset:33792
	ds_read_b128 v[196:199], v161 offset:34816
	ds_read_b128 v[200:203], v161 offset:35840
	ds_read_b128 v[204:207], v161 offset:36864
	ds_read_b128 v[208:211], v161 offset:37888
	ds_read_b128 v[212:215], v161 offset:38912
	ds_read_b128 v[236:239], v161 offset:39936
	global_load_lds_dwordx4 v[242:243], off
	v_lshl_add_u64 v[242:243], s[54:55], 0, v[144:145]
	s_mov_b32 m0, s66
	s_nop 0
	global_load_lds_dwordx4 v[242:243], off
	s_waitcnt vmcnt(8)
	s_waitcnt lgkmcnt(0)
	s_barrier
	s_waitcnt lgkmcnt(0)
	v_mfma_f32_16x16x32_bf16 v[126:129], v[130:133], v[182:185], v[126:129]
	v_mfma_f32_16x16x32_bf16 v[122:125], v[138:141], v[182:185], v[122:125]
	v_mfma_f32_16x16x32_bf16 v[110:113], v[130:133], v[196:199], v[110:113]
	v_mfma_f32_16x16x32_bf16 v[106:109], v[138:141], v[196:199], v[106:109]
	v_mfma_f32_16x16x32_bf16 v[94:97], v[130:133], v[204:207], v[94:97]
	v_mfma_f32_16x16x32_bf16 v[90:93], v[138:141], v[204:207], v[90:93]
	v_mfma_f32_16x16x32_bf16 v[78:81], v[130:133], v[212:215], v[78:81]
	v_mfma_f32_16x16x32_bf16 v[74:77], v[138:141], v[212:215], v[74:77]
	v_mfma_f32_16x16x32_bf16 v[126:129], v[134:137], v[186:189], v[126:129]
	v_mfma_f32_16x16x32_bf16 v[122:125], v[162:165], v[186:189], v[122:125]
	v_mfma_f32_16x16x32_bf16 v[110:113], v[134:137], v[200:203], v[110:113]
	v_mfma_f32_16x16x32_bf16 v[106:109], v[162:165], v[200:203], v[106:109]
	v_mfma_f32_16x16x32_bf16 v[94:97], v[134:137], v[208:211], v[94:97]
	v_mfma_f32_16x16x32_bf16 v[90:93], v[162:165], v[208:211], v[90:93]
	v_mfma_f32_16x16x32_bf16 v[78:81], v[134:137], v[236:239], v[78:81]
	v_mfma_f32_16x16x32_bf16 v[74:77], v[162:165], v[236:239], v[74:77]
	v_mfma_f32_16x16x32_bf16 v[118:121], v[166:169], v[182:185], v[118:121]
	v_mfma_f32_16x16x32_bf16 v[114:117], v[174:177], v[182:185], v[114:117]
	v_mfma_f32_16x16x32_bf16 v[102:105], v[166:169], v[196:199], v[102:105]
	v_mfma_f32_16x16x32_bf16 v[98:101], v[174:177], v[196:199], v[98:101]
	v_mfma_f32_16x16x32_bf16 v[86:89], v[166:169], v[204:207], v[86:89]
	v_mfma_f32_16x16x32_bf16 v[82:85], v[174:177], v[204:207], v[82:85]
	v_mfma_f32_16x16x32_bf16 v[70:73], v[166:169], v[212:215], v[70:73]
	v_mfma_f32_16x16x32_bf16 v[66:69], v[174:177], v[212:215], v[66:69]
	v_mfma_f32_16x16x32_bf16 v[118:121], v[170:173], v[186:189], v[118:121]
	v_mfma_f32_16x16x32_bf16 v[114:117], v[178:181], v[186:189], v[114:117]
	v_mfma_f32_16x16x32_bf16 v[102:105], v[170:173], v[200:203], v[102:105]
	v_mfma_f32_16x16x32_bf16 v[98:101], v[178:181], v[200:203], v[98:101]
	v_mfma_f32_16x16x32_bf16 v[86:89], v[170:173], v[208:211], v[86:89]
	v_mfma_f32_16x16x32_bf16 v[82:85], v[178:181], v[208:211], v[82:85]
	v_mfma_f32_16x16x32_bf16 v[70:73], v[170:173], v[236:239], v[70:73]
	v_mfma_f32_16x16x32_bf16 v[66:69], v[178:181], v[236:239], v[66:69]
	s_barrier
; #define PG8_STAGE(bufoff, gbase, voff) do { _Pragma("unroll") for (int _i = 0; _i < 2; ++_i) \
;         __builtin_amdgcn_global_load_lds((const unsigned*)((const char*)(gbase) + (voff)[_i]), (LAS unsigned*)(lds + (bufoff) + ldsw + _i * 8192), 16, 0, 0); } while (0)
; #define PG8_STAGEA(bufoff, gbase, voff) do { _Pragma("unroll") for (int _i = 0; _i < 2; ++_i) \
;         __builtin_amdgcn_global_load_lds((const unsigned*)((const char*)(gbase) + (voff)[_i]), (LAS unsigned*)(lds + (bufoff) + ldsw + _i * 8192), 16, 0, 0); } while (0)
; #define PG8_LDA(dst, b, h) do { _Pragma("unroll") for (int m = 0; m < 4; ++m) _Pragma("unroll") for (int k = 0; k < 2; ++k) dst[m][k] = *(const LAS bf16x8*)(lds + PG8_SA(b, h) + aoff + m * 2048 + k * 1024); } while (0)
; #define PG8_MMA(ai, bj, At, Bt) do { __builtin_amdgcn_s_setprio(3); _Pragma("unroll") for (int m = 0; m < 4; ++m) _Pragma("unroll") for (int n = 0; n < 2; ++n) _Pragma("unroll") for (int k = 0; k < 2; ++k) \
;         acc[ai][bj][m][n] = __builtin_amdgcn_mfma_f32_16x16x32_bf16(Bt[n][k], At[m][k], acc[ai][bj][m][n], 0, 0, 0); __builtin_amdgcn_s_setprio(0); } while (0)
; #define PG8_WAIT_V(n) asm volatile("s_waitcnt vmcnt(" #n ")" ::: "memory")
; #define PG8_WAIT_L(n) asm volatile("s_waitcnt lgkmcnt(" #n ")" ::: "memory")
; #define PG8_BAR __builtin_amdgcn_s_barrier()
; #define PG8_SCHED __builtin_amdgcn_sched_barrier(0)
; template <class Epi, int PARTS>
; __device__ __forceinline__ void gemm_phase(LAS unsigned char* lds, const Gemm g, const StaticOrder& S, const Epi& E) {
;     ...
;             PG8_LDA(At, 1, 1); PG8_STAGE(PG8_SB(1, 0), b3, voffB); PG8_STAGE(PG8_SB(1, 1), b3 + hstepB, voffB); PG8_STAGEA(PG8_SA(1, 0), a3, voffA);
;             PG8_WAIT_V(8); PG8_WAIT_L(0); PG8_BAR; PG8_MMA(1, 0, At, B0); PG8_MMA(1, 1, At, B1); PG8_BAR; PG8_SCHED;
;         }
;         if (wr == 0) PG8_BAR;
	s_add_i32 s34, s34, s62
	v_lshl_add_u64 v[224:225], v[224:225], 0, s[72:73]
	s_mov_b32 m0, s34
	ds_read_b128 v[182:185], v161 offset:49152
	ds_read_b128 v[186:189], v161 offset:50176
	ds_read_b128 v[196:199], v161 offset:51200
	ds_read_b128 v[200:203], v161 offset:52224
	ds_read_b128 v[204:207], v161 offset:53248
	ds_read_b128 v[208:211], v161 offset:54272
	ds_read_b128 v[212:215], v161 offset:55296
	ds_read_b128 v[236:239], v161 offset:56320
	global_load_lds_dwordx4 v[224:225], off
	s_add_i32 m0, s34, 0x2000
	s_add_u32 s54, s58, 0x40080
	v_lshl_add_u64 v[224:225], v[228:229], 0, s[72:73]
	s_addc_u32 s55, s59, 0
	s_add_i32 s34, s35, s62
	global_load_lds_dwordx4 v[224:225], off
	v_lshl_add_u64 v[224:225], s[54:55], 0, v[146:147]
	s_mov_b32 m0, s34
	s_nop 0
	global_load_lds_dwordx4 v[224:225], off
	v_lshl_add_u64 v[224:225], s[54:55], 0, v[142:143]
	s_add_i32 m0, s34, 0x2000
	s_nop 0
	global_load_lds_dwordx4 v[224:225], off
	v_lshl_add_u64 v[224:225], v[230:231], 0, s[72:73]
	s_mov_b32 m0, s74
	s_nop 0
	global_load_lds_dwordx4 v[224:225], off
	v_lshl_add_u64 v[224:225], v[240:241], 0, s[72:73]
	s_mov_b32 m0, s75
	s_nop 0
	global_load_lds_dwordx4 v[224:225], off
	s_waitcnt vmcnt(8)
	s_waitcnt lgkmcnt(0)
	s_barrier
	s_waitcnt lgkmcnt(0)
	v_mfma_f32_16x16x32_bf16 v[62:65], v[130:133], v[182:185], v[62:65]
	v_mfma_f32_16x16x32_bf16 v[58:61], v[138:141], v[182:185], v[58:61]
	v_mfma_f32_16x16x32_bf16 v[46:49], v[130:133], v[196:199], v[46:49]
	v_mfma_f32_16x16x32_bf16 v[42:45], v[138:141], v[196:199], v[42:45]
	v_mfma_f32_16x16x32_bf16 v[30:33], v[130:133], v[204:207], v[30:33]
	v_mfma_f32_16x16x32_bf16 v[26:29], v[138:141], v[204:207], v[26:29]
	v_mfma_f32_16x16x32_bf16 v[14:17], v[130:133], v[212:215], v[14:17]
	v_mfma_f32_16x16x32_bf16 v[10:13], v[138:141], v[212:215], v[10:13]
	v_mfma_f32_16x16x32_bf16 v[62:65], v[134:137], v[186:189], v[62:65]
	v_mfma_f32_16x16x32_bf16 v[58:61], v[162:165], v[186:189], v[58:61]
	v_mfma_f32_16x16x32_bf16 v[46:49], v[134:137], v[200:203], v[46:49]
	v_mfma_f32_16x16x32_bf16 v[42:45], v[162:165], v[200:203], v[42:45]
	v_mfma_f32_16x16x32_bf16 v[30:33], v[134:137], v[208:211], v[30:33]
	v_mfma_f32_16x16x32_bf16 v[26:29], v[162:165], v[208:211], v[26:29]
	v_mfma_f32_16x16x32_bf16 v[14:17], v[134:137], v[236:239], v[14:17]
	v_mfma_f32_16x16x32_bf16 v[10:13], v[162:165], v[236:239], v[10:13]
	v_mfma_f32_16x16x32_bf16 v[54:57], v[166:169], v[182:185], v[54:57]
	v_mfma_f32_16x16x32_bf16 v[50:53], v[174:177], v[182:185], v[50:53]
	v_mfma_f32_16x16x32_bf16 v[38:41], v[166:169], v[196:199], v[38:41]
	v_mfma_f32_16x16x32_bf16 v[34:37], v[174:177], v[196:199], v[34:37]
	v_mfma_f32_16x16x32_bf16 v[22:25], v[166:169], v[204:207], v[22:25]
	v_mfma_f32_16x16x32_bf16 v[18:21], v[174:177], v[204:207], v[18:21]
	v_mfma_f32_16x16x32_bf16 v[6:9], v[166:169], v[212:215], v[6:9]
	v_mfma_f32_16x16x32_bf16 v[2:5], v[174:177], v[212:215], v[2:5]
	v_mfma_f32_16x16x32_bf16 v[54:57], v[170:173], v[186:189], v[54:57]
	v_mfma_f32_16x16x32_bf16 v[50:53], v[178:181], v[186:189], v[50:53]
	v_mfma_f32_16x16x32_bf16 v[38:41], v[170:173], v[200:203], v[38:41]
	v_mfma_f32_16x16x32_bf16 v[34:37], v[178:181], v[200:203], v[34:37]
	v_mfma_f32_16x16x32_bf16 v[22:25], v[170:173], v[208:211], v[22:25]
	v_mfma_f32_16x16x32_bf16 v[18:21], v[178:181], v[208:211], v[18:21]
	v_mfma_f32_16x16x32_bf16 v[6:9], v[170:173], v[236:239], v[6:9]
	v_mfma_f32_16x16x32_bf16 v[2:5], v[178:181], v[236:239], v[2:5]
	s_barrier
	s_add_i32 s69, s69, 2
	s_add_u32 s47, s47, 0x100
	s_addc_u32 s53, s53, 0
	s_cmp_gt_u32 s69, 13
	s_mov_b64 s[54:55], s[56:57]
	s_cbranch_scc0 .LBB0_438
	s_setprio 0
	s_and_b64 vcc, exec, s[42:43]
	s_cbranch_vccz .LBB0_441
	s_barrier
